# GEMM k-iteration: drop compiler vmcnt(0) drain; PEER table conversion moved off workgroups owning an extra tile; outproj k-loop hand-pipelined (both k-steps' fragments prefetched, LDS-DMA issue interl
# speedup vs baseline: 1.1381x; 1.1381x over previous
.LBB0_21:
	s_and_b32 s21, s17, 0x8000
	s_waitcnt vmcnt(8)
	s_barrier
	v_add_u32_e32 v140, s21, v104
	v_or_b32_e32 v141, s21, v73
	ds_read_b128 v[106:109], v140
	ds_read_b128 v[110:113], v140 offset:2048
	ds_read_b128 v[116:119], v140 offset:4096
	ds_read_b128 v[120:123], v140 offset:6144
	ds_read_b128 v[124:127], v141 offset:16384
	ds_read_b128 v[128:131], v141 offset:18432
	ds_read_b128 v[132:135], v141 offset:20480
	ds_read_b128 v[136:139], v141 offset:22528
	s_waitcnt lgkmcnt(0)
	v_mfma_f32_16x16x32_bf16 v[60:63], v[106:109], v[124:127], v[60:63]
	v_mfma_f32_16x16x32_bf16 v[56:59], v[106:109], v[128:131], v[56:59]
	v_mfma_f32_16x16x32_bf16 v[52:55], v[106:109], v[132:135], v[52:55]
	v_mfma_f32_16x16x32_bf16 v[48:51], v[106:109], v[136:139], v[48:51]
	v_mfma_f32_16x16x32_bf16 v[44:47], v[110:113], v[124:127], v[44:47]
	v_mfma_f32_16x16x32_bf16 v[40:43], v[110:113], v[128:131], v[40:43]
	v_mfma_f32_16x16x32_bf16 v[36:39], v[110:113], v[132:135], v[36:39]
	v_mfma_f32_16x16x32_bf16 v[32:35], v[110:113], v[136:139], v[32:35]
	v_mfma_f32_16x16x32_bf16 v[28:31], v[116:119], v[124:127], v[28:31]
	v_mfma_f32_16x16x32_bf16 v[24:27], v[116:119], v[128:131], v[24:27]
	v_mfma_f32_16x16x32_bf16 v[20:23], v[116:119], v[132:135], v[20:23]
	v_mfma_f32_16x16x32_bf16 v[16:19], v[116:119], v[136:139], v[16:19]
	v_mfma_f32_16x16x32_bf16 v[12:15], v[120:123], v[124:127], v[12:15]
	v_mfma_f32_16x16x32_bf16 v[8:11], v[120:123], v[128:131], v[8:11]
	v_mfma_f32_16x16x32_bf16 v[4:7], v[120:123], v[132:135], v[4:7]
	v_mfma_f32_16x16x32_bf16 v[0:3], v[120:123], v[136:139], v[0:3]
	ds_read_b128 v[106:109], v140 offset:1024
	ds_read_b128 v[110:113], v140 offset:3072
	ds_read_b128 v[116:119], v140 offset:5120
	ds_read_b128 v[120:123], v140 offset:7168
	ds_read_b128 v[124:127], v141 offset:17408
	ds_read_b128 v[128:131], v141 offset:19456
	ds_read_b128 v[132:135], v141 offset:21504
	ds_read_b128 v[136:139], v141 offset:23552
	s_waitcnt lgkmcnt(0)
	s_barrier
	s_waitcnt lgkmcnt(3)
	v_mfma_f32_16x16x32_bf16 v[60:63], v[106:109], v[124:127], v[60:63]
	s_waitcnt lgkmcnt(2)
	v_mfma_f32_16x16x32_bf16 v[56:59], v[106:109], v[128:131], v[56:59]
	s_waitcnt lgkmcnt(1)
	v_mfma_f32_16x16x32_bf16 v[52:55], v[106:109], v[132:135], v[52:55]
	s_waitcnt lgkmcnt(0)
	v_mfma_f32_16x16x32_bf16 v[48:51], v[106:109], v[136:139], v[48:51]
	v_add_u32_e32 v108, s21, v105
	v_add_u32_e32 v109, 0x1000, v108
	v_readfirstlane_b32 s21, v108
	v_lshl_add_u64 v[106:107], v[90:91], 0, s[0:1]
	s_mov_b32 m0, s21
	v_readfirstlane_b32 s21, v109
	v_add_u32_e32 v109, 0x2000, v108
	global_load_lds_dwordx4 v[106:107], off
	v_lshl_add_u64 v[106:107], v[88:89], 0, s[0:1]
	s_mov_b32 m0, s21
	v_readfirstlane_b32 s21, v109
	v_add_u32_e32 v109, 0x3000, v108
	global_load_lds_dwordx4 v[106:107], off
	v_lshl_add_u64 v[106:107], v[86:87], 0, s[0:1]
	s_mov_b32 m0, s21
	v_readfirstlane_b32 s21, v109
	v_add_u32_e32 v109, 0x4000, v108
	global_load_lds_dwordx4 v[106:107], off
	v_lshl_add_u64 v[106:107], v[84:85], 0, s[0:1]
	s_mov_b32 m0, s21
	v_readfirstlane_b32 s21, v109
	v_add_u32_e32 v109, 0x5000, v108
	global_load_lds_dwordx4 v[106:107], off
	v_lshl_add_u64 v[106:107], v[82:83], 0, s[0:1]
	s_mov_b32 m0, s21
	v_readfirstlane_b32 s21, v109
	v_add_u32_e32 v109, 0x6000, v108
	global_load_lds_dwordx4 v[106:107], off
	v_lshl_add_u64 v[106:107], v[78:79], 0, s[0:1]
	s_mov_b32 m0, s21
	v_readfirstlane_b32 s21, v109
	v_add_u32_e32 v108, 0x7000, v108
	global_load_lds_dwordx4 v[106:107], off
	v_lshl_add_u64 v[106:107], v[76:77], 0, s[0:1]
	s_mov_b32 m0, s21
	v_readfirstlane_b32 s21, v108
	global_load_lds_dwordx4 v[106:107], off
	v_lshl_add_u64 v[106:107], v[74:75], 0, s[0:1]
	s_mov_b32 m0, s21
	v_mfma_f32_16x16x32_bf16 v[44:47], v[110:113], v[124:127], v[44:47]
	global_load_lds_dwordx4 v[106:107], off
	s_add_u32 s0, s0, 0x80
	v_mfma_f32_16x16x32_bf16 v[40:43], v[110:113], v[128:131], v[40:43]
	s_addc_u32 s1, s1, 0
	s_add_i32 s17, s17, 0x8000
	s_cmpk_lg_i32 s0, 0x700
	v_mfma_f32_16x16x32_bf16 v[36:39], v[110:113], v[132:135], v[36:39]
	v_mfma_f32_16x16x32_bf16 v[32:35], v[110:113], v[136:139], v[32:35]
	v_mfma_f32_16x16x32_bf16 v[28:31], v[116:119], v[124:127], v[28:31]
	v_mfma_f32_16x16x32_bf16 v[24:27], v[116:119], v[128:131], v[24:27]
	v_mfma_f32_16x16x32_bf16 v[20:23], v[116:119], v[132:135], v[20:23]
	v_mfma_f32_16x16x32_bf16 v[16:19], v[116:119], v[136:139], v[16:19]
	v_mfma_f32_16x16x32_bf16 v[12:15], v[120:123], v[124:127], v[12:15]
	v_mfma_f32_16x16x32_bf16 v[8:11], v[120:123], v[128:131], v[8:11]
	v_mfma_f32_16x16x32_bf16 v[4:7], v[120:123], v[132:135], v[4:7]
	v_mfma_f32_16x16x32_bf16 v[0:3], v[120:123], v[136:139], v[0:3]
	s_cbranch_scc1 .LBB0_21
	s_waitcnt vmcnt(8)
	s_barrier
	ds_read_b128 v[74:77], v104
	ds_read_b128 v[82:85], v104 offset:2048
	ds_read_b128 v[86:89], v104 offset:4096
	ds_read_b128 v[106:109], v104 offset:6144
	ds_read_b128 v[110:113], v73 offset:16384
	ds_read_b128 v[116:119], v73 offset:18432
	ds_read_b128 v[120:123], v73 offset:20480
	ds_read_b128 v[124:127], v73 offset:22528
	s_waitcnt lgkmcnt(0)
	v_mfma_f32_16x16x32_bf16 v[60:63], v[74:77], v[110:113], v[60:63]
	v_readlane_b32 s0, v249, 30
	v_readlane_b32 s1, v249, 31
	v_readlane_b32 s22, v249, 41
	v_mfma_f32_16x16x32_bf16 v[56:59], v[74:77], v[116:119], v[56:59]
	v_readlane_b32 s23, v249, 42
	s_movk_i32 s21, 0x6f
	v_mfma_f32_16x16x32_bf16 v[52:55], v[74:77], v[120:123], v[52:55]
	v_mfma_f32_16x16x32_bf16 v[48:51], v[74:77], v[124:127], v[48:51]
	v_mfma_f32_16x16x32_bf16 v[44:47], v[82:85], v[110:113], v[44:47]
	v_mfma_f32_16x16x32_bf16 v[40:43], v[82:85], v[116:119], v[40:43]
	v_mfma_f32_16x16x32_bf16 v[36:39], v[82:85], v[120:123], v[36:39]
	v_mfma_f32_16x16x32_bf16 v[32:35], v[82:85], v[124:127], v[32:35]
	v_mfma_f32_16x16x32_bf16 v[28:31], v[86:89], v[110:113], v[28:31]
	v_mfma_f32_16x16x32_bf16 v[24:27], v[86:89], v[116:119], v[24:27]
	v_mfma_f32_16x16x32_bf16 v[20:23], v[86:89], v[120:123], v[20:23]
	v_mfma_f32_16x16x32_bf16 v[16:19], v[86:89], v[124:127], v[16:19]
	v_mfma_f32_16x16x32_bf16 v[12:15], v[106:109], v[110:113], v[12:15]
	v_mfma_f32_16x16x32_bf16 v[8:11], v[106:109], v[116:119], v[8:11]
	v_mfma_f32_16x16x32_bf16 v[4:7], v[106:109], v[120:123], v[4:7]
	v_mfma_f32_16x16x32_bf16 v[0:3], v[106:109], v[124:127], v[0:3]
	ds_read_b128 v[74:77], v104 offset:1024
	ds_read_b128 v[82:85], v104 offset:3072
	ds_read_b128 v[86:89], v104 offset:5120
	ds_read_b128 v[106:109], v104 offset:7168
	ds_read_b128 v[110:113], v73 offset:17408
	ds_read_b128 v[116:119], v73 offset:19456
	ds_read_b128 v[120:123], v73 offset:21504
	ds_read_b128 v[124:127], v73 offset:23552
	s_waitcnt lgkmcnt(0)
	s_barrier
	s_waitcnt vmcnt(0)
	s_barrier
	s_waitcnt lgkmcnt(3)
	v_mfma_f32_16x16x32_bf16 v[60:63], v[74:77], v[110:113], v[60:63]
	s_waitcnt lgkmcnt(2)
	v_mfma_f32_16x16x32_bf16 v[56:59], v[74:77], v[116:119], v[56:59]
	s_waitcnt lgkmcnt(1)
	v_mfma_f32_16x16x32_bf16 v[52:55], v[74:77], v[120:123], v[52:55]
	s_waitcnt lgkmcnt(0)
	v_mfma_f32_16x16x32_bf16 v[48:51], v[74:77], v[124:127], v[48:51]
	v_mfma_f32_16x16x32_bf16 v[44:47], v[82:85], v[110:113], v[44:47]
	v_mfma_f32_16x16x32_bf16 v[40:43], v[82:85], v[116:119], v[40:43]
	v_mfma_f32_16x16x32_bf16 v[36:39], v[82:85], v[120:123], v[36:39]
	v_mfma_f32_16x16x32_bf16 v[32:35], v[82:85], v[124:127], v[32:35]
	v_mfma_f32_16x16x32_bf16 v[28:31], v[86:89], v[110:113], v[28:31]
	v_mfma_f32_16x16x32_bf16 v[24:27], v[86:89], v[116:119], v[24:27]
	v_mfma_f32_16x16x32_bf16 v[20:23], v[86:89], v[120:123], v[20:23]
	v_mfma_f32_16x16x32_bf16 v[16:19], v[86:89], v[124:127], v[16:19]
	v_mfma_f32_16x16x32_bf16 v[12:15], v[106:109], v[110:113], v[12:15]
	v_mfma_f32_16x16x32_bf16 v[8:11], v[106:109], v[116:119], v[8:11]
	v_mfma_f32_16x16x32_bf16 v[4:7], v[106:109], v[120:123], v[4:7]
	v_mfma_f32_16x16x32_bf16 v[0:3], v[106:109], v[124:127], v[0:3]
	ds_read_b128 v[74:77], v104 offset:32768
	ds_read_b128 v[82:85], v104 offset:34816
	ds_read_b128 v[86:89], v104 offset:36864
	ds_read_b128 v[106:109], v104 offset:38912
	ds_read_b128 v[110:113], v73 offset:49152
	ds_read_b128 v[116:119], v73 offset:51200
	ds_read_b128 v[120:123], v73 offset:53248
	ds_read_b128 v[124:127], v73 offset:55296
	s_waitcnt lgkmcnt(3)
	v_mfma_f32_16x16x32_bf16 v[60:63], v[74:77], v[110:113], v[60:63]
	s_waitcnt lgkmcnt(2)
	v_mfma_f32_16x16x32_bf16 v[56:59], v[74:77], v[116:119], v[56:59]
	s_waitcnt lgkmcnt(1)
	v_mfma_f32_16x16x32_bf16 v[52:55], v[74:77], v[120:123], v[52:55]
	s_waitcnt lgkmcnt(0)
	v_mfma_f32_16x16x32_bf16 v[48:51], v[74:77], v[124:127], v[48:51]
	v_mfma_f32_16x16x32_bf16 v[44:47], v[82:85], v[110:113], v[44:47]
	v_mfma_f32_16x16x32_bf16 v[40:43], v[82:85], v[116:119], v[40:43]
	v_mfma_f32_16x16x32_bf16 v[36:39], v[82:85], v[120:123], v[36:39]
	v_mfma_f32_16x16x32_bf16 v[32:35], v[82:85], v[124:127], v[32:35]
	v_mfma_f32_16x16x32_bf16 v[28:31], v[86:89], v[110:113], v[28:31]
	v_mfma_f32_16x16x32_bf16 v[24:27], v[86:89], v[116:119], v[24:27]
	v_mfma_f32_16x16x32_bf16 v[20:23], v[86:89], v[120:123], v[20:23]
	v_mfma_f32_16x16x32_bf16 v[16:19], v[86:89], v[124:127], v[16:19]
	v_mfma_f32_16x16x32_bf16 v[12:15], v[106:109], v[110:113], v[12:15]
	v_mfma_f32_16x16x32_bf16 v[8:11], v[106:109], v[116:119], v[8:11]
	v_mfma_f32_16x16x32_bf16 v[4:7], v[106:109], v[120:123], v[4:7]
	v_mfma_f32_16x16x32_bf16 v[0:3], v[106:109], v[124:127], v[0:3]
	ds_read_b128 v[74:77], v104 offset:33792
	ds_read_b128 v[82:85], v104 offset:35840
	ds_read_b128 v[86:89], v104 offset:37888
	ds_read_b128 v[104:107], v104 offset:39936
	ds_read_b128 v[108:111], v73 offset:50176
	ds_read_b128 v[116:119], v73 offset:52224
	ds_read_b128 v[120:123], v73 offset:54272
	ds_read_b128 v[124:127], v73 offset:56320
	s_waitcnt lgkmcnt(0)
	s_barrier
	s_waitcnt lgkmcnt(0)
	s_barrier
	s_load_dwordx2 s[0:1], s[0:1], 0x130
	v_mov_b32_e32 v73, v80
	v_mfma_f32_16x16x32_bf16 v[60:63], v[74:77], v[108:111], v[60:63]
	s_waitcnt lgkmcnt(0)
	s_add_u32 s0, s0, s22
	s_addc_u32 s1, s1, s23
	s_lshl_b32 s17, s20, 15
	s_add_u32 s0, s0, s17
	s_addc_u32 s1, s1, 0
	v_mfma_f32_16x16x32_bf16 v[56:59], v[74:77], v[116:119], v[56:59]
	s_mov_b64 s[22:23], 0x80
	s_movk_i32 s17, 0x7f
	v_mfma_f32_16x16x32_bf16 v[52:55], v[74:77], v[120:123], v[52:55]
	v_mfma_f32_16x16x32_bf16 v[48:51], v[74:77], v[124:127], v[48:51]
	v_lshl_add_u64 v[74:75], s[0:1], 0, v[72:73]
	v_add_u32_e32 v73, 0x9000, v92
	v_lshl_add_u64 v[76:77], v[64:65], 1, v[74:75]
	v_readfirstlane_b32 s0, v73
	v_add_u32_e32 v73, 0xa000, v92
	s_mov_b32 m0, s0
	v_readfirstlane_b32 s0, v73
	v_add_u32_e32 v73, 0xb000, v92
	global_load_lds_dwordx4 v[76:77], off
	v_lshl_add_u64 v[78:79], v[66:67], 1, v[74:75]
	s_mov_b32 m0, s0
	v_readfirstlane_b32 s0, v73
	v_add_u32_e32 v73, 0xc000, v92
	v_mfma_f32_16x16x32_bf16 v[44:47], v[82:85], v[108:111], v[44:47]
	global_load_lds_dwordx4 v[78:79], off
	s_mov_b32 m0, s0
	v_mfma_f32_16x16x32_bf16 v[40:43], v[82:85], v[116:119], v[40:43]
	v_readfirstlane_b32 s0, v73
	v_add_u32_e32 v73, 0xd000, v92
	v_lshl_add_u64 v[76:77], v[76:77], 0, s[22:23]
	v_mfma_f32_16x16x32_bf16 v[36:39], v[82:85], v[120:123], v[36:39]
	v_mfma_f32_16x16x32_bf16 v[32:35], v[82:85], v[124:127], v[32:35]
	v_lshl_add_u64 v[82:83], v[68:69], 1, v[74:75]
	global_load_lds_dwordx4 v[82:83], off
	v_lshl_add_u64 v[74:75], v[70:71], 1, v[74:75]
	s_mov_b32 m0, s0
	v_readfirstlane_b32 s0, v73
	v_add_u32_e32 v73, 0xe000, v92
	global_load_lds_dwordx4 v[74:75], off
	s_mov_b32 m0, s0
	v_readfirstlane_b32 s0, v73
	v_add_u32_e32 v73, 0xf000, v92
	global_load_lds_dwordx4 v[76:77], off
	v_lshl_add_u64 v[76:77], v[78:79], 0, s[22:23]
	s_mov_b32 m0, s0
	v_readfirstlane_b32 s0, v73
	v_add_u32_e32 v73, 0xd000, v93
	global_load_lds_dwordx4 v[76:77], off
	v_lshl_add_u64 v[76:77], v[82:83], 0, s[22:23]
	s_mov_b32 m0, s0
	v_readfirstlane_b32 s0, v73
	global_load_lds_dwordx4 v[76:77], off
	v_lshl_add_u64 v[74:75], v[74:75], 0, s[22:23]
	s_mov_b32 m0, s0
	v_mfma_f32_16x16x32_bf16 v[28:31], v[86:89], v[108:111], v[28:31]
	global_load_lds_dwordx4 v[74:75], off
	v_lshl_or_b32 v74, s20, 9, v98
	global_load_dword v73, v74, s[10:11]
	v_mfma_f32_16x16x32_bf16 v[24:27], v[86:89], v[116:119], v[24:27]
	s_movk_i32 s22, 0x5f
	s_movk_i32 s23, 0x4f
	s_waitcnt vmcnt(0)
	v_add_f32_e32 v60, v60, v73
	v_bfe_u32 v75, v60, 16, 1
	v_add3_u32 v75, v60, v75, s33
	v_add_u32_e32 v60, v96, v97
	v_add_f32_e32 v61, v61, v73
	ds_write_b16_d16_hi v60, v75
	v_bfe_u32 v75, v61, 16, 1
	v_add3_u32 v61, v61, v75, s33
	ds_write_b16_d16_hi v60, v61 offset:272
	v_add_f32_e32 v61, v62, v73
	v_bfe_u32 v62, v61, 16, 1
	v_add3_u32 v61, v61, v62, s33
	ds_write_b16_d16_hi v60, v61 offset:544
	v_add_f32_e32 v61, v63, v73
	v_bfe_u32 v62, v61, 16, 1
	v_add3_u32 v61, v61, v62, s33
	ds_write_b16_d16_hi v60, v61 offset:816
	global_load_dword v61, v74, s[10:11] offset:64
	v_add_f32_e32 v44, v44, v73
	v_add_f32_e32 v28, v28, v73
	v_mfma_f32_16x16x32_bf16 v[20:23], v[86:89], v[120:123], v[20:23]
	s_waitcnt vmcnt(0)
	v_add_f32_e32 v56, v56, v61
	v_bfe_u32 v62, v56, 16, 1
	v_add3_u32 v56, v56, v62, s33
	ds_write_b16_d16_hi v60, v56 offset:32
	v_add_f32_e32 v56, v57, v61
	v_bfe_u32 v57, v56, 16, 1
	v_add3_u32 v56, v56, v57, s33
	ds_write_b16_d16_hi v60, v56 offset:304
	v_add_f32_e32 v56, v58, v61
	v_bfe_u32 v57, v56, 16, 1
	v_add3_u32 v56, v56, v57, s33
	ds_write_b16_d16_hi v60, v56 offset:576
	v_add_f32_e32 v56, v59, v61
	v_bfe_u32 v57, v56, 16, 1
	v_add3_u32 v56, v56, v57, s33
	ds_write_b16_d16_hi v60, v56 offset:848
	global_load_dword v56, v74, s[10:11] offset:128
	v_add_f32_e32 v40, v40, v61
	v_add_f32_e32 v24, v24, v61
	v_mfma_f32_16x16x32_bf16 v[16:19], v[86:89], v[124:127], v[16:19]
	s_waitcnt vmcnt(0)
	v_add_f32_e32 v52, v52, v56
	v_bfe_u32 v57, v52, 16, 1
	v_add3_u32 v52, v52, v57, s33
	ds_write_b16_d16_hi v60, v52 offset:64
	v_add_f32_e32 v52, v53, v56
	v_bfe_u32 v53, v52, 16, 1
	v_add3_u32 v52, v52, v53, s33
	ds_write_b16_d16_hi v60, v52 offset:336
	v_add_f32_e32 v52, v54, v56
	v_bfe_u32 v53, v52, 16, 1
	v_add3_u32 v52, v52, v53, s33
	ds_write_b16_d16_hi v60, v52 offset:608
	v_add_f32_e32 v52, v55, v56
	v_bfe_u32 v53, v52, 16, 1
	v_add3_u32 v52, v52, v53, s33
	ds_write_b16_d16_hi v60, v52 offset:880
	global_load_dword v52, v74, s[10:11] offset:192
	v_add_f32_e32 v36, v36, v56
	v_add_f32_e32 v20, v20, v56
	v_mfma_f32_16x16x32_bf16 v[12:15], v[104:107], v[108:111], v[12:15]
	s_waitcnt vmcnt(0)
	v_add_f32_e32 v48, v48, v52
	v_bfe_u32 v53, v48, 16, 1
	v_add3_u32 v48, v48, v53, s33
	ds_write_b16_d16_hi v60, v48 offset:96
	v_add_f32_e32 v48, v49, v52
	v_bfe_u32 v49, v48, 16, 1
	v_add3_u32 v48, v48, v49, s33
	ds_write_b16_d16_hi v60, v48 offset:368
	v_add_f32_e32 v48, v50, v52
	v_bfe_u32 v49, v48, 16, 1
	v_add3_u32 v48, v48, v49, s33
	ds_write_b16_d16_hi v60, v48 offset:640
	v_add_f32_e32 v48, v51, v52
	v_bfe_u32 v49, v48, 16, 1
	v_add3_u32 v48, v48, v49, s33
	ds_write_b16_d16_hi v60, v48 offset:912
	v_bfe_u32 v48, v44, 16, 1
	v_add3_u32 v44, v44, v48, s33
	ds_write_b16_d16_hi v60, v44 offset:4352
	v_add_f32_e32 v44, v45, v73
	v_bfe_u32 v45, v44, 16, 1
	v_add3_u32 v44, v44, v45, s33
	ds_write_b16_d16_hi v60, v44 offset:4624
	v_add_f32_e32 v44, v46, v73
	v_bfe_u32 v45, v44, 16, 1
	v_add3_u32 v44, v44, v45, s33
	ds_write_b16_d16_hi v100, v44 offset:272
	v_add_f32_e32 v44, v47, v73
	v_bfe_u32 v45, v44, 16, 1
	v_add3_u32 v44, v44, v45, s33
	ds_write_b16_d16_hi v100, v44 offset:544
	v_bfe_u32 v44, v40, 16, 1
	v_add3_u32 v40, v40, v44, s33
	ds_write_b16_d16_hi v60, v40 offset:4384
	v_add_f32_e32 v40, v41, v61
	v_bfe_u32 v41, v40, 16, 1
	v_add3_u32 v40, v40, v41, s33
	ds_write_b16_d16_hi v100, v40 offset:32
	v_add_f32_e32 v40, v42, v61
	v_bfe_u32 v41, v40, 16, 1
	v_add3_u32 v40, v40, v41, s33
	ds_write_b16_d16_hi v100, v40 offset:304
	v_add_f32_e32 v40, v43, v61
	v_bfe_u32 v41, v40, 16, 1
	v_add3_u32 v40, v40, v41, s33
	ds_write_b16_d16_hi v100, v40 offset:576
	v_bfe_u32 v40, v36, 16, 1
	v_add3_u32 v36, v36, v40, s33
	ds_write_b16_d16_hi v60, v36 offset:4416
	v_add_f32_e32 v36, v37, v56
	v_bfe_u32 v37, v36, 16, 1
	v_add3_u32 v36, v36, v37, s33
	ds_write_b16_d16_hi v100, v36 offset:64
	v_add_f32_e32 v36, v38, v56
	v_bfe_u32 v37, v36, 16, 1
	v_add3_u32 v36, v36, v37, s33
	ds_write_b16_d16_hi v100, v36 offset:336
	v_add_f32_e32 v36, v39, v56
	v_bfe_u32 v37, v36, 16, 1
	v_add3_u32 v36, v36, v37, s33
	v_add_f32_e32 v32, v32, v52
	ds_write_b16_d16_hi v100, v36 offset:608
	v_bfe_u32 v36, v32, 16, 1
	v_add3_u32 v32, v32, v36, s33
	ds_write_b16_d16_hi v60, v32 offset:4448
	v_add_f32_e32 v32, v33, v52
	v_bfe_u32 v33, v32, 16, 1
	v_add3_u32 v32, v32, v33, s33
	ds_write_b16_d16_hi v100, v32 offset:96
	v_add_f32_e32 v32, v34, v52
	v_bfe_u32 v33, v32, 16, 1
	v_add3_u32 v32, v32, v33, s33
	ds_write_b16_d16_hi v100, v32 offset:368
	v_add_f32_e32 v32, v35, v52
	v_bfe_u32 v33, v32, 16, 1
	v_add3_u32 v32, v32, v33, s33
	ds_write_b16_d16_hi v100, v32 offset:640
	v_bfe_u32 v32, v28, 16, 1
	v_add3_u32 v28, v28, v32, s33
	ds_write_b16_d16_hi v100, v28 offset:4080
	v_add_f32_e32 v28, v29, v73
	v_bfe_u32 v29, v28, 16, 1
	v_add3_u32 v28, v28, v29, s33
	ds_write_b16_d16_hi v100, v28 offset:4352
	v_add_f32_e32 v28, v30, v73
	v_bfe_u32 v29, v28, 16, 1
	v_add3_u32 v28, v28, v29, s33
	ds_write_b16_d16_hi v100, v28 offset:4624
	v_add_f32_e32 v28, v31, v73
	v_bfe_u32 v29, v28, 16, 1
	v_add3_u32 v28, v28, v29, s33
	ds_write_b16_d16_hi v100, v28 offset:4896
	v_bfe_u32 v28, v24, 16, 1
	v_add3_u32 v24, v24, v28, s33
	ds_write_b16_d16_hi v100, v24 offset:4112
	v_add_f32_e32 v24, v25, v61
	v_bfe_u32 v25, v24, 16, 1
	v_add3_u32 v24, v24, v25, s33
	ds_write_b16_d16_hi v100, v24 offset:4384
	v_add_f32_e32 v24, v26, v61
	v_bfe_u32 v25, v24, 16, 1
	v_add3_u32 v24, v24, v25, s33
	ds_write_b16_d16_hi v100, v24 offset:4656
	v_add_f32_e32 v24, v27, v61
	v_bfe_u32 v25, v24, 16, 1
	v_add3_u32 v24, v24, v25, s33
	ds_write_b16_d16_hi v100, v24 offset:4928
	v_bfe_u32 v24, v20, 16, 1
	v_add3_u32 v20, v20, v24, s33
	ds_write_b16_d16_hi v100, v20 offset:4144
	v_add_f32_e32 v20, v21, v56
	v_bfe_u32 v21, v20, 16, 1
	v_add3_u32 v20, v20, v21, s33
	ds_write_b16_d16_hi v100, v20 offset:4416
	v_add_f32_e32 v20, v22, v56
	v_bfe_u32 v21, v20, 16, 1
	v_add3_u32 v20, v20, v21, s33
	ds_write_b16_d16_hi v100, v20 offset:4688
	v_add_f32_e32 v20, v23, v56
	v_bfe_u32 v21, v20, 16, 1
	v_add3_u32 v20, v20, v21, s33
	v_add_f32_e32 v16, v16, v52
	ds_write_b16_d16_hi v100, v20 offset:4960
	v_bfe_u32 v20, v16, 16, 1
	v_add3_u32 v16, v16, v20, s33
	ds_write_b16_d16_hi v100, v16 offset:4176
	v_add_f32_e32 v16, v17, v52
	v_bfe_u32 v17, v16, 16, 1
	v_add3_u32 v16, v16, v17, s33
	ds_write_b16_d16_hi v100, v16 offset:4448
	v_add_f32_e32 v16, v18, v52
	v_bfe_u32 v17, v16, 16, 1
	v_add3_u32 v16, v16, v17, s33
	ds_write_b16_d16_hi v100, v16 offset:4720
	v_add_f32_e32 v16, v19, v52
	v_bfe_u32 v17, v16, 16, 1
	v_add3_u32 v16, v16, v17, s33
	v_add_f32_e32 v12, v12, v73
	ds_write_b16_d16_hi v100, v16 offset:4992
	v_bfe_u32 v16, v12, 16, 1
	v_add3_u32 v12, v12, v16, s33
	ds_write_b16_d16_hi v100, v12 offset:8432
	v_add_f32_e32 v12, v13, v73
	v_bfe_u32 v13, v12, 16, 1
	v_add3_u32 v12, v12, v13, s33
	ds_write_b16_d16_hi v100, v12 offset:8704
	v_add_f32_e32 v12, v14, v73
	v_mfma_f32_16x16x32_bf16 v[8:11], v[104:107], v[116:119], v[8:11]
	v_bfe_u32 v13, v12, 16, 1
	v_add3_u32 v12, v12, v13, s33
	ds_write_b16_d16_hi v100, v12 offset:8976
	v_add_f32_e32 v12, v15, v73
	v_bfe_u32 v13, v12, 16, 1
	v_add3_u32 v12, v12, v13, s33
	s_nop 1
	v_add_f32_e32 v8, v8, v61
	ds_write_b16_d16_hi v100, v12 offset:9248
	v_bfe_u32 v12, v8, 16, 1
	v_add3_u32 v8, v8, v12, s33
	ds_write_b16_d16_hi v100, v8 offset:8464
	v_add_f32_e32 v8, v9, v61
	v_bfe_u32 v9, v8, 16, 1
	v_add3_u32 v8, v8, v9, s33
	ds_write_b16_d16_hi v100, v8 offset:8736
	v_add_f32_e32 v8, v10, v61
	v_mfma_f32_16x16x32_bf16 v[4:7], v[104:107], v[120:123], v[4:7]
	v_bfe_u32 v9, v8, 16, 1
	v_add3_u32 v8, v8, v9, s33
	ds_write_b16_d16_hi v100, v8 offset:9008
	v_add_f32_e32 v8, v11, v61
	v_bfe_u32 v9, v8, 16, 1
	v_add3_u32 v8, v8, v9, s33
	s_nop 1
	v_add_f32_e32 v4, v4, v56
	ds_write_b16_d16_hi v100, v8 offset:9280
	v_bfe_u32 v8, v4, 16, 1
	v_add3_u32 v4, v4, v8, s33
	ds_write_b16_d16_hi v100, v4 offset:8496
	v_add_f32_e32 v4, v5, v56
	v_bfe_u32 v5, v4, 16, 1
	v_add3_u32 v4, v4, v5, s33
	ds_write_b16_d16_hi v100, v4 offset:8768
	v_add_f32_e32 v4, v6, v56
	v_mfma_f32_16x16x32_bf16 v[0:3], v[104:107], v[124:127], v[0:3]
	v_bfe_u32 v5, v4, 16, 1
	v_add3_u32 v4, v4, v5, s33
	ds_write_b16_d16_hi v100, v4 offset:9040
	v_add_f32_e32 v4, v7, v56
	v_bfe_u32 v5, v4, 16, 1
	v_add3_u32 v4, v4, v5, s33
	s_nop 1
	v_add_f32_e32 v0, v0, v52
	ds_write_b16_d16_hi v100, v4 offset:9312
	v_bfe_u32 v4, v0, 16, 1
	v_add3_u32 v0, v0, v4, s33
	ds_write_b16_d16_hi v100, v0 offset:8528
	v_add_f32_e32 v0, v1, v52
	v_bfe_u32 v1, v0, 16, 1
	v_add3_u32 v0, v0, v1, s33
	ds_write_b16_d16_hi v100, v0 offset:8800
	v_add_f32_e32 v0, v2, v52
	v_bfe_u32 v1, v0, 16, 1
	v_add3_u32 v0, v0, v1, s33
	ds_write_b16_d16_hi v100, v0 offset:9072
	v_add_f32_e32 v0, v3, v52
	v_bfe_u32 v1, v0, 16, 1
	v_add3_u32 v0, v0, v1, s33
	ds_write_b16_d16_hi v100, v0 offset:9344
	s_waitcnt vmcnt(0)
	s_waitcnt lgkmcnt(0)
	s_barrier
	ds_read_b128 v[0:3], v101
	ds_read_b128 v[4:7], v101 offset:4352
	ds_read_b128 v[8:11], v101 offset:8704
	ds_read_b128 v[12:15], v101 offset:13056
	ds_read_b128 v[16:19], v102 offset:36864
	ds_read_b128 v[20:23], v102 offset:38912
	ds_read_b128 v[24:27], v102 offset:40960
	ds_read_b128 v[28:31], v102 offset:43008
	s_waitcnt lgkmcnt(3)
	v_mfma_f32_16x16x32_bf16 v[32:35], v[0:3], v[16:19], 0
	s_waitcnt lgkmcnt(2)
	v_mfma_f32_16x16x32_bf16 v[36:39], v[0:3], v[20:23], 0
	s_waitcnt lgkmcnt(1)
	v_mfma_f32_16x16x32_bf16 v[40:43], v[0:3], v[24:27], 0
	s_waitcnt lgkmcnt(0)
	v_mfma_f32_16x16x32_bf16 v[0:3], v[0:3], v[28:31], 0
	v_mfma_f32_16x16x32_bf16 v[44:47], v[4:7], v[16:19], 0
	v_mfma_f32_16x16x32_bf16 v[48:51], v[4:7], v[20:23], 0
	v_mfma_f32_16x16x32_bf16 v[52:55], v[4:7], v[24:27], 0
	v_mfma_f32_16x16x32_bf16 v[4:7], v[4:7], v[28:31], 0
	v_mfma_f32_16x16x32_bf16 v[56:59], v[8:11], v[16:19], 0
	v_mfma_f32_16x16x32_bf16 v[60:63], v[8:11], v[20:23], 0
	v_mfma_f32_16x16x32_bf16 v[74:77], v[8:11], v[24:27], 0
	v_mfma_f32_16x16x32_bf16 v[8:11], v[8:11], v[28:31], 0
	v_mfma_f32_16x16x32_bf16 v[16:19], v[12:15], v[16:19], 0
	v_mfma_f32_16x16x32_bf16 v[20:23], v[12:15], v[20:23], 0
	v_mfma_f32_16x16x32_bf16 v[24:27], v[12:15], v[24:27], 0
	v_mfma_f32_16x16x32_bf16 v[12:15], v[12:15], v[28:31], 0
	ds_read_b128 v[28:31], v101 offset:64
	ds_read_b128 v[82:85], v101 offset:4416
	ds_read_b128 v[86:89], v101 offset:8768
	ds_read_b128 v[104:107], v101 offset:13120
	ds_read_b128 v[108:111], v102 offset:37888
	ds_read_b128 v[116:119], v102 offset:39936
	ds_read_b128 v[120:123], v102 offset:41984
	ds_read_b128 v[124:127], v102 offset:44032
	s_waitcnt lgkmcnt(3)
	v_mfma_f32_16x16x32_bf16 v[32:35], v[28:31], v[108:111], v[32:35]
	s_waitcnt lgkmcnt(2)
	v_mfma_f32_16x16x32_bf16 v[36:39], v[28:31], v[116:119], v[36:39]
	s_waitcnt lgkmcnt(1)
	v_mfma_f32_16x16x32_bf16 v[40:43], v[28:31], v[120:123], v[40:43]
	s_waitcnt lgkmcnt(0)
	v_mfma_f32_16x16x32_bf16 v[0:3], v[28:31], v[124:127], v[0:3]
	v_mfma_f32_16x16x32_bf16 v[28:31], v[82:85], v[108:111], v[44:47]
	v_mfma_f32_16x16x32_bf16 v[44:47], v[82:85], v[116:119], v[48:51]
	v_mfma_f32_16x16x32_bf16 v[48:51], v[82:85], v[120:123], v[52:55]
	v_mfma_f32_16x16x32_bf16 v[4:7], v[82:85], v[124:127], v[4:7]
	v_mfma_f32_16x16x32_bf16 v[52:55], v[86:89], v[108:111], v[56:59]
	v_mfma_f32_16x16x32_bf16 v[56:59], v[86:89], v[116:119], v[60:63]
	v_mfma_f32_16x16x32_bf16 v[60:63], v[86:89], v[120:123], v[74:77]
	v_mfma_f32_16x16x32_bf16 v[8:11], v[86:89], v[124:127], v[8:11]
	v_mfma_f32_16x16x32_bf16 v[16:19], v[104:107], v[108:111], v[16:19]
	v_mfma_f32_16x16x32_bf16 v[20:23], v[104:107], v[116:119], v[20:23]
	v_mfma_f32_16x16x32_bf16 v[24:27], v[104:107], v[120:123], v[24:27]
	v_mfma_f32_16x16x32_bf16 v[12:15], v[104:107], v[124:127], v[12:15]
	ds_read_b128 v[74:77], v101 offset:128
	ds_read_b128 v[82:85], v101 offset:4480
	ds_read_b128 v[86:89], v101 offset:8832
	ds_read_b128 v[104:107], v101 offset:13184
	ds_read_b128 v[108:111], v102 offset:53248
	ds_read_b128 v[116:119], v102 offset:55296
	ds_read_b128 v[120:123], v102 offset:57344
	ds_read_b128 v[124:127], v102 offset:59392
	s_waitcnt lgkmcnt(3)
	v_mfma_f32_16x16x32_bf16 v[32:35], v[74:77], v[108:111], v[32:35]
	s_waitcnt lgkmcnt(2)
	v_mfma_f32_16x16x32_bf16 v[36:39], v[74:77], v[116:119], v[36:39]
	s_waitcnt lgkmcnt(1)
	v_mfma_f32_16x16x32_bf16 v[40:43], v[74:77], v[120:123], v[40:43]
	s_waitcnt lgkmcnt(0)
	v_mfma_f32_16x16x32_bf16 v[0:3], v[74:77], v[124:127], v[0:3]
	v_mfma_f32_16x16x32_bf16 v[28:31], v[82:85], v[108:111], v[28:31]
	v_mfma_f32_16x16x32_bf16 v[44:47], v[82:85], v[116:119], v[44:47]
	v_mfma_f32_16x16x32_bf16 v[48:51], v[82:85], v[120:123], v[48:51]
	v_mfma_f32_16x16x32_bf16 v[4:7], v[82:85], v[124:127], v[4:7]
	v_mfma_f32_16x16x32_bf16 v[52:55], v[86:89], v[108:111], v[52:55]
	v_mfma_f32_16x16x32_bf16 v[56:59], v[86:89], v[116:119], v[56:59]
	v_mfma_f32_16x16x32_bf16 v[60:63], v[86:89], v[120:123], v[60:63]
	v_mfma_f32_16x16x32_bf16 v[8:11], v[86:89], v[124:127], v[8:11]
	v_mfma_f32_16x16x32_bf16 v[74:77], v[104:107], v[108:111], v[16:19]
	v_mfma_f32_16x16x32_bf16 v[82:85], v[104:107], v[116:119], v[20:23]
	v_mfma_f32_16x16x32_bf16 v[24:27], v[104:107], v[120:123], v[24:27]
	v_mfma_f32_16x16x32_bf16 v[86:89], v[104:107], v[124:127], v[12:15]
	s_nop 2
	ds_read_b128 v[12:15], v101 offset:192
	ds_read_b128 v[16:19], v101 offset:4544
	ds_read_b128 v[104:107], v101 offset:8896
	ds_read_b128 v[108:111], v101 offset:13248
	ds_read_b128 v[116:119], v102 offset:54272
	ds_read_b128 v[120:123], v102 offset:56320
	ds_read_b128 v[124:127], v102 offset:58368
	ds_read_b128 v[128:131], v102 offset:60416
	s_waitcnt lgkmcnt(0)
	s_barrier
	v_mfma_f32_16x16x32_bf16 v[32:35], v[12:15], v[116:119], v[32:35]
	v_mfma_f32_16x16x32_bf16 v[36:39], v[12:15], v[120:123], v[36:39]
	v_mfma_f32_16x16x32_bf16 v[136:139], v[16:19], v[128:131], v[4:7]
	s_nop 5
	v_cmp_gt_i32_e64 s[0:1], 0, v32
	v_mfma_f32_16x16x32_bf16 v[4:7], v[108:111], v[124:127], v[24:27]
	s_nop 2
	v_not_b32_e32 v24, v32
	v_cndmask_b32_e64 v24, -|v32|, v24, s[0:1]
	v_not_b32_e32 v26, v33
	v_cmp_gt_i32_e64 s[0:1], 0, v33
	v_not_b32_e32 v27, v34
	v_not_b32_e32 v32, v35
	v_cndmask_b32_e64 v26, -|v33|, v26, s[0:1]
	v_cmp_gt_i32_e64 s[0:1], 0, v34
	v_not_b32_e32 v33, v36
	v_and_b32_e32 v24, 0xffffff80, v24
	v_cndmask_b32_e64 v27, -|v34|, v27, s[0:1]
	v_cmp_gt_i32_e64 s[0:1], 0, v35
	v_bitop3_b32 v24, v94, s17, v24 bitop3:0x36
	v_add_u32_e32 v25, v98, v99
	v_cndmask_b32_e64 v32, -|v35|, v32, s[0:1]
	v_cmp_gt_i32_e64 s[0:1], 0, v36
	v_and_b32_e32 v26, 0xffffff80, v26
	v_bitop3_b32 v26, v94, s17, v26 bitop3:0x36
	v_cndmask_b32_e64 v33, -|v36|, v33, s[0:1]
	v_and_b32_e32 v33, 0xffffff80, v33
	v_bitop3_b32 v33, v94, s21, v33 bitop3:0x36
	ds_write2_b32 v25, v24, v33 offset1:16
	v_not_b32_e32 v24, v37
	v_cmp_gt_i32_e64 s[0:1], 0, v37
	v_and_b32_e32 v27, 0xffffff80, v27
	v_bitop3_b32 v27, v94, s17, v27 bitop3:0x36
	v_cndmask_b32_e64 v24, -|v37|, v24, s[0:1]
	v_and_b32_e32 v24, 0xffffff80, v24
	v_bitop3_b32 v24, v94, s21, v24 bitop3:0x36
	ds_write2_b32 v25, v26, v24 offset0:129 offset1:145
	v_not_b32_e32 v24, v38
	v_cmp_gt_i32_e64 s[0:1], 0, v38
	v_add_u32_e32 v26, 0x400, v25
	v_mfma_f32_16x16x32_bf16 v[40:43], v[12:15], v[124:127], v[40:43]
	v_cndmask_b32_e64 v24, -|v38|, v24, s[0:1]
	v_and_b32_e32 v24, 0xffffff80, v24
	v_bitop3_b32 v24, v94, s21, v24 bitop3:0x36
	ds_write2_b32 v26, v27, v24 offset0:2 offset1:18
	v_not_b32_e32 v24, v39
	v_cmp_gt_i32_e64 s[0:1], 0, v39
	v_and_b32_e32 v32, 0xffffff80, v32
	v_bitop3_b32 v32, v94, s17, v32 bitop3:0x36
	v_cndmask_b32_e64 v24, -|v39|, v24, s[0:1]
	v_and_b32_e32 v24, 0xffffff80, v24
	v_bitop3_b32 v24, v94, s21, v24 bitop3:0x36
	v_mfma_f32_16x16x32_bf16 v[132:135], v[12:15], v[128:131], v[0:3]
	ds_write2_b32 v26, v32, v24 offset0:131 offset1:147
	v_not_b32_e32 v24, v40
	v_cmp_gt_i32_e64 s[0:1], 0, v40
	v_not_b32_e32 v27, v41
	v_not_b32_e32 v32, v42
	v_cndmask_b32_e64 v24, -|v40|, v24, s[0:1]
	v_cmp_gt_i32_e64 s[0:1], 0, v41
	v_not_b32_e32 v33, v43
	v_not_b32_e32 v34, v132
	v_cndmask_b32_e64 v27, -|v41|, v27, s[0:1]
	v_cmp_gt_i32_e64 s[0:1], 0, v42
	v_and_b32_e32 v24, 0xffffff80, v24
	v_bitop3_b32 v24, v94, s22, v24 bitop3:0x36
	v_cndmask_b32_e64 v32, -|v42|, v32, s[0:1]
	v_cmp_gt_i32_e64 s[0:1], 0, v43
	v_and_b32_e32 v27, 0xffffff80, v27
	v_bitop3_b32 v27, v94, s22, v27 bitop3:0x36
	v_cndmask_b32_e64 v33, -|v43|, v33, s[0:1]
	v_cmp_gt_i32_e64 s[0:1], 0, v132
	v_and_b32_e32 v32, 0xffffff80, v32
	v_bitop3_b32 v32, v94, s22, v32 bitop3:0x36
	v_cndmask_b32_e64 v34, -|v132|, v34, s[0:1]
	v_and_b32_e32 v34, 0xffffff80, v34
	v_bitop3_b32 v34, v94, s23, v34 bitop3:0x36
	ds_write2_b32 v25, v24, v34 offset0:32 offset1:48
	v_not_b32_e32 v24, v133
	v_cmp_gt_i32_e64 s[0:1], 0, v133
	v_mfma_f32_16x16x32_bf16 v[28:31], v[16:19], v[116:119], v[28:31]
	v_and_b32_e32 v33, 0xffffff80, v33
	v_cndmask_b32_e64 v24, -|v133|, v24, s[0:1]
	v_and_b32_e32 v24, 0xffffff80, v24
	v_bitop3_b32 v24, v94, s23, v24 bitop3:0x36
	ds_write2_b32 v25, v27, v24 offset0:161 offset1:177
	v_not_b32_e32 v24, v134
	v_cmp_gt_i32_e64 s[0:1], 0, v134
	v_bitop3_b32 v33, v94, s22, v33 bitop3:0x36
	v_mfma_f32_16x16x32_bf16 v[44:47], v[16:19], v[120:123], v[44:47]
	v_cndmask_b32_e64 v24, -|v134|, v24, s[0:1]
	v_and_b32_e32 v24, 0xffffff80, v24
	v_bitop3_b32 v24, v94, s23, v24 bitop3:0x36
	ds_write2_b32 v26, v32, v24 offset0:34 offset1:50
	v_not_b32_e32 v24, v135
	v_cmp_gt_i32_e64 s[0:1], 0, v135
	v_not_b32_e32 v27, v31
	v_mfma_f32_16x16x32_bf16 v[48:51], v[16:19], v[124:127], v[48:51]
	v_cndmask_b32_e64 v24, -|v135|, v24, s[0:1]
	v_and_b32_e32 v24, 0xffffff80, v24
	v_bitop3_b32 v24, v94, s23, v24 bitop3:0x36
	ds_write2_b32 v26, v33, v24 offset0:163 offset1:179
	v_not_b32_e32 v24, v28
	v_cmp_gt_i32_e64 s[0:1], 0, v28
	v_not_b32_e32 v26, v29
	v_mfma_f32_16x16x32_bf16 v[52:55], v[104:107], v[116:119], v[52:55]
	v_cndmask_b32_e64 v24, -|v28|, v24, s[0:1]
	v_cmp_gt_i32_e64 s[0:1], 0, v29
	v_not_b32_e32 v28, v44
	v_and_b32_e32 v24, 0xffffff80, v24
	v_cndmask_b32_e64 v26, -|v29|, v26, s[0:1]
	v_and_b32_e32 v26, 0xffffff80, v26
	v_bitop3_b32 v26, v94, s17, v26 bitop3:0x36
	ds_write_b32 v25, v26 offset:8772
	v_not_b32_e32 v26, v30
	v_cmp_gt_i32_e64 s[0:1], 0, v30
	v_bitop3_b32 v24, v94, s17, v24 bitop3:0x36
	v_add_u32_e32 v25, 0x2000, v25
	v_cndmask_b32_e64 v26, -|v30|, v26, s[0:1]
	v_cmp_gt_i32_e64 s[0:1], 0, v31
	v_not_b32_e32 v29, v47
	v_not_b32_e32 v30, v48
	v_cndmask_b32_e64 v27, -|v31|, v27, s[0:1]
	v_cmp_gt_i32_e64 s[0:1], 0, v44
	v_not_b32_e32 v31, v49
	v_and_b32_e32 v26, 0xffffff80, v26
	v_cndmask_b32_e64 v28, -|v44|, v28, s[0:1]
	v_and_b32_e32 v28, 0xffffff80, v28
	v_bitop3_b32 v28, v94, s21, v28 bitop3:0x36
	ds_write2_b32 v25, v24, v28 offset0:16 offset1:32
	v_not_b32_e32 v24, v45
	v_cmp_gt_i32_e64 s[0:1], 0, v45
	v_not_b32_e32 v28, v46
	v_bitop3_b32 v26, v94, s17, v26 bitop3:0x36
	v_cndmask_b32_e64 v24, -|v45|, v24, s[0:1]
	v_cmp_gt_i32_e64 s[0:1], 0, v46
	v_and_b32_e32 v24, 0xffffff80, v24
	v_bitop3_b32 v24, v94, s21, v24 bitop3:0x36
	v_cndmask_b32_e64 v28, -|v46|, v28, s[0:1]
	v_cmp_gt_i32_e64 s[0:1], 0, v47
	v_and_b32_e32 v28, 0xffffff80, v28
	v_bitop3_b32 v28, v94, s21, v28 bitop3:0x36
	v_cndmask_b32_e64 v29, -|v47|, v29, s[0:1]
	v_cmp_gt_i32_e64 s[0:1], 0, v48
	v_and_b32_e32 v29, 0xffffff80, v29
	v_bitop3_b32 v29, v94, s21, v29 bitop3:0x36
	v_cndmask_b32_e64 v30, -|v48|, v30, s[0:1]
	v_cmp_gt_i32_e64 s[0:1], 0, v49
	v_and_b32_e32 v30, 0xffffff80, v30
	v_bitop3_b32 v30, v94, s22, v30 bitop3:0x36
	v_cndmask_b32_e64 v31, -|v49|, v31, s[0:1]
	v_and_b32_e32 v31, 0xffffff80, v31
	v_bitop3_b32 v31, v94, s22, v31 bitop3:0x36
	ds_write2_b32 v103, v24, v31 offset0:16 offset1:32
	v_not_b32_e32 v24, v50
	v_cmp_gt_i32_e64 s[0:1], 0, v50
	v_and_b32_e32 v27, 0xffffff80, v27
	v_bitop3_b32 v27, v94, s17, v27 bitop3:0x36
	v_cndmask_b32_e64 v24, -|v50|, v24, s[0:1]
	v_and_b32_e32 v24, 0xffffff80, v24
	v_bitop3_b32 v24, v94, s22, v24 bitop3:0x36
	ds_write2_b32 v103, v28, v24 offset0:145 offset1:161
	v_not_b32_e32 v24, v51
	v_cmp_gt_i32_e64 s[0:1], 0, v51
	v_add_u32_e32 v28, 0x400, v103
	v_mfma_f32_16x16x32_bf16 v[56:59], v[104:107], v[120:123], v[56:59]
	v_cndmask_b32_e64 v24, -|v51|, v24, s[0:1]
	v_and_b32_e32 v24, 0xffffff80, v24
	v_bitop3_b32 v24, v94, s22, v24 bitop3:0x36
	ds_write2_b32 v28, v29, v24 offset0:18 offset1:34
	v_not_b32_e32 v24, v136
	v_cmp_gt_i32_e64 s[0:1], 0, v136
	s_nop 1
	v_not_b32_e32 v28, v56
	v_add_u32_e32 v29, 0x1c00, v103
	v_cndmask_b32_e64 v24, -|v136|, v24, s[0:1]
	v_and_b32_e32 v24, 0xffffff80, v24
	v_bitop3_b32 v24, v94, s23, v24 bitop3:0x36
	ds_write2_b32 v25, v30, v24 offset0:48 offset1:64
	v_not_b32_e32 v24, v137
	v_cmp_gt_i32_e64 s[0:1], 0, v137
	v_add_u32_e32 v25, 0x200, v103
	v_mfma_f32_16x16x32_bf16 v[20:23], v[104:107], v[124:127], v[60:63]
	v_cndmask_b32_e64 v24, -|v137|, v24, s[0:1]
	v_and_b32_e32 v24, 0xffffff80, v24
	v_bitop3_b32 v24, v94, s23, v24 bitop3:0x36
	ds_write2_b32 v103, v24, v26 offset0:48 offset1:129
	v_not_b32_e32 v24, v138
	v_cmp_gt_i32_e64 s[0:1], 0, v138
	v_not_b32_e32 v26, v54
	v_mfma_f32_16x16x32_bf16 v[16:19], v[104:107], v[128:131], v[8:11]
	v_cndmask_b32_e64 v24, -|v138|, v24, s[0:1]
	v_and_b32_e32 v24, 0xffffff80, v24
	v_bitop3_b32 v24, v94, s23, v24 bitop3:0x36
	ds_write2_b32 v25, v24, v27 offset0:49 offset1:130
	v_not_b32_e32 v24, v139
	v_cmp_gt_i32_e64 s[0:1], 0, v139
	v_not_b32_e32 v25, v53
	v_not_b32_e32 v27, v55
	v_cndmask_b32_e64 v24, -|v139|, v24, s[0:1]
	v_and_b32_e32 v24, 0xffffff80, v24
	v_bitop3_b32 v24, v94, s23, v24 bitop3:0x36
	ds_write_b32 v103, v24 offset:1224
	v_not_b32_e32 v24, v52
	v_cmp_gt_i32_e64 s[0:1], 0, v52
	v_mfma_f32_16x16x32_bf16 v[12:15], v[108:111], v[116:119], v[74:77]
	s_nop 0
	v_cndmask_b32_e64 v24, -|v52|, v24, s[0:1]
	v_cmp_gt_i32_e64 s[0:1], 0, v53
	v_and_b32_e32 v24, 0xffffff80, v24
	v_bitop3_b32 v24, v94, s17, v24 bitop3:0x36
	v_cndmask_b32_e64 v25, -|v53|, v25, s[0:1]
	v_cmp_gt_i32_e64 s[0:1], 0, v54
	v_and_b32_e32 v25, 0xffffff80, v25
	v_bitop3_b32 v25, v94, s17, v25 bitop3:0x36
	v_cndmask_b32_e64 v26, -|v54|, v26, s[0:1]
	v_cmp_gt_i32_e64 s[0:1], 0, v55
	v_and_b32_e32 v26, 0xffffff80, v26
	v_bitop3_b32 v26, v94, s17, v26 bitop3:0x36
	v_cndmask_b32_e64 v27, -|v55|, v27, s[0:1]
	v_cmp_gt_i32_e64 s[0:1], 0, v56
	v_and_b32_e32 v27, 0xffffff80, v27
	v_bitop3_b32 v27, v94, s17, v27 bitop3:0x36
	v_cndmask_b32_e64 v28, -|v56|, v28, s[0:1]
	v_and_b32_e32 v28, 0xffffff80, v28
	v_bitop3_b32 v28, v94, s21, v28 bitop3:0x36
	ds_write2_b32 v29, v24, v28 offset0:143 offset1:159
	v_not_b32_e32 v24, v57
	v_cmp_gt_i32_e64 s[0:1], 0, v57
	v_add_u32_e32 v28, 0x2000, v103
	v_mfma_f32_16x16x32_bf16 v[8:11], v[108:111], v[120:123], v[82:85]
	v_cndmask_b32_e64 v24, -|v57|, v24, s[0:1]
	v_and_b32_e32 v24, 0xffffff80, v24
	v_bitop3_b32 v24, v94, s21, v24 bitop3:0x36
	ds_write2_b32 v28, v25, v24 offset0:16 offset1:32
	v_not_b32_e32 v24, v58
	v_cmp_gt_i32_e64 s[0:1], 0, v58
	v_add_u32_e32 v25, 0x2400, v103
	v_mfma_f32_16x16x32_bf16 v[0:3], v[108:111], v[128:131], v[86:89]
	v_cndmask_b32_e64 v24, -|v58|, v24, s[0:1]
	v_and_b32_e32 v24, 0xffffff80, v24
	v_bitop3_b32 v24, v94, s21, v24 bitop3:0x36
	ds_write2_b32 v28, v26, v24 offset0:145 offset1:161
	v_not_b32_e32 v24, v59
	v_cmp_gt_i32_e64 s[0:1], 0, v59
	s_nop 1
	v_cndmask_b32_e64 v24, -|v59|, v24, s[0:1]
	v_and_b32_e32 v24, 0xffffff80, v24
	v_bitop3_b32 v24, v94, s21, v24 bitop3:0x36
	ds_write2_b32 v25, v27, v24 offset0:18 offset1:34
	v_not_b32_e32 v24, v20
	v_cmp_gt_i32_e64 s[0:1], 0, v20
	s_nop 1
	v_cndmask_b32_e64 v20, -|v20|, v24, s[0:1]
	v_not_b32_e32 v24, v21
	v_cmp_gt_i32_e64 s[0:1], 0, v21
	v_and_b32_e32 v20, 0xffffff80, v20
	v_bitop3_b32 v20, v94, s22, v20 bitop3:0x36
	v_cndmask_b32_e64 v21, -|v21|, v24, s[0:1]
	v_not_b32_e32 v24, v22
	v_cmp_gt_i32_e64 s[0:1], 0, v22
	v_and_b32_e32 v21, 0xffffff80, v21
	v_bitop3_b32 v21, v94, s22, v21 bitop3:0x36
	v_cndmask_b32_e64 v22, -|v22|, v24, s[0:1]
	v_not_b32_e32 v24, v23
	v_cmp_gt_i32_e64 s[0:1], 0, v23
	v_and_b32_e32 v22, 0xffffff80, v22
	v_bitop3_b32 v22, v94, s22, v22 bitop3:0x36
	v_cndmask_b32_e64 v23, -|v23|, v24, s[0:1]
	v_not_b32_e32 v24, v16
	v_cmp_gt_i32_e64 s[0:1], 0, v16
	v_and_b32_e32 v23, 0xffffff80, v23
	v_bitop3_b32 v23, v94, s22, v23 bitop3:0x36
	v_cndmask_b32_e64 v16, -|v16|, v24, s[0:1]
	v_and_b32_e32 v16, 0xffffff80, v16
	v_bitop3_b32 v16, v94, s23, v16 bitop3:0x36
	ds_write2_b32 v29, v20, v16 offset0:175 offset1:191
	v_not_b32_e32 v16, v17
	v_cmp_gt_i32_e64 s[0:1], 0, v17
	s_nop 1
	v_cndmask_b32_e64 v16, -|v17|, v16, s[0:1]
	v_and_b32_e32 v16, 0xffffff80, v16
	v_bitop3_b32 v16, v94, s23, v16 bitop3:0x36
	ds_write2_b32 v28, v21, v16 offset0:48 offset1:64
	v_not_b32_e32 v16, v18
	v_cmp_gt_i32_e64 s[0:1], 0, v18
	s_nop 1
	v_cndmask_b32_e64 v16, -|v18|, v16, s[0:1]
	v_and_b32_e32 v16, 0xffffff80, v16
	v_bitop3_b32 v16, v94, s23, v16 bitop3:0x36
	ds_write2_b32 v28, v22, v16 offset0:177 offset1:193
	v_not_b32_e32 v16, v19
	v_cmp_gt_i32_e64 s[0:1], 0, v19
	s_nop 1
	v_cndmask_b32_e64 v16, -|v19|, v16, s[0:1]
	v_and_b32_e32 v16, 0xffffff80, v16
	v_bitop3_b32 v16, v94, s23, v16 bitop3:0x36
	ds_write2_b32 v25, v23, v16 offset0:50 offset1:66
	v_not_b32_e32 v16, v12
	v_cmp_gt_i32_e64 s[0:1], 0, v12
	s_nop 1
	v_cndmask_b32_e64 v12, -|v12|, v16, s[0:1]
	v_not_b32_e32 v16, v13
	v_cmp_gt_i32_e64 s[0:1], 0, v13
	v_and_b32_e32 v12, 0xffffff80, v12
	v_bitop3_b32 v12, v94, s17, v12 bitop3:0x36
	v_cndmask_b32_e64 v13, -|v13|, v16, s[0:1]
	v_not_b32_e32 v16, v14
	v_cmp_gt_i32_e64 s[0:1], 0, v14
	v_and_b32_e32 v13, 0xffffff80, v13
	v_bitop3_b32 v13, v94, s17, v13 bitop3:0x36
	v_cndmask_b32_e64 v14, -|v14|, v16, s[0:1]
	v_not_b32_e32 v16, v15
	v_cmp_gt_i32_e64 s[0:1], 0, v15
	v_and_b32_e32 v14, 0xffffff80, v14
	v_bitop3_b32 v14, v94, s17, v14 bitop3:0x36
	v_cndmask_b32_e64 v15, -|v15|, v16, s[0:1]
	v_not_b32_e32 v16, v8
	v_cmp_gt_i32_e64 s[0:1], 0, v8
	v_and_b32_e32 v15, 0xffffff80, v15
	v_bitop3_b32 v15, v94, s17, v15 bitop3:0x36
	v_cndmask_b32_e64 v8, -|v8|, v16, s[0:1]
	v_and_b32_e32 v8, 0xffffff80, v8
	v_bitop3_b32 v8, v94, s21, v8 bitop3:0x36
	v_add_u32_e32 v16, 0x3c00, v103
	ds_write2_b32 v16, v12, v8 offset0:159 offset1:175
	v_not_b32_e32 v8, v9
	v_cmp_gt_i32_e64 s[0:1], 0, v9
	s_nop 1
	v_cndmask_b32_e64 v8, -|v9|, v8, s[0:1]
	v_and_b32_e32 v8, 0xffffff80, v8
	v_bitop3_b32 v8, v94, s21, v8 bitop3:0x36
	v_add_u32_e32 v9, 0x4000, v103
	ds_write2_b32 v9, v13, v8 offset0:32 offset1:48
	v_not_b32_e32 v8, v10
	v_cmp_gt_i32_e64 s[0:1], 0, v10
	s_nop 1
	v_cndmask_b32_e64 v8, -|v10|, v8, s[0:1]
	v_and_b32_e32 v8, 0xffffff80, v8
	v_bitop3_b32 v8, v94, s21, v8 bitop3:0x36
	ds_write2_b32 v9, v14, v8 offset0:161 offset1:177
	v_not_b32_e32 v8, v11
	v_cmp_gt_i32_e64 s[0:1], 0, v11
	v_add_u32_e32 v10, 0x4400, v103
	s_nop 0
	v_cndmask_b32_e64 v8, -|v11|, v8, s[0:1]
	v_and_b32_e32 v8, 0xffffff80, v8
	v_bitop3_b32 v8, v94, s21, v8 bitop3:0x36
	ds_write2_b32 v10, v15, v8 offset0:34 offset1:50
	v_not_b32_e32 v8, v4
	v_cmp_gt_i32_e64 s[0:1], 0, v4
	s_nop 1
	v_cndmask_b32_e64 v4, -|v4|, v8, s[0:1]
	v_not_b32_e32 v8, v5
	v_cmp_gt_i32_e64 s[0:1], 0, v5
	v_and_b32_e32 v4, 0xffffff80, v4
	v_bitop3_b32 v4, v94, s22, v4 bitop3:0x36
	v_cndmask_b32_e64 v5, -|v5|, v8, s[0:1]
	v_not_b32_e32 v8, v6
	v_cmp_gt_i32_e64 s[0:1], 0, v6
	v_and_b32_e32 v5, 0xffffff80, v5
	v_bitop3_b32 v5, v94, s22, v5 bitop3:0x36
	v_cndmask_b32_e64 v6, -|v6|, v8, s[0:1]
	v_not_b32_e32 v8, v7
	v_cmp_gt_i32_e64 s[0:1], 0, v7
	v_and_b32_e32 v6, 0xffffff80, v6
	v_bitop3_b32 v6, v94, s22, v6 bitop3:0x36
	v_cndmask_b32_e64 v7, -|v7|, v8, s[0:1]
	v_not_b32_e32 v8, v0
	v_cmp_gt_i32_e64 s[0:1], 0, v0
	v_and_b32_e32 v7, 0xffffff80, v7
	v_bitop3_b32 v7, v94, s22, v7 bitop3:0x36
	v_cndmask_b32_e64 v0, -|v0|, v8, s[0:1]
	v_and_b32_e32 v0, 0xffffff80, v0
	v_bitop3_b32 v0, v94, s23, v0 bitop3:0x36
	ds_write2_b32 v16, v4, v0 offset0:191 offset1:207
	v_not_b32_e32 v0, v1
	v_cmp_gt_i32_e64 s[0:1], 0, v1
	s_nop 1
	v_cndmask_b32_e64 v0, -|v1|, v0, s[0:1]
	v_and_b32_e32 v0, 0xffffff80, v0
	v_bitop3_b32 v0, v94, s23, v0 bitop3:0x36
	ds_write2_b32 v9, v5, v0 offset0:64 offset1:80
	v_not_b32_e32 v0, v2
	v_cmp_gt_i32_e64 s[0:1], 0, v2
	s_nop 1
	v_cndmask_b32_e64 v0, -|v2|, v0, s[0:1]
	v_and_b32_e32 v0, 0xffffff80, v0
	v_bitop3_b32 v0, v94, s23, v0 bitop3:0x36
	ds_write2_b32 v9, v6, v0 offset0:193 offset1:209
	v_not_b32_e32 v0, v3
	v_cmp_gt_i32_e64 s[0:1], 0, v3
	s_nop 1
	v_cndmask_b32_e64 v0, -|v3|, v0, s[0:1]
	v_and_b32_e32 v0, 0xffffff80, v0
	v_bitop3_b32 v0, v94, s23, v0 bitop3:0x36
	ds_write2_b32 v10, v7, v0 offset0:66 offset1:82
	s_waitcnt lgkmcnt(0)
	s_barrier
	s_and_saveexec_b64 s[0:1], vcc
	s_cbranch_execz .LBB0_19
	ds_read2_b32 v[0:1], v95 offset1:1
	ds_read2_b32 v[2:3], v95 offset0:2 offset1:3
	ds_read2_b32 v[4:5], v95 offset0:4 offset1:5
	ds_read2_b32 v[6:7], v95 offset0:6 offset1:7
	ds_read2_b32 v[8:9], v95 offset0:8 offset1:9
	ds_read2_b32 v[10:11], v95 offset0:10 offset1:11
	ds_read2_b32 v[12:13], v95 offset0:12 offset1:13
	ds_read2_b32 v[14:15], v95 offset0:14 offset1:15
	ds_read2_b32 v[16:17], v95 offset0:16 offset1:17
	ds_read2_b32 v[18:19], v95 offset0:18 offset1:19
	ds_read2_b32 v[20:21], v95 offset0:20 offset1:21
	ds_read2_b32 v[22:23], v95 offset0:22 offset1:23
	ds_read2_b32 v[24:25], v95 offset0:24 offset1:25
	ds_read2_b32 v[26:27], v95 offset0:26 offset1:27
	ds_read2_b32 v[28:29], v95 offset0:28 offset1:29
	ds_read2_b32 v[30:31], v95 offset0:30 offset1:31
	ds_read2_b32 v[32:33], v95 offset0:32 offset1:33
	ds_read2_b32 v[34:35], v95 offset0:34 offset1:35
	ds_read2_b32 v[36:37], v95 offset0:36 offset1:37
	ds_read2_b32 v[38:39], v95 offset0:38 offset1:39
	ds_read2_b32 v[40:41], v95 offset0:40 offset1:41
	ds_read2_b32 v[42:43], v95 offset0:42 offset1:43
	ds_read2_b32 v[44:45], v95 offset0:44 offset1:45
	ds_read2_b32 v[46:47], v95 offset0:46 offset1:47
	ds_read2_b32 v[48:49], v95 offset0:48 offset1:49
	ds_read2_b32 v[50:51], v95 offset0:50 offset1:51
	ds_read2_b32 v[52:53], v95 offset0:52 offset1:53
	ds_read2_b32 v[54:55], v95 offset0:54 offset1:55
	ds_read2_b32 v[56:57], v95 offset0:56 offset1:57
	ds_read2_b32 v[58:59], v95 offset0:58 offset1:59
	ds_read2_b32 v[60:61], v95 offset0:60 offset1:61
	ds_read2_b32 v[62:63], v95 offset0:62 offset1:63
	ds_read2_b32 v[74:75], v95 offset0:64 offset1:65
	ds_read2_b32 v[76:77], v95 offset0:66 offset1:67
	ds_read2_b32 v[78:79], v95 offset0:68 offset1:69
	ds_read2_b32 v[82:83], v95 offset0:70 offset1:71
	ds_read2_b32 v[84:85], v95 offset0:72 offset1:73
	ds_read2_b32 v[86:87], v95 offset0:74 offset1:75
	ds_read2_b32 v[88:89], v95 offset0:76 offset1:77
	ds_read2_b32 v[90:91], v95 offset0:78 offset1:79
	ds_read2_b32 v[104:105], v95 offset0:80 offset1:81
	ds_read2_b32 v[106:107], v95 offset0:82 offset1:83
	ds_read2_b32 v[108:109], v95 offset0:84 offset1:85
	ds_read2_b32 v[110:111], v95 offset0:86 offset1:87
	ds_read2_b32 v[112:113], v95 offset0:88 offset1:89
	ds_read2_b32 v[116:117], v95 offset0:90 offset1:91
	ds_read2_b32 v[118:119], v95 offset0:92 offset1:93
	ds_read2_b32 v[120:121], v95 offset0:94 offset1:95
	ds_read2_b32 v[122:123], v95 offset0:96 offset1:97
	ds_read2_b32 v[124:125], v95 offset0:98 offset1:99
	ds_read2_b32 v[126:127], v95 offset0:100 offset1:101
	ds_read2_b32 v[128:129], v95 offset0:102 offset1:103
	ds_read2_b32 v[130:131], v95 offset0:104 offset1:105
	ds_read2_b32 v[132:133], v95 offset0:106 offset1:107
	ds_read2_b32 v[134:135], v95 offset0:108 offset1:109
	ds_read2_b32 v[136:137], v95 offset0:110 offset1:111
	ds_read2_b32 v[138:139], v95 offset0:112 offset1:113
	ds_read2_b32 v[140:141], v95 offset0:114 offset1:115
	ds_read2_b32 v[142:143], v95 offset0:116 offset1:117
	ds_read2_b32 v[144:145], v95 offset0:118 offset1:119
	ds_read2_b32 v[146:147], v95 offset0:120 offset1:121
	ds_read2_b32 v[148:149], v95 offset0:122 offset1:123
	ds_read2_b32 v[150:151], v95 offset0:124 offset1:125
	ds_read2_b32 v[152:153], v95 offset0:126 offset1:127
	s_waitcnt lgkmcnt(14)
	v_max_u32_e32 v73, v0, v1
	v_min_u32_e32 v0, v0, v1
	v_max_u32_e32 v1, v2, v3
	v_min_u32_e32 v2, v2, v3
	v_max_u32_e32 v3, v4, v5
	v_min_u32_e32 v4, v4, v5
	v_max_u32_e32 v5, v6, v7
	v_min_u32_e32 v6, v6, v7
	v_max_u32_e32 v7, v8, v9
	v_min_u32_e32 v8, v8, v9
	v_max_u32_e32 v9, v10, v11
	v_min_u32_e32 v10, v10, v11
	v_max_u32_e32 v11, v12, v13
	v_min_u32_e32 v12, v12, v13
	v_max_u32_e32 v13, v14, v15
	v_min_u32_e32 v14, v14, v15
	v_max_u32_e32 v15, v16, v17
	v_min_u32_e32 v16, v16, v17
	v_max_u32_e32 v17, v18, v19
	v_min_u32_e32 v18, v18, v19
	v_max_u32_e32 v19, v20, v21
	v_min_u32_e32 v20, v20, v21
	v_max_u32_e32 v21, v22, v23
	v_min_u32_e32 v22, v22, v23
	v_max_u32_e32 v23, v24, v25
	v_min_u32_e32 v24, v24, v25
	v_max_u32_e32 v25, v26, v27
	v_min_u32_e32 v26, v26, v27
	v_max_u32_e32 v27, v28, v29
	v_min_u32_e32 v28, v28, v29
	v_max_u32_e32 v29, v30, v31
	v_min_u32_e32 v30, v30, v31
	v_max_u32_e32 v31, v32, v33
	v_min_u32_e32 v32, v32, v33
	v_max_u32_e32 v33, v34, v35
	v_min_u32_e32 v34, v34, v35
	v_max_u32_e32 v35, v36, v37
	v_min_u32_e32 v36, v36, v37
	v_max_u32_e32 v37, v38, v39
	v_min_u32_e32 v38, v38, v39
	v_max_u32_e32 v39, v40, v41
	v_min_u32_e32 v40, v40, v41
	v_max_u32_e32 v41, v42, v43
	v_min_u32_e32 v42, v42, v43
	v_max_u32_e32 v43, v44, v45
	v_min_u32_e32 v44, v44, v45
	v_max_u32_e32 v45, v46, v47
	v_min_u32_e32 v46, v46, v47
	v_max_u32_e32 v47, v48, v49
	v_min_u32_e32 v48, v48, v49
	v_max_u32_e32 v49, v50, v51
	v_min_u32_e32 v50, v50, v51
	v_max_u32_e32 v51, v52, v53
	v_min_u32_e32 v52, v52, v53
	v_max_u32_e32 v53, v54, v55
	v_min_u32_e32 v54, v54, v55
	v_max_u32_e32 v55, v56, v57
	v_min_u32_e32 v56, v56, v57
	v_max_u32_e32 v57, v58, v59
	v_min_u32_e32 v58, v58, v59
	v_max_u32_e32 v59, v60, v61
	v_min_u32_e32 v60, v60, v61
	v_max_u32_e32 v61, v62, v63
	v_min_u32_e32 v62, v62, v63
	v_max_u32_e32 v63, v74, v75
	v_min_u32_e32 v74, v74, v75
	v_max_u32_e32 v75, v76, v77
	v_min_u32_e32 v76, v76, v77
	v_max_u32_e32 v77, v78, v79
	v_min_u32_e32 v78, v78, v79
	v_max_u32_e32 v79, v82, v83
	v_min_u32_e32 v82, v82, v83
	v_max_u32_e32 v83, v84, v85
	v_min_u32_e32 v84, v84, v85
	v_max_u32_e32 v85, v86, v87
	v_min_u32_e32 v86, v86, v87
	v_max_u32_e32 v87, v88, v89
	v_min_u32_e32 v88, v88, v89
	v_max_u32_e32 v89, v90, v91
	v_min_u32_e32 v90, v90, v91
	v_max_u32_e32 v91, v104, v105
	v_min_u32_e32 v104, v104, v105
	v_max_u32_e32 v105, v106, v107
	v_min_u32_e32 v106, v106, v107
	v_max_u32_e32 v107, v108, v109
	v_min_u32_e32 v108, v108, v109
	v_max_u32_e32 v109, v110, v111
	v_min_u32_e32 v110, v110, v111
	v_max_u32_e32 v111, v112, v113
	v_min_u32_e32 v112, v112, v113
	v_max_u32_e32 v113, v116, v117
	v_min_u32_e32 v116, v116, v117
	v_max_u32_e32 v117, v118, v119
	v_min_u32_e32 v118, v118, v119
	v_max_u32_e32 v119, v120, v121
	v_min_u32_e32 v120, v120, v121
	v_max_u32_e32 v121, v122, v123
	v_min_u32_e32 v122, v122, v123
	v_max_u32_e32 v123, v124, v125
	v_min_u32_e32 v124, v124, v125
	s_waitcnt lgkmcnt(13)
	v_max_u32_e32 v125, v126, v127
	v_min_u32_e32 v126, v126, v127
	s_waitcnt lgkmcnt(12)
	v_max_u32_e32 v127, v128, v129
	v_min_u32_e32 v128, v128, v129
	s_waitcnt lgkmcnt(11)
	v_max_u32_e32 v129, v130, v131
	v_min_u32_e32 v130, v130, v131
	s_waitcnt lgkmcnt(10)
	v_max_u32_e32 v131, v132, v133
	v_min_u32_e32 v132, v132, v133
	s_waitcnt lgkmcnt(9)
	v_max_u32_e32 v133, v134, v135
	v_min_u32_e32 v134, v134, v135
	s_waitcnt lgkmcnt(8)
	v_max_u32_e32 v135, v136, v137
	v_min_u32_e32 v136, v136, v137
	s_waitcnt lgkmcnt(7)
	v_max_u32_e32 v137, v138, v139
	v_min_u32_e32 v138, v138, v139
	s_waitcnt lgkmcnt(6)
	v_max_u32_e32 v139, v140, v141
	v_min_u32_e32 v140, v140, v141
	s_waitcnt lgkmcnt(5)
	v_max_u32_e32 v141, v142, v143
	v_min_u32_e32 v142, v142, v143
	s_waitcnt lgkmcnt(4)
	v_max_u32_e32 v143, v144, v145
	v_min_u32_e32 v144, v144, v145
	s_waitcnt lgkmcnt(3)
	v_max_u32_e32 v145, v146, v147
	v_min_u32_e32 v146, v146, v147
	s_waitcnt lgkmcnt(2)
	v_max_u32_e32 v147, v148, v149
	v_min_u32_e32 v148, v148, v149
	s_waitcnt lgkmcnt(1)
	v_max_u32_e32 v149, v150, v151
	v_min_u32_e32 v150, v150, v151
	s_waitcnt lgkmcnt(0)
	v_max_u32_e32 v151, v152, v153
	v_min_u32_e32 v152, v152, v153
	v_max_u32_e32 v153, v73, v2
	v_min_u32_e32 v2, v73, v2
	v_max_u32_e32 v73, v0, v1
	v_min_u32_e32 v0, v0, v1
	v_max_u32_e32 v1, v3, v6
	v_min_u32_e32 v3, v3, v6
	v_max_u32_e32 v6, v4, v5
	v_min_u32_e32 v4, v4, v5
	v_max_u32_e32 v5, v7, v10
	v_min_u32_e32 v7, v7, v10
	v_max_u32_e32 v10, v8, v9
	v_min_u32_e32 v8, v8, v9
	v_max_u32_e32 v9, v11, v14
	v_min_u32_e32 v11, v11, v14
	v_max_u32_e32 v14, v12, v13
	v_min_u32_e32 v12, v12, v13
	v_max_u32_e32 v13, v15, v18
	v_min_u32_e32 v15, v15, v18
	v_max_u32_e32 v18, v16, v17
	v_min_u32_e32 v16, v16, v17
	v_max_u32_e32 v17, v19, v22
	v_min_u32_e32 v19, v19, v22
	v_max_u32_e32 v22, v20, v21
	v_min_u32_e32 v20, v20, v21
	v_max_u32_e32 v21, v23, v26
	v_min_u32_e32 v23, v23, v26
	v_max_u32_e32 v26, v24, v25
	v_min_u32_e32 v24, v24, v25
	v_max_u32_e32 v25, v27, v30
	v_min_u32_e32 v27, v27, v30
	v_max_u32_e32 v30, v28, v29
	v_min_u32_e32 v28, v28, v29
	v_max_u32_e32 v29, v31, v34
	v_min_u32_e32 v31, v31, v34
	v_max_u32_e32 v34, v32, v33
	v_min_u32_e32 v32, v32, v33
	v_max_u32_e32 v33, v35, v38
	v_min_u32_e32 v35, v35, v38
	v_max_u32_e32 v38, v36, v37
	v_min_u32_e32 v36, v36, v37
	v_max_u32_e32 v37, v39, v42
	v_min_u32_e32 v39, v39, v42
	v_max_u32_e32 v42, v40, v41
	v_min_u32_e32 v40, v40, v41
	v_max_u32_e32 v41, v43, v46
	v_min_u32_e32 v43, v43, v46
	v_max_u32_e32 v46, v44, v45
	v_min_u32_e32 v44, v44, v45
	v_max_u32_e32 v45, v47, v50
	v_min_u32_e32 v47, v47, v50
	v_max_u32_e32 v50, v48, v49
	v_min_u32_e32 v48, v48, v49
	v_max_u32_e32 v49, v51, v54
	v_min_u32_e32 v51, v51, v54
	v_max_u32_e32 v54, v52, v53
	v_min_u32_e32 v52, v52, v53
	v_max_u32_e32 v53, v55, v58
	v_min_u32_e32 v55, v55, v58
	v_max_u32_e32 v58, v56, v57
	v_min_u32_e32 v56, v56, v57
	v_max_u32_e32 v57, v59, v62
	v_min_u32_e32 v59, v59, v62
	v_max_u32_e32 v62, v60, v61
	v_min_u32_e32 v60, v60, v61
	v_max_u32_e32 v61, v63, v76
	v_min_u32_e32 v63, v63, v76
	v_max_u32_e32 v76, v74, v75
	v_min_u32_e32 v74, v74, v75
	v_max_u32_e32 v75, v77, v82
	v_min_u32_e32 v77, v77, v82
	v_max_u32_e32 v82, v78, v79
	v_min_u32_e32 v78, v78, v79
	v_max_u32_e32 v79, v83, v86
	v_min_u32_e32 v83, v83, v86
	v_max_u32_e32 v86, v84, v85
	v_min_u32_e32 v84, v84, v85
	v_max_u32_e32 v85, v87, v90
	v_min_u32_e32 v87, v87, v90
	v_max_u32_e32 v90, v88, v89
	v_min_u32_e32 v88, v88, v89
	v_max_u32_e32 v89, v91, v106
	v_min_u32_e32 v91, v91, v106
	v_max_u32_e32 v106, v104, v105
	v_min_u32_e32 v104, v104, v105
	v_max_u32_e32 v105, v107, v110
	v_min_u32_e32 v107, v107, v110
	v_max_u32_e32 v110, v108, v109
	v_min_u32_e32 v108, v108, v109
	v_max_u32_e32 v109, v111, v116
	v_min_u32_e32 v111, v111, v116
	v_max_u32_e32 v116, v112, v113
	v_min_u32_e32 v112, v112, v113
	v_max_u32_e32 v113, v117, v120
	v_min_u32_e32 v117, v117, v120
	v_max_u32_e32 v120, v118, v119
	v_min_u32_e32 v118, v118, v119
	v_max_u32_e32 v119, v121, v124
	v_min_u32_e32 v121, v121, v124
	v_max_u32_e32 v124, v122, v123
	v_min_u32_e32 v122, v122, v123
	v_max_u32_e32 v123, v125, v128
	v_min_u32_e32 v125, v125, v128
	v_max_u32_e32 v128, v126, v127
	v_min_u32_e32 v126, v126, v127
	v_max_u32_e32 v127, v129, v132
	v_min_u32_e32 v129, v129, v132
	v_max_u32_e32 v132, v130, v131
	v_min_u32_e32 v130, v130, v131
	v_max_u32_e32 v131, v133, v136
	v_min_u32_e32 v133, v133, v136
	v_max_u32_e32 v136, v134, v135
	v_min_u32_e32 v134, v134, v135
	v_max_u32_e32 v135, v137, v140
	v_min_u32_e32 v137, v137, v140
	v_max_u32_e32 v140, v138, v139
	v_min_u32_e32 v138, v138, v139
	v_max_u32_e32 v139, v141, v144
	v_min_u32_e32 v141, v141, v144
	v_max_u32_e32 v144, v142, v143
	v_min_u32_e32 v142, v142, v143
	v_max_u32_e32 v143, v145, v148
	v_min_u32_e32 v145, v145, v148
	v_max_u32_e32 v148, v146, v147
	v_min_u32_e32 v146, v146, v147
	v_max_u32_e32 v147, v149, v152
	v_min_u32_e32 v149, v149, v152
	v_max_u32_e32 v152, v150, v151
	v_min_u32_e32 v150, v150, v151
	v_max_u32_e32 v151, v153, v73
	v_min_u32_e32 v73, v153, v73
	v_max_u32_e32 v153, v2, v0
	v_min_u32_e32 v0, v2, v0
	v_max_u32_e32 v2, v3, v4
	v_min_u32_e32 v3, v3, v4
	v_max_u32_e32 v4, v1, v6
	v_min_u32_e32 v1, v1, v6
	v_max_u32_e32 v6, v5, v10
	v_min_u32_e32 v5, v5, v10
	v_max_u32_e32 v10, v7, v8
	v_min_u32_e32 v7, v7, v8
	v_max_u32_e32 v8, v11, v12
	v_min_u32_e32 v11, v11, v12
	v_max_u32_e32 v12, v9, v14
	v_min_u32_e32 v9, v9, v14
	v_max_u32_e32 v14, v13, v18
	v_min_u32_e32 v13, v13, v18
	v_max_u32_e32 v18, v15, v16
	v_min_u32_e32 v15, v15, v16
	v_max_u32_e32 v16, v19, v20
	v_min_u32_e32 v19, v19, v20
	v_max_u32_e32 v20, v17, v22
	v_min_u32_e32 v17, v17, v22
	v_max_u32_e32 v22, v21, v26
	v_min_u32_e32 v21, v21, v26
	v_max_u32_e32 v26, v23, v24
	v_min_u32_e32 v23, v23, v24
	v_max_u32_e32 v24, v27, v28
	v_min_u32_e32 v27, v27, v28
	v_max_u32_e32 v28, v25, v30
	v_min_u32_e32 v25, v25, v30
	v_max_u32_e32 v30, v29, v34
	v_min_u32_e32 v29, v29, v34
	v_max_u32_e32 v34, v31, v32
	v_min_u32_e32 v31, v31, v32
	v_max_u32_e32 v32, v35, v36
	v_min_u32_e32 v35, v35, v36
	v_max_u32_e32 v36, v33, v38
	v_min_u32_e32 v33, v33, v38
	v_max_u32_e32 v38, v37, v42
	v_min_u32_e32 v37, v37, v42
	v_max_u32_e32 v42, v39, v40
	v_min_u32_e32 v39, v39, v40
	v_max_u32_e32 v40, v43, v44
	v_min_u32_e32 v43, v43, v44
	v_max_u32_e32 v44, v41, v46
	v_min_u32_e32 v41, v41, v46
	v_max_u32_e32 v46, v45, v50
	v_min_u32_e32 v45, v45, v50
	v_max_u32_e32 v50, v47, v48
	v_min_u32_e32 v47, v47, v48
	v_max_u32_e32 v48, v51, v52
	v_min_u32_e32 v51, v51, v52
	v_max_u32_e32 v52, v49, v54
	v_min_u32_e32 v49, v49, v54
	v_max_u32_e32 v54, v53, v58
	v_min_u32_e32 v53, v53, v58
	v_max_u32_e32 v58, v55, v56
	v_min_u32_e32 v55, v55, v56
	v_max_u32_e32 v56, v59, v60
	v_min_u32_e32 v59, v59, v60
	v_max_u32_e32 v60, v57, v62
	v_min_u32_e32 v57, v57, v62
	v_max_u32_e32 v62, v61, v76
	v_min_u32_e32 v61, v61, v76
	v_max_u32_e32 v76, v63, v74
	v_min_u32_e32 v63, v63, v74
	v_max_u32_e32 v74, v77, v78
	v_min_u32_e32 v77, v77, v78
	v_max_u32_e32 v78, v75, v82
	v_min_u32_e32 v75, v75, v82
	v_max_u32_e32 v82, v79, v86
	v_min_u32_e32 v79, v79, v86
	v_max_u32_e32 v86, v83, v84
	v_min_u32_e32 v83, v83, v84
	v_max_u32_e32 v84, v87, v88
	v_min_u32_e32 v87, v87, v88
	v_max_u32_e32 v88, v85, v90
	v_min_u32_e32 v85, v85, v90
	v_max_u32_e32 v90, v89, v106
	v_min_u32_e32 v89, v89, v106
	v_max_u32_e32 v106, v91, v104
	v_min_u32_e32 v91, v91, v104
	v_max_u32_e32 v104, v107, v108
	v_min_u32_e32 v107, v107, v108
	v_max_u32_e32 v108, v105, v110
	v_min_u32_e32 v105, v105, v110
	v_max_u32_e32 v110, v109, v116
	v_min_u32_e32 v109, v109, v116
	v_max_u32_e32 v116, v111, v112
	v_min_u32_e32 v111, v111, v112
	v_max_u32_e32 v112, v117, v118
	v_min_u32_e32 v117, v117, v118
	v_max_u32_e32 v118, v113, v120
	v_min_u32_e32 v113, v113, v120
	v_max_u32_e32 v120, v119, v124
	v_min_u32_e32 v119, v119, v124
	v_max_u32_e32 v124, v121, v122
	v_min_u32_e32 v121, v121, v122
	v_max_u32_e32 v122, v125, v126
	v_min_u32_e32 v125, v125, v126
	v_max_u32_e32 v126, v123, v128
	v_min_u32_e32 v123, v123, v128
	v_max_u32_e32 v128, v127, v132
	v_min_u32_e32 v127, v127, v132
	v_max_u32_e32 v132, v129, v130
	v_min_u32_e32 v129, v129, v130
	v_max_u32_e32 v130, v133, v134
	v_min_u32_e32 v133, v133, v134
	v_max_u32_e32 v134, v131, v136
	v_min_u32_e32 v131, v131, v136
	v_max_u32_e32 v136, v135, v140
	v_min_u32_e32 v135, v135, v140
	v_max_u32_e32 v140, v137, v138
	v_min_u32_e32 v137, v137, v138
	v_max_u32_e32 v138, v141, v142
	v_min_u32_e32 v141, v141, v142
	v_max_u32_e32 v142, v139, v144
	v_min_u32_e32 v139, v139, v144
	v_max_u32_e32 v144, v143, v148
	v_min_u32_e32 v143, v143, v148
	v_max_u32_e32 v148, v145, v146
	v_min_u32_e32 v145, v145, v146
	v_max_u32_e32 v146, v149, v150
	v_min_u32_e32 v149, v149, v150
	v_max_u32_e32 v150, v147, v152
	v_min_u32_e32 v147, v147, v152
	v_max_u32_e32 v152, v151, v3
	v_min_u32_e32 v3, v151, v3
	v_max_u32_e32 v151, v73, v2
	v_min_u32_e32 v2, v73, v2
	v_max_u32_e32 v73, v153, v1
	v_min_u32_e32 v1, v153, v1
	v_max_u32_e32 v153, v0, v4
	v_min_u32_e32 v0, v0, v4
	v_max_u32_e32 v4, v6, v11
	v_min_u32_e32 v6, v6, v11
	v_max_u32_e32 v11, v5, v8
	v_min_u32_e32 v5, v5, v8
	v_max_u32_e32 v8, v10, v9
	v_min_u32_e32 v9, v10, v9
	v_max_u32_e32 v10, v7, v12
	v_min_u32_e32 v7, v7, v12
	v_max_u32_e32 v12, v14, v19
	v_min_u32_e32 v14, v14, v19
	v_max_u32_e32 v19, v13, v16
	v_min_u32_e32 v13, v13, v16
	v_max_u32_e32 v16, v18, v17
	v_min_u32_e32 v17, v18, v17
	v_max_u32_e32 v18, v15, v20
	v_min_u32_e32 v15, v15, v20
	v_max_u32_e32 v20, v22, v27
	v_min_u32_e32 v22, v22, v27
	v_max_u32_e32 v27, v21, v24
	v_min_u32_e32 v21, v21, v24
	v_max_u32_e32 v24, v26, v25
	v_min_u32_e32 v25, v26, v25
	v_max_u32_e32 v26, v23, v28
	v_min_u32_e32 v23, v23, v28
	v_max_u32_e32 v28, v30, v35
	v_min_u32_e32 v30, v30, v35
	v_max_u32_e32 v35, v29, v32
	v_min_u32_e32 v29, v29, v32
	v_max_u32_e32 v32, v34, v33
	v_min_u32_e32 v33, v34, v33
	v_max_u32_e32 v34, v31, v36
	v_min_u32_e32 v31, v31, v36
	v_max_u32_e32 v36, v38, v43
	v_min_u32_e32 v38, v38, v43
	v_max_u32_e32 v43, v37, v40
	v_min_u32_e32 v37, v37, v40
	v_max_u32_e32 v40, v42, v41
	v_min_u32_e32 v41, v42, v41
	v_max_u32_e32 v42, v39, v44
	v_min_u32_e32 v39, v39, v44
	v_max_u32_e32 v44, v46, v51
	v_min_u32_e32 v46, v46, v51
	v_max_u32_e32 v51, v45, v48
	v_min_u32_e32 v45, v45, v48
	v_max_u32_e32 v48, v50, v49
	v_min_u32_e32 v49, v50, v49
	v_max_u32_e32 v50, v47, v52
	v_min_u32_e32 v47, v47, v52
	v_max_u32_e32 v52, v54, v59
	v_min_u32_e32 v54, v54, v59
	v_max_u32_e32 v59, v53, v56
	v_min_u32_e32 v53, v53, v56
	v_max_u32_e32 v56, v58, v57
	v_min_u32_e32 v57, v58, v57
	v_max_u32_e32 v58, v55, v60
	v_min_u32_e32 v55, v55, v60
	v_max_u32_e32 v60, v62, v77
	v_min_u32_e32 v62, v62, v77
	v_max_u32_e32 v77, v61, v74
	v_min_u32_e32 v61, v61, v74
	v_max_u32_e32 v74, v76, v75
	v_min_u32_e32 v75, v76, v75
	v_max_u32_e32 v76, v63, v78
	v_min_u32_e32 v63, v63, v78
	v_max_u32_e32 v78, v82, v87
	v_min_u32_e32 v82, v82, v87
	v_max_u32_e32 v87, v79, v84
	v_min_u32_e32 v79, v79, v84
	v_max_u32_e32 v84, v86, v85
	v_min_u32_e32 v85, v86, v85
	v_max_u32_e32 v86, v83, v88
	v_min_u32_e32 v83, v83, v88
	v_max_u32_e32 v88, v90, v107
	v_min_u32_e32 v90, v90, v107
	v_max_u32_e32 v107, v89, v104
	v_min_u32_e32 v89, v89, v104
	v_max_u32_e32 v104, v106, v105
	v_min_u32_e32 v105, v106, v105
	v_max_u32_e32 v106, v91, v108
	v_min_u32_e32 v91, v91, v108
	v_max_u32_e32 v108, v110, v117
	v_min_u32_e32 v110, v110, v117
	v_max_u32_e32 v117, v109, v112
	v_min_u32_e32 v109, v109, v112
	v_max_u32_e32 v112, v116, v113
	v_min_u32_e32 v113, v116, v113
	v_max_u32_e32 v116, v111, v118
	v_min_u32_e32 v111, v111, v118
	v_max_u32_e32 v118, v120, v125
	v_min_u32_e32 v120, v120, v125
	v_max_u32_e32 v125, v119, v122
	v_min_u32_e32 v119, v119, v122
	v_max_u32_e32 v122, v124, v123
	v_min_u32_e32 v123, v124, v123
	v_max_u32_e32 v124, v121, v126
	v_min_u32_e32 v121, v121, v126
	v_max_u32_e32 v126, v128, v133
	v_min_u32_e32 v128, v128, v133
	v_max_u32_e32 v133, v127, v130
	v_min_u32_e32 v127, v127, v130
	v_max_u32_e32 v130, v132, v131
	v_min_u32_e32 v131, v132, v131
	v_max_u32_e32 v132, v129, v134
	v_min_u32_e32 v129, v129, v134
	v_max_u32_e32 v134, v136, v141
	v_min_u32_e32 v136, v136, v141
	v_max_u32_e32 v141, v135, v138
	v_min_u32_e32 v135, v135, v138
	v_max_u32_e32 v138, v140, v139
	v_min_u32_e32 v139, v140, v139
	v_max_u32_e32 v140, v137, v142
	v_min_u32_e32 v137, v137, v142
	v_max_u32_e32 v142, v144, v149
	v_min_u32_e32 v144, v144, v149
	v_max_u32_e32 v149, v143, v146
	v_min_u32_e32 v143, v143, v146
	v_max_u32_e32 v146, v148, v147
	v_min_u32_e32 v147, v148, v147
	v_max_u32_e32 v148, v145, v150
	v_min_u32_e32 v145, v145, v150
	v_max_u32_e32 v150, v152, v73
	v_min_u32_e32 v73, v152, v73
	v_max_u32_e32 v152, v151, v153
	v_min_u32_e32 v151, v151, v153
	v_max_u32_e32 v153, v3, v1
	v_min_u32_e32 v1, v3, v1
	v_max_u32_e32 v3, v2, v0
	v_min_u32_e32 v0, v2, v0
	v_max_u32_e32 v2, v6, v9
	v_min_u32_e32 v6, v6, v9
	v_max_u32_e32 v9, v5, v7
	v_min_u32_e32 v5, v5, v7
	v_max_u32_e32 v7, v4, v8
	v_min_u32_e32 v4, v4, v8
	v_max_u32_e32 v8, v11, v10
	v_min_u32_e32 v10, v11, v10
	v_max_u32_e32 v11, v12, v16
	v_min_u32_e32 v12, v12, v16
	v_max_u32_e32 v16, v19, v18
	v_min_u32_e32 v18, v19, v18
	v_max_u32_e32 v19, v14, v17
	v_min_u32_e32 v14, v14, v17
	v_max_u32_e32 v17, v13, v15
	v_min_u32_e32 v13, v13, v15
	v_max_u32_e32 v15, v22, v25
	v_min_u32_e32 v22, v22, v25
	v_max_u32_e32 v25, v21, v23
	v_min_u32_e32 v21, v21, v23
	v_max_u32_e32 v23, v20, v24
	v_min_u32_e32 v20, v20, v24
	v_max_u32_e32 v24, v27, v26
	v_min_u32_e32 v26, v27, v26
	v_max_u32_e32 v27, v28, v32
	v_min_u32_e32 v28, v28, v32
	v_max_u32_e32 v32, v35, v34
	v_min_u32_e32 v34, v35, v34
	v_max_u32_e32 v35, v30, v33
	v_min_u32_e32 v30, v30, v33
	v_max_u32_e32 v33, v29, v31
	v_min_u32_e32 v29, v29, v31
	v_max_u32_e32 v31, v38, v41
	v_min_u32_e32 v38, v38, v41
	v_max_u32_e32 v41, v37, v39
	v_min_u32_e32 v37, v37, v39
	v_max_u32_e32 v39, v36, v40
	v_min_u32_e32 v36, v36, v40
	v_max_u32_e32 v40, v43, v42
	v_min_u32_e32 v42, v43, v42
	v_max_u32_e32 v43, v44, v48
	v_min_u32_e32 v44, v44, v48
	v_max_u32_e32 v48, v51, v50
	v_min_u32_e32 v50, v51, v50
	v_max_u32_e32 v51, v46, v49
	v_min_u32_e32 v46, v46, v49
	v_max_u32_e32 v49, v45, v47
	v_min_u32_e32 v45, v45, v47
	v_max_u32_e32 v47, v54, v57
	v_min_u32_e32 v54, v54, v57
	v_max_u32_e32 v57, v53, v55
	v_min_u32_e32 v53, v53, v55
	v_max_u32_e32 v55, v52, v56
	v_min_u32_e32 v52, v52, v56
	v_max_u32_e32 v56, v59, v58
	v_min_u32_e32 v58, v59, v58
	v_max_u32_e32 v59, v60, v74
	v_min_u32_e32 v60, v60, v74
	v_max_u32_e32 v74, v77, v76
	v_min_u32_e32 v76, v77, v76
	v_max_u32_e32 v77, v62, v75
	v_min_u32_e32 v62, v62, v75
	v_max_u32_e32 v75, v61, v63
	v_min_u32_e32 v61, v61, v63
	v_max_u32_e32 v63, v82, v85
	v_min_u32_e32 v82, v82, v85
	v_max_u32_e32 v85, v79, v83
	v_min_u32_e32 v79, v79, v83
	v_max_u32_e32 v83, v78, v84
	v_min_u32_e32 v78, v78, v84
	v_max_u32_e32 v84, v87, v86
	v_min_u32_e32 v86, v87, v86
	v_max_u32_e32 v87, v88, v104
	v_min_u32_e32 v88, v88, v104
	v_max_u32_e32 v104, v107, v106
	v_min_u32_e32 v106, v107, v106
	v_max_u32_e32 v107, v90, v105
	v_min_u32_e32 v90, v90, v105
	v_max_u32_e32 v105, v89, v91
	v_min_u32_e32 v89, v89, v91
	v_max_u32_e32 v91, v110, v113
	v_min_u32_e32 v110, v110, v113
	v_max_u32_e32 v113, v109, v111
	v_min_u32_e32 v109, v109, v111
	v_max_u32_e32 v111, v108, v112
	v_min_u32_e32 v108, v108, v112
	v_max_u32_e32 v112, v117, v116
	v_min_u32_e32 v116, v117, v116
	v_max_u32_e32 v117, v118, v122
	v_min_u32_e32 v118, v118, v122
	v_max_u32_e32 v122, v125, v124
	v_min_u32_e32 v124, v125, v124
	v_max_u32_e32 v125, v120, v123
	v_min_u32_e32 v120, v120, v123
	v_max_u32_e32 v123, v119, v121
	v_min_u32_e32 v119, v119, v121
	v_max_u32_e32 v121, v128, v131
	v_min_u32_e32 v128, v128, v131
	v_max_u32_e32 v131, v127, v129
	v_min_u32_e32 v127, v127, v129
	v_max_u32_e32 v129, v126, v130
	v_min_u32_e32 v126, v126, v130
	v_max_u32_e32 v130, v133, v132
	v_min_u32_e32 v132, v133, v132
	v_max_u32_e32 v133, v134, v138
	v_min_u32_e32 v134, v134, v138
	v_max_u32_e32 v138, v141, v140
	v_min_u32_e32 v140, v141, v140
	v_max_u32_e32 v141, v136, v139
	v_min_u32_e32 v136, v136, v139
	v_max_u32_e32 v139, v135, v137
	v_min_u32_e32 v135, v135, v137
	v_max_u32_e32 v137, v144, v147
	v_min_u32_e32 v144, v144, v147
	v_max_u32_e32 v147, v143, v145
	v_min_u32_e32 v143, v143, v145
	v_max_u32_e32 v145, v142, v146
	v_min_u32_e32 v142, v142, v146
	v_max_u32_e32 v146, v149, v148
	v_min_u32_e32 v148, v149, v148
	v_max_u32_e32 v149, v150, v152
	v_min_u32_e32 v150, v150, v152
	v_max_u32_e32 v152, v73, v151
	v_min_u32_e32 v73, v73, v151
	v_max_u32_e32 v151, v153, v3
	v_min_u32_e32 v3, v153, v3
	v_max_u32_e32 v153, v1, v0
	v_min_u32_e32 v0, v1, v0
	v_max_u32_e32 v1, v6, v5
	v_min_u32_e32 v5, v6, v5
	v_max_u32_e32 v6, v2, v9
	v_min_u32_e32 v2, v2, v9
	v_max_u32_e32 v9, v4, v10
	v_min_u32_e32 v4, v4, v10
	v_max_u32_e32 v10, v7, v8
	v_min_u32_e32 v7, v7, v8
	v_max_u32_e32 v8, v11, v16
	v_min_u32_e32 v11, v11, v16
	v_max_u32_e32 v16, v12, v18
	v_min_u32_e32 v12, v12, v18
	v_max_u32_e32 v18, v19, v17
	v_min_u32_e32 v17, v19, v17
	v_max_u32_e32 v19, v14, v13
	v_min_u32_e32 v13, v14, v13
	v_max_u32_e32 v14, v22, v21
	v_min_u32_e32 v21, v22, v21
	v_max_u32_e32 v22, v15, v25
	v_min_u32_e32 v15, v15, v25
	v_max_u32_e32 v25, v20, v26
	v_min_u32_e32 v20, v20, v26
	v_max_u32_e32 v26, v23, v24
	v_min_u32_e32 v23, v23, v24
	v_max_u32_e32 v24, v27, v32
	v_min_u32_e32 v27, v27, v32
	v_max_u32_e32 v32, v28, v34
	v_min_u32_e32 v28, v28, v34
	v_max_u32_e32 v34, v35, v33
	v_min_u32_e32 v33, v35, v33
	v_max_u32_e32 v35, v30, v29
	v_min_u32_e32 v29, v30, v29
	v_max_u32_e32 v30, v38, v37
	v_min_u32_e32 v37, v38, v37
	v_max_u32_e32 v38, v31, v41
	v_min_u32_e32 v31, v31, v41
	v_max_u32_e32 v41, v36, v42
	v_min_u32_e32 v36, v36, v42
	v_max_u32_e32 v42, v39, v40
	v_min_u32_e32 v39, v39, v40
	v_max_u32_e32 v40, v43, v48
	v_min_u32_e32 v43, v43, v48
	v_max_u32_e32 v48, v44, v50
	v_min_u32_e32 v44, v44, v50
	v_max_u32_e32 v50, v51, v49
	v_min_u32_e32 v49, v51, v49
	v_max_u32_e32 v51, v46, v45
	v_min_u32_e32 v45, v46, v45
	v_max_u32_e32 v46, v54, v53
	v_min_u32_e32 v53, v54, v53
	v_max_u32_e32 v54, v47, v57
	v_min_u32_e32 v47, v47, v57
	v_max_u32_e32 v57, v52, v58
	v_min_u32_e32 v52, v52, v58
	v_max_u32_e32 v58, v55, v56
	v_min_u32_e32 v55, v55, v56
	v_max_u32_e32 v56, v59, v74
	v_min_u32_e32 v59, v59, v74
	v_max_u32_e32 v74, v60, v76
	v_min_u32_e32 v60, v60, v76
	v_max_u32_e32 v76, v77, v75
	v_min_u32_e32 v75, v77, v75
	v_max_u32_e32 v77, v62, v61
	v_min_u32_e32 v61, v62, v61
	v_max_u32_e32 v62, v82, v79
	v_min_u32_e32 v79, v82, v79
	v_max_u32_e32 v82, v63, v85
	v_min_u32_e32 v63, v63, v85
	v_max_u32_e32 v85, v78, v86
	v_min_u32_e32 v78, v78, v86
	v_max_u32_e32 v86, v83, v84
	v_min_u32_e32 v83, v83, v84
	v_max_u32_e32 v84, v87, v104
	v_min_u32_e32 v87, v87, v104
	v_max_u32_e32 v104, v88, v106
	v_min_u32_e32 v88, v88, v106
	v_max_u32_e32 v106, v107, v105
	v_min_u32_e32 v105, v107, v105
	v_max_u32_e32 v107, v90, v89
	v_min_u32_e32 v89, v90, v89
	v_max_u32_e32 v90, v110, v109
	v_min_u32_e32 v109, v110, v109
	v_max_u32_e32 v110, v91, v113
	v_min_u32_e32 v91, v91, v113
	v_max_u32_e32 v113, v108, v116
	v_min_u32_e32 v108, v108, v116
	v_max_u32_e32 v116, v111, v112
	v_min_u32_e32 v111, v111, v112
	v_max_u32_e32 v112, v117, v122
	v_min_u32_e32 v117, v117, v122
	v_max_u32_e32 v122, v118, v124
	v_min_u32_e32 v118, v118, v124
	v_max_u32_e32 v124, v125, v123
	v_min_u32_e32 v123, v125, v123
	v_max_u32_e32 v125, v120, v119
	v_min_u32_e32 v119, v120, v119
	v_max_u32_e32 v120, v128, v127
	v_min_u32_e32 v127, v128, v127
	v_max_u32_e32 v128, v121, v131
	v_min_u32_e32 v121, v121, v131
	v_max_u32_e32 v131, v126, v132
	v_min_u32_e32 v126, v126, v132
	v_max_u32_e32 v132, v129, v130
	v_min_u32_e32 v129, v129, v130
	v_max_u32_e32 v130, v133, v138
	v_min_u32_e32 v133, v133, v138
	v_max_u32_e32 v138, v134, v140
	v_min_u32_e32 v134, v134, v140
	v_max_u32_e32 v140, v141, v139
	v_min_u32_e32 v139, v141, v139
	v_max_u32_e32 v141, v136, v135
	v_min_u32_e32 v135, v136, v135
	v_max_u32_e32 v136, v144, v143
	v_min_u32_e32 v143, v144, v143
	v_max_u32_e32 v144, v137, v147
	v_min_u32_e32 v137, v137, v147
	v_max_u32_e32 v147, v142, v148
	v_min_u32_e32 v142, v142, v148
	v_max_u32_e32 v148, v145, v146
	v_min_u32_e32 v145, v145, v146
	v_max_u32_e32 v146, v149, v5
	v_min_u32_e32 v5, v149, v5
	v_max_u32_e32 v149, v150, v1
	v_min_u32_e32 v1, v150, v1
	v_max_u32_e32 v150, v152, v2
	v_min_u32_e32 v2, v152, v2
	v_max_u32_e32 v152, v73, v6
	v_min_u32_e32 v6, v73, v6
	v_max_u32_e32 v73, v151, v4
	v_min_u32_e32 v4, v151, v4
	v_max_u32_e32 v151, v3, v9
	v_min_u32_e32 v3, v3, v9
	v_max_u32_e32 v9, v153, v7
	v_min_u32_e32 v7, v153, v7
	v_max_u32_e32 v153, v0, v10
	v_min_u32_e32 v0, v0, v10
	v_max_u32_e32 v10, v8, v21
	v_min_u32_e32 v8, v8, v21
	v_max_u32_e32 v21, v11, v14
	v_min_u32_e32 v11, v11, v14
	v_max_u32_e32 v14, v16, v15
	v_min_u32_e32 v15, v16, v15
	v_max_u32_e32 v16, v12, v22
	v_min_u32_e32 v12, v12, v22
	v_max_u32_e32 v22, v18, v20
	v_min_u32_e32 v18, v18, v20
	v_max_u32_e32 v20, v17, v25
	v_min_u32_e32 v17, v17, v25
	v_max_u32_e32 v25, v19, v23
	v_min_u32_e32 v19, v19, v23
	v_max_u32_e32 v23, v13, v26
	v_min_u32_e32 v13, v13, v26
	v_max_u32_e32 v26, v24, v37
	v_min_u32_e32 v24, v24, v37
	v_max_u32_e32 v37, v27, v30
	v_min_u32_e32 v27, v27, v30
	v_max_u32_e32 v30, v32, v31
	v_min_u32_e32 v31, v32, v31
	v_max_u32_e32 v32, v28, v38
	v_min_u32_e32 v28, v28, v38
	v_max_u32_e32 v38, v34, v36
	v_min_u32_e32 v34, v34, v36
	v_max_u32_e32 v36, v33, v41
	v_min_u32_e32 v33, v33, v41
	v_max_u32_e32 v41, v35, v39
	v_min_u32_e32 v35, v35, v39
	v_max_u32_e32 v39, v29, v42
	v_min_u32_e32 v29, v29, v42
	v_max_u32_e32 v42, v40, v53
	v_min_u32_e32 v40, v40, v53
	v_max_u32_e32 v53, v43, v46
	v_min_u32_e32 v43, v43, v46
	v_max_u32_e32 v46, v48, v47
	v_min_u32_e32 v47, v48, v47
	v_max_u32_e32 v48, v44, v54
	v_min_u32_e32 v44, v44, v54
	v_max_u32_e32 v54, v50, v52
	v_min_u32_e32 v50, v50, v52
	v_max_u32_e32 v52, v49, v57
	v_min_u32_e32 v49, v49, v57
	v_max_u32_e32 v57, v51, v55
	v_min_u32_e32 v51, v51, v55
	v_max_u32_e32 v55, v45, v58
	v_min_u32_e32 v45, v45, v58
	v_max_u32_e32 v58, v56, v79
	v_min_u32_e32 v56, v56, v79
	v_max_u32_e32 v79, v59, v62
	v_min_u32_e32 v59, v59, v62
	v_max_u32_e32 v62, v74, v63
	v_min_u32_e32 v63, v74, v63
	v_max_u32_e32 v74, v60, v82
	v_min_u32_e32 v60, v60, v82
	v_max_u32_e32 v82, v76, v78
	v_min_u32_e32 v76, v76, v78
	v_max_u32_e32 v78, v75, v85
	v_min_u32_e32 v75, v75, v85
	v_max_u32_e32 v85, v77, v83
	v_min_u32_e32 v77, v77, v83
	v_max_u32_e32 v83, v61, v86
	v_min_u32_e32 v61, v61, v86
	v_max_u32_e32 v86, v84, v109
	v_min_u32_e32 v84, v84, v109
	v_max_u32_e32 v109, v87, v90
	v_min_u32_e32 v87, v87, v90
	v_max_u32_e32 v90, v104, v91
	v_min_u32_e32 v91, v104, v91
	v_max_u32_e32 v104, v88, v110
	v_min_u32_e32 v88, v88, v110
	v_max_u32_e32 v110, v106, v108
	v_min_u32_e32 v106, v106, v108
	v_max_u32_e32 v108, v105, v113
	v_min_u32_e32 v105, v105, v113
	v_max_u32_e32 v113, v107, v111
	v_min_u32_e32 v107, v107, v111
	v_max_u32_e32 v111, v89, v116
	v_min_u32_e32 v89, v89, v116
	v_max_u32_e32 v116, v112, v127
	v_min_u32_e32 v112, v112, v127
	v_max_u32_e32 v127, v117, v120
	v_min_u32_e32 v117, v117, v120
	v_max_u32_e32 v120, v122, v121
	v_min_u32_e32 v121, v122, v121
	v_max_u32_e32 v122, v118, v128
	v_min_u32_e32 v118, v118, v128
	v_max_u32_e32 v128, v124, v126
	v_min_u32_e32 v124, v124, v126
	v_max_u32_e32 v126, v123, v131
	v_min_u32_e32 v123, v123, v131
	v_max_u32_e32 v131, v125, v129
	v_min_u32_e32 v125, v125, v129
	v_max_u32_e32 v129, v119, v132
	v_min_u32_e32 v119, v119, v132
	v_max_u32_e32 v132, v130, v143
	v_min_u32_e32 v130, v130, v143
	v_max_u32_e32 v143, v133, v136
	v_min_u32_e32 v133, v133, v136
	v_max_u32_e32 v136, v138, v137
	v_min_u32_e32 v137, v138, v137
	v_max_u32_e32 v138, v134, v144
	v_min_u32_e32 v134, v134, v144
	v_max_u32_e32 v144, v140, v142
	v_min_u32_e32 v140, v140, v142
	v_max_u32_e32 v142, v139, v147
	v_min_u32_e32 v139, v139, v147
	v_max_u32_e32 v147, v141, v145
	v_min_u32_e32 v141, v141, v145
	v_max_u32_e32 v145, v135, v148
	v_min_u32_e32 v135, v135, v148
	v_max_u32_e32 v148, v146, v73
	v_min_u32_e32 v73, v146, v73
	v_max_u32_e32 v146, v149, v151
	v_min_u32_e32 v149, v149, v151
	v_max_u32_e32 v151, v150, v9
	v_min_u32_e32 v9, v150, v9
	v_max_u32_e32 v150, v152, v153
	v_min_u32_e32 v152, v152, v153
	v_max_u32_e32 v153, v5, v4
	v_min_u32_e32 v4, v5, v4
	v_max_u32_e32 v5, v1, v3
	v_min_u32_e32 v1, v1, v3
	v_max_u32_e32 v3, v2, v7
	v_min_u32_e32 v2, v2, v7
	v_max_u32_e32 v7, v6, v0
	v_min_u32_e32 v0, v6, v0
	v_max_u32_e32 v6, v8, v18
	v_min_u32_e32 v8, v8, v18
	v_max_u32_e32 v18, v11, v17
	v_min_u32_e32 v11, v11, v17
	v_max_u32_e32 v17, v15, v19
	v_min_u32_e32 v15, v15, v19
	v_max_u32_e32 v19, v12, v13
	v_min_u32_e32 v12, v12, v13
	v_max_u32_e32 v13, v10, v22
	v_min_u32_e32 v10, v10, v22
	v_max_u32_e32 v22, v21, v20
	v_min_u32_e32 v20, v21, v20
	v_max_u32_e32 v21, v14, v25
	v_min_u32_e32 v14, v14, v25
	v_max_u32_e32 v25, v16, v23
	v_min_u32_e32 v16, v16, v23
	v_max_u32_e32 v23, v26, v38
	v_min_u32_e32 v26, v26, v38
	v_max_u32_e32 v38, v37, v36
	v_min_u32_e32 v36, v37, v36
	v_max_u32_e32 v37, v30, v41
	v_min_u32_e32 v30, v30, v41
	v_max_u32_e32 v41, v32, v39
	v_min_u32_e32 v32, v32, v39
	v_max_u32_e32 v39, v24, v34
	v_min_u32_e32 v24, v24, v34
	v_max_u32_e32 v34, v27, v33
	v_min_u32_e32 v27, v27, v33
	v_max_u32_e32 v33, v31, v35
	v_min_u32_e32 v31, v31, v35
	v_max_u32_e32 v35, v28, v29
	v_min_u32_e32 v28, v28, v29
	v_max_u32_e32 v29, v40, v50
	v_min_u32_e32 v40, v40, v50
	v_max_u32_e32 v50, v43, v49
	v_min_u32_e32 v43, v43, v49
	v_max_u32_e32 v49, v47, v51
	v_min_u32_e32 v47, v47, v51
	v_max_u32_e32 v51, v44, v45
	v_min_u32_e32 v44, v44, v45
	v_max_u32_e32 v45, v42, v54
	v_min_u32_e32 v42, v42, v54
	v_max_u32_e32 v54, v53, v52
	v_min_u32_e32 v52, v53, v52
	v_max_u32_e32 v53, v46, v57
	v_min_u32_e32 v46, v46, v57
	v_max_u32_e32 v57, v48, v55
	v_min_u32_e32 v48, v48, v55
	v_max_u32_e32 v55, v58, v82
	v_min_u32_e32 v58, v58, v82
	v_max_u32_e32 v82, v79, v78
	v_min_u32_e32 v78, v79, v78
	v_max_u32_e32 v79, v62, v85
	v_min_u32_e32 v62, v62, v85
	v_max_u32_e32 v85, v74, v83
	v_min_u32_e32 v74, v74, v83
	v_max_u32_e32 v83, v56, v76
	v_min_u32_e32 v56, v56, v76
	v_max_u32_e32 v76, v59, v75
	v_min_u32_e32 v59, v59, v75
	v_max_u32_e32 v75, v63, v77
	v_min_u32_e32 v63, v63, v77
	v_max_u32_e32 v77, v60, v61
	v_min_u32_e32 v60, v60, v61
	v_max_u32_e32 v61, v84, v106
	v_min_u32_e32 v84, v84, v106
	v_max_u32_e32 v106, v87, v105
	v_min_u32_e32 v87, v87, v105
	v_max_u32_e32 v105, v91, v107
	v_min_u32_e32 v91, v91, v107
	v_max_u32_e32 v107, v88, v89
	v_min_u32_e32 v88, v88, v89
	v_max_u32_e32 v89, v86, v110
	v_min_u32_e32 v86, v86, v110
	v_max_u32_e32 v110, v109, v108
	v_min_u32_e32 v108, v109, v108
	v_max_u32_e32 v109, v90, v113
	v_min_u32_e32 v90, v90, v113
	v_max_u32_e32 v113, v104, v111
	v_min_u32_e32 v104, v104, v111
	v_max_u32_e32 v111, v116, v128
	v_min_u32_e32 v116, v116, v128
	v_max_u32_e32 v128, v127, v126
	v_min_u32_e32 v126, v127, v126
	v_max_u32_e32 v127, v120, v131
	v_min_u32_e32 v120, v120, v131
	v_max_u32_e32 v131, v122, v129
	v_min_u32_e32 v122, v122, v129
	v_max_u32_e32 v129, v112, v124
	v_min_u32_e32 v112, v112, v124
	v_max_u32_e32 v124, v117, v123
	v_min_u32_e32 v117, v117, v123
	v_max_u32_e32 v123, v121, v125
	v_min_u32_e32 v121, v121, v125
	v_max_u32_e32 v125, v118, v119
	v_min_u32_e32 v118, v118, v119
	v_max_u32_e32 v119, v130, v140
	v_min_u32_e32 v130, v130, v140
	v_max_u32_e32 v140, v133, v139
	v_min_u32_e32 v133, v133, v139
	v_max_u32_e32 v139, v137, v141
	v_min_u32_e32 v137, v137, v141
	v_max_u32_e32 v141, v134, v135
	v_min_u32_e32 v134, v134, v135
	v_max_u32_e32 v135, v132, v144
	v_min_u32_e32 v132, v132, v144
	v_max_u32_e32 v144, v143, v142
	v_min_u32_e32 v142, v143, v142
	v_max_u32_e32 v143, v136, v147
	v_min_u32_e32 v136, v136, v147
	v_max_u32_e32 v147, v138, v145
	v_min_u32_e32 v138, v138, v145
	v_max_u32_e32 v145, v148, v151
	v_min_u32_e32 v148, v148, v151
	v_max_u32_e32 v151, v146, v150
	v_min_u32_e32 v146, v146, v150
	v_max_u32_e32 v150, v73, v9
	v_min_u32_e32 v9, v73, v9
	v_max_u32_e32 v73, v149, v152
	v_min_u32_e32 v149, v149, v152
	v_max_u32_e32 v152, v153, v3
	v_min_u32_e32 v3, v153, v3
	v_max_u32_e32 v153, v5, v7
	v_min_u32_e32 v5, v5, v7
	v_max_u32_e32 v7, v4, v2
	v_min_u32_e32 v2, v4, v2
	v_max_u32_e32 v4, v1, v0
	v_min_u32_e32 v0, v1, v0
	v_max_u32_e32 v1, v8, v15
	v_min_u32_e32 v8, v8, v15
	v_max_u32_e32 v15, v11, v12
	v_min_u32_e32 v11, v11, v12
	v_max_u32_e32 v12, v6, v17
	v_min_u32_e32 v6, v6, v17
	v_max_u32_e32 v17, v18, v19
	v_min_u32_e32 v18, v18, v19
	v_max_u32_e32 v19, v10, v14
	v_min_u32_e32 v10, v10, v14
	v_max_u32_e32 v14, v20, v16
	v_min_u32_e32 v16, v20, v16
	v_max_u32_e32 v20, v13, v21
	v_min_u32_e32 v13, v13, v21
	v_max_u32_e32 v21, v22, v25
	v_min_u32_e32 v22, v22, v25
	v_max_u32_e32 v25, v23, v37
	v_min_u32_e32 v23, v23, v37
	v_max_u32_e32 v37, v38, v41
	v_min_u32_e32 v38, v38, v41
	v_max_u32_e32 v41, v26, v30
	v_min_u32_e32 v26, v26, v30
	v_max_u32_e32 v30, v36, v32
	v_min_u32_e32 v32, v36, v32
	v_max_u32_e32 v36, v39, v33
	v_min_u32_e32 v33, v39, v33
	v_max_u32_e32 v39, v34, v35
	v_min_u32_e32 v34, v34, v35
	v_max_u32_e32 v35, v24, v31
	v_min_u32_e32 v24, v24, v31
	v_max_u32_e32 v31, v27, v28
	v_min_u32_e32 v27, v27, v28
	v_max_u32_e32 v28, v40, v47
	v_min_u32_e32 v40, v40, v47
	v_max_u32_e32 v47, v43, v44
	v_min_u32_e32 v43, v43, v44
	v_max_u32_e32 v44, v29, v49
	v_min_u32_e32 v29, v29, v49
	v_max_u32_e32 v49, v50, v51
	v_min_u32_e32 v50, v50, v51
	v_max_u32_e32 v51, v42, v46
	v_min_u32_e32 v42, v42, v46
	v_max_u32_e32 v46, v52, v48
	v_min_u32_e32 v48, v52, v48
	v_max_u32_e32 v52, v45, v53
	v_min_u32_e32 v45, v45, v53
	v_max_u32_e32 v53, v54, v57
	v_min_u32_e32 v54, v54, v57
	v_max_u32_e32 v57, v55, v79
	v_min_u32_e32 v55, v55, v79
	v_max_u32_e32 v79, v82, v85
	v_min_u32_e32 v82, v82, v85
	v_max_u32_e32 v85, v58, v62
	v_min_u32_e32 v58, v58, v62
	v_max_u32_e32 v62, v78, v74
	v_min_u32_e32 v74, v78, v74
	v_max_u32_e32 v78, v83, v75
	v_min_u32_e32 v75, v83, v75
	v_max_u32_e32 v83, v76, v77
	v_min_u32_e32 v76, v76, v77
	v_max_u32_e32 v77, v56, v63
	v_min_u32_e32 v56, v56, v63
	v_max_u32_e32 v63, v59, v60
	v_min_u32_e32 v59, v59, v60
	v_max_u32_e32 v60, v84, v91
	v_min_u32_e32 v84, v84, v91
	v_max_u32_e32 v91, v87, v88
	v_min_u32_e32 v87, v87, v88
	v_max_u32_e32 v88, v61, v105
	v_min_u32_e32 v61, v61, v105
	v_max_u32_e32 v105, v106, v107
	v_min_u32_e32 v106, v106, v107
	v_max_u32_e32 v107, v86, v90
	v_min_u32_e32 v86, v86, v90
	v_max_u32_e32 v90, v108, v104
	v_min_u32_e32 v104, v108, v104
	v_max_u32_e32 v108, v89, v109
	v_min_u32_e32 v89, v89, v109
	v_max_u32_e32 v109, v110, v113
	v_min_u32_e32 v110, v110, v113
	v_max_u32_e32 v113, v111, v127
	v_min_u32_e32 v111, v111, v127
	v_max_u32_e32 v127, v128, v131
	v_min_u32_e32 v128, v128, v131
	v_max_u32_e32 v131, v116, v120
	v_min_u32_e32 v116, v116, v120
	v_max_u32_e32 v120, v126, v122
	v_min_u32_e32 v122, v126, v122
	v_max_u32_e32 v126, v129, v123
	v_min_u32_e32 v123, v129, v123
	v_max_u32_e32 v129, v124, v125
	v_min_u32_e32 v124, v124, v125
	v_max_u32_e32 v125, v112, v121
	v_min_u32_e32 v112, v112, v121
	v_max_u32_e32 v121, v117, v118
	v_min_u32_e32 v117, v117, v118
	v_max_u32_e32 v118, v130, v137
	v_min_u32_e32 v130, v130, v137
	v_max_u32_e32 v137, v133, v134
	v_min_u32_e32 v133, v133, v134
	v_max_u32_e32 v134, v119, v139
	v_min_u32_e32 v119, v119, v139
	v_max_u32_e32 v139, v140, v141
	v_min_u32_e32 v140, v140, v141
	v_max_u32_e32 v141, v132, v136
	v_min_u32_e32 v132, v132, v136
	v_max_u32_e32 v136, v142, v138
	v_min_u32_e32 v138, v142, v138
	v_max_u32_e32 v142, v135, v143
	v_min_u32_e32 v135, v135, v143
	v_max_u32_e32 v143, v144, v147
	v_min_u32_e32 v144, v144, v147
	v_min_u32_e32 v147, v145, v151
	v_min_u32_e32 v154, v148, v146
	v_min_u32_e32 v155, v150, v73
	v_min_u32_e32 v156, v9, v149
	v_min_u32_e32 v157, v152, v153
	v_min_u32_e32 v158, v3, v5
	v_min_u32_e32 v159, v7, v4
	v_min_u32_e32 v160, v2, v0
	v_min_u32_e32 v161, v8, v11
	v_min_u32_e32 v162, v1, v15
	v_min_u32_e32 v163, v6, v18
	v_min_u32_e32 v164, v12, v17
	v_min_u32_e32 v165, v10, v16
	v_min_u32_e32 v166, v19, v14
	v_min_u32_e32 v167, v13, v22
	v_min_u32_e32 v168, v20, v21
	v_min_u32_e32 v169, v25, v37
	v_min_u32_e32 v170, v23, v38
	v_min_u32_e32 v171, v41, v30
	v_min_u32_e32 v172, v26, v32
	v_min_u32_e32 v173, v36, v39
	v_min_u32_e32 v174, v33, v34
	v_min_u32_e32 v175, v35, v31
	v_min_u32_e32 v176, v24, v27
	v_min_u32_e32 v177, v40, v43
	v_min_u32_e32 v178, v28, v47
	v_min_u32_e32 v179, v29, v50
	v_min_u32_e32 v180, v44, v49
	v_min_u32_e32 v181, v42, v48
	v_min_u32_e32 v182, v51, v46
	v_min_u32_e32 v183, v45, v54
	v_min_u32_e32 v184, v52, v53
	v_min_u32_e32 v185, v57, v79
	v_min_u32_e32 v186, v55, v82
	v_min_u32_e32 v187, v85, v62
	v_min_u32_e32 v188, v58, v74
	v_min_u32_e32 v189, v78, v83
	v_min_u32_e32 v190, v75, v76
	v_min_u32_e32 v191, v77, v63
	v_min_u32_e32 v192, v56, v59
	v_min_u32_e32 v193, v84, v87
	v_min_u32_e32 v194, v60, v91
	v_min_u32_e32 v195, v61, v106
	v_min_u32_e32 v196, v88, v105
	v_min_u32_e32 v197, v86, v104
	v_min_u32_e32 v198, v107, v90
	v_min_u32_e32 v199, v89, v110
	v_min_u32_e32 v200, v108, v109
	v_min_u32_e32 v201, v113, v127
	v_min_u32_e32 v202, v111, v128
	v_min_u32_e32 v203, v131, v120
	v_min_u32_e32 v204, v116, v122
	v_min_u32_e32 v205, v126, v129
	v_min_u32_e32 v206, v123, v124
	v_min_u32_e32 v207, v125, v121
	v_min_u32_e32 v208, v112, v117
	v_min_u32_e32 v209, v130, v133
	v_min_u32_e32 v210, v118, v137
	v_min_u32_e32 v211, v119, v140
	v_min_u32_e32 v212, v134, v139
	v_min_u32_e32 v213, v132, v138
	v_min_u32_e32 v214, v141, v136
	v_min_u32_e32 v215, v135, v144
	v_min_u32_e32 v216, v142, v143
	v_max3_u32 v145, v145, v151, v161
	v_max3_u32 v8, v147, v8, v11
	v_max3_u32 v11, v148, v146, v162
	v_max3_u32 v1, v154, v1, v15
	v_max3_u32 v15, v150, v73, v163
	v_max3_u32 v6, v155, v6, v18
	v_max3_u32 v9, v9, v149, v164
	v_max3_u32 v12, v156, v12, v17
	v_max3_u32 v17, v152, v153, v165
	v_max3_u32 v10, v157, v10, v16
	v_max3_u32 v3, v3, v5, v166
	v_max3_u32 v5, v158, v19, v14
	v_max3_u32 v4, v7, v4, v167
	v_max3_u32 v7, v159, v13, v22
	v_max3_u32 v0, v2, v0, v168
	v_max3_u32 v2, v160, v20, v21
	v_max3_u32 v13, v25, v37, v177
	v_max3_u32 v14, v169, v40, v43
	v_max3_u32 v16, v23, v38, v178
	v_max3_u32 v18, v170, v28, v47
	v_max3_u32 v19, v41, v30, v179
	v_max3_u32 v20, v171, v29, v50
	v_max3_u32 v21, v26, v32, v180
	v_max3_u32 v22, v172, v44, v49
	v_max3_u32 v23, v36, v39, v181
	v_max3_u32 v25, v173, v42, v48
	v_max3_u32 v26, v33, v34, v182
	v_max3_u32 v28, v174, v51, v46
	v_max3_u32 v29, v35, v31, v183
	v_max3_u32 v30, v175, v45, v54
	v_max3_u32 v24, v24, v27, v184
	v_max3_u32 v27, v176, v52, v53
	v_max3_u32 v31, v57, v79, v193
	v_max3_u32 v32, v185, v84, v87
	v_max3_u32 v33, v55, v82, v194
	v_max3_u32 v34, v186, v60, v91
	v_max3_u32 v35, v85, v62, v195
	v_max3_u32 v36, v187, v61, v106
	v_max3_u32 v37, v58, v74, v196
	v_max3_u32 v38, v188, v88, v105
	v_max3_u32 v39, v78, v83, v197
	v_max3_u32 v40, v189, v86, v104
	v_max3_u32 v41, v75, v76, v198
	v_max3_u32 v42, v190, v107, v90
	v_max3_u32 v43, v77, v63, v199
	v_max3_u32 v44, v191, v89, v110
	v_max3_u32 v45, v56, v59, v200
	v_max3_u32 v46, v192, v108, v109
	v_max3_u32 v47, v113, v127, v209
	v_max3_u32 v48, v201, v130, v133
	v_max3_u32 v49, v111, v128, v210
	v_max3_u32 v50, v202, v118, v137
	v_max3_u32 v51, v131, v120, v211
	v_max3_u32 v52, v203, v119, v140
	v_max3_u32 v53, v116, v122, v212
	v_max3_u32 v54, v204, v134, v139
	v_max3_u32 v55, v126, v129, v213
	v_max3_u32 v56, v205, v132, v138
	v_max3_u32 v57, v123, v124, v214
	v_max3_u32 v58, v206, v141, v136
	v_max3_u32 v59, v125, v121, v215
	v_max3_u32 v60, v207, v135, v144
	v_max3_u32 v61, v112, v117, v216
	v_max3_u32 v62, v208, v142, v143
	v_max_u32_e32 v63, v145, v17
	v_min_u32_e32 v17, v145, v17
	v_max_u32_e32 v73, v8, v10
	v_min_u32_e32 v8, v8, v10
	v_max_u32_e32 v10, v11, v3
	v_min_u32_e32 v3, v11, v3
	v_max_u32_e32 v11, v1, v5
	v_min_u32_e32 v1, v1, v5
	v_max_u32_e32 v5, v15, v4
	v_min_u32_e32 v4, v15, v4
	v_max_u32_e32 v15, v6, v7
	v_min_u32_e32 v6, v6, v7
	v_max_u32_e32 v7, v9, v0
	v_min_u32_e32 v0, v9, v0
	v_max_u32_e32 v9, v12, v2
	v_min_u32_e32 v2, v12, v2
	v_max_u32_e32 v12, v13, v23
	v_min_u32_e32 v13, v13, v23
	v_max_u32_e32 v23, v14, v25
	v_min_u32_e32 v14, v14, v25
	v_max_u32_e32 v25, v16, v26
	v_min_u32_e32 v16, v16, v26
	v_max_u32_e32 v26, v18, v28
	v_min_u32_e32 v18, v18, v28
	v_max_u32_e32 v28, v19, v29
	v_min_u32_e32 v19, v19, v29
	v_max_u32_e32 v29, v20, v30
	v_min_u32_e32 v20, v20, v30
	v_max_u32_e32 v30, v21, v24
	v_min_u32_e32 v21, v21, v24
	v_max_u32_e32 v24, v22, v27
	v_min_u32_e32 v22, v22, v27
	v_max_u32_e32 v27, v31, v39
	v_min_u32_e32 v31, v31, v39
	v_max_u32_e32 v39, v32, v40
	v_min_u32_e32 v32, v32, v40
	v_max_u32_e32 v40, v33, v41
	v_min_u32_e32 v33, v33, v41
	v_max_u32_e32 v41, v34, v42
	v_min_u32_e32 v34, v34, v42
	v_max_u32_e32 v42, v35, v43
	v_min_u32_e32 v35, v35, v43
	v_max_u32_e32 v43, v36, v44
	v_min_u32_e32 v36, v36, v44
	v_max_u32_e32 v44, v37, v45
	v_min_u32_e32 v37, v37, v45
	v_max_u32_e32 v45, v38, v46
	v_min_u32_e32 v38, v38, v46
	v_max_u32_e32 v46, v47, v55
	v_min_u32_e32 v47, v47, v55
	v_max_u32_e32 v55, v48, v56
	v_min_u32_e32 v48, v48, v56
	v_max_u32_e32 v56, v49, v57
	v_min_u32_e32 v49, v49, v57
	v_max_u32_e32 v57, v50, v58
	v_min_u32_e32 v50, v50, v58
	v_max_u32_e32 v58, v51, v59
	v_min_u32_e32 v51, v51, v59
	v_max_u32_e32 v59, v52, v60
	v_min_u32_e32 v52, v52, v60
	v_max_u32_e32 v60, v53, v61
	v_min_u32_e32 v53, v53, v61
	v_max_u32_e32 v61, v54, v62
	v_min_u32_e32 v54, v54, v62
	v_max_u32_e32 v62, v63, v5
	v_min_u32_e32 v5, v63, v5
	v_max_u32_e32 v63, v73, v15
	v_min_u32_e32 v15, v73, v15
	v_max_u32_e32 v73, v10, v7
	v_min_u32_e32 v7, v10, v7
	v_max_u32_e32 v10, v11, v9
	v_min_u32_e32 v9, v11, v9
	v_max_u32_e32 v11, v17, v4
	v_min_u32_e32 v4, v17, v4
	v_max_u32_e32 v17, v8, v6
	v_min_u32_e32 v6, v8, v6
	v_max_u32_e32 v8, v3, v0
	v_min_u32_e32 v0, v3, v0
	v_max_u32_e32 v3, v1, v2
	v_min_u32_e32 v1, v1, v2
	v_max_u32_e32 v2, v13, v19
	v_min_u32_e32 v13, v13, v19
	v_max_u32_e32 v19, v14, v20
	v_min_u32_e32 v14, v14, v20
	v_max_u32_e32 v20, v16, v21
	v_min_u32_e32 v16, v16, v21
	v_max_u32_e32 v21, v18, v22
	v_min_u32_e32 v18, v18, v22
	v_max_u32_e32 v22, v12, v28
	v_min_u32_e32 v12, v12, v28
	v_max_u32_e32 v28, v23, v29
	v_min_u32_e32 v23, v23, v29
	v_max_u32_e32 v29, v25, v30
	v_min_u32_e32 v25, v25, v30
	v_max_u32_e32 v30, v26, v24
	v_min_u32_e32 v24, v26, v24
	v_max_u32_e32 v26, v27, v42
	v_min_u32_e32 v27, v27, v42
	v_max_u32_e32 v42, v39, v43
	v_min_u32_e32 v39, v39, v43
	v_max_u32_e32 v43, v40, v44
	v_min_u32_e32 v40, v40, v44
	v_max_u32_e32 v44, v41, v45
	v_min_u32_e32 v41, v41, v45
	v_max_u32_e32 v45, v31, v35
	v_min_u32_e32 v31, v31, v35
	v_max_u32_e32 v35, v32, v36
	v_min_u32_e32 v32, v32, v36
	v_max_u32_e32 v36, v33, v37
	v_min_u32_e32 v33, v33, v37
	v_max_u32_e32 v37, v34, v38
	v_min_u32_e32 v34, v34, v38
	v_max_u32_e32 v38, v47, v51
	v_min_u32_e32 v47, v47, v51
	v_max_u32_e32 v51, v48, v52
	v_min_u32_e32 v48, v48, v52
	v_max_u32_e32 v52, v49, v53
	v_min_u32_e32 v49, v49, v53
	v_max_u32_e32 v53, v50, v54
	v_min_u32_e32 v50, v50, v54
	v_max_u32_e32 v54, v46, v58
	v_min_u32_e32 v46, v46, v58
	v_max_u32_e32 v58, v55, v59
	v_min_u32_e32 v55, v55, v59
	v_max_u32_e32 v59, v56, v60
	v_min_u32_e32 v56, v56, v60
	v_max_u32_e32 v60, v57, v61
	v_min_u32_e32 v57, v57, v61
	v_max_u32_e32 v61, v62, v73
	v_min_u32_e32 v62, v62, v73
	v_max_u32_e32 v73, v63, v10
	v_min_u32_e32 v10, v63, v10
	v_max_u32_e32 v63, v5, v7
	v_min_u32_e32 v5, v5, v7
	v_max_u32_e32 v7, v15, v9
	v_min_u32_e32 v9, v15, v9
	v_max_u32_e32 v15, v11, v8
	v_min_u32_e32 v8, v11, v8
	v_max_u32_e32 v11, v17, v3
	v_min_u32_e32 v3, v17, v3
	v_max_u32_e32 v17, v4, v0
	v_min_u32_e32 v0, v4, v0
	v_max_u32_e32 v4, v6, v1
	v_min_u32_e32 v1, v6, v1
	v_max_u32_e32 v6, v13, v16
	v_min_u32_e32 v13, v13, v16
	v_max_u32_e32 v16, v14, v18
	v_min_u32_e32 v14, v14, v18
	v_max_u32_e32 v18, v2, v20
	v_min_u32_e32 v2, v2, v20
	v_max_u32_e32 v20, v19, v21
	v_min_u32_e32 v19, v19, v21
	v_max_u32_e32 v21, v12, v25
	v_min_u32_e32 v12, v12, v25
	v_max_u32_e32 v25, v23, v24
	v_min_u32_e32 v23, v23, v24
	v_max_u32_e32 v24, v22, v29
	v_min_u32_e32 v22, v22, v29
	v_max_u32_e32 v29, v28, v30
	v_min_u32_e32 v28, v28, v30
	v_max_u32_e32 v30, v26, v43
	v_min_u32_e32 v26, v26, v43
	v_max_u32_e32 v43, v42, v44
	v_min_u32_e32 v42, v42, v44
	v_max_u32_e32 v44, v27, v40
	v_min_u32_e32 v27, v27, v40
	v_max_u32_e32 v40, v39, v41
	v_min_u32_e32 v39, v39, v41
	v_max_u32_e32 v41, v45, v36
	v_min_u32_e32 v36, v45, v36
	v_max_u32_e32 v45, v35, v37
	v_min_u32_e32 v35, v35, v37
	v_max_u32_e32 v37, v31, v33
	v_min_u32_e32 v31, v31, v33
	v_max_u32_e32 v33, v32, v34
	v_min_u32_e32 v32, v32, v34
	v_max_u32_e32 v34, v47, v49
	v_min_u32_e32 v47, v47, v49
	v_max_u32_e32 v49, v48, v50
	v_min_u32_e32 v48, v48, v50
	v_max_u32_e32 v50, v38, v52
	v_min_u32_e32 v38, v38, v52
	v_max_u32_e32 v52, v51, v53
	v_min_u32_e32 v51, v51, v53
	v_max_u32_e32 v53, v46, v56
	v_min_u32_e32 v46, v46, v56
	v_max_u32_e32 v56, v55, v57
	v_min_u32_e32 v55, v55, v57
	v_max_u32_e32 v57, v54, v59
	v_min_u32_e32 v54, v54, v59
	v_max_u32_e32 v59, v58, v60
	v_min_u32_e32 v58, v58, v60
	v_min_u32_e32 v60, v61, v73
	v_min_u32_e32 v74, v62, v10
	v_min_u32_e32 v75, v63, v7
	v_min_u32_e32 v76, v5, v9
	v_min_u32_e32 v77, v15, v11
	v_min_u32_e32 v78, v8, v3
	v_min_u32_e32 v79, v17, v4
	v_min_u32_e32 v82, v0, v1
	v_min_u32_e32 v83, v13, v14
	v_min_u32_e32 v84, v6, v16
	v_min_u32_e32 v85, v2, v19
	v_min_u32_e32 v86, v18, v20
	v_min_u32_e32 v87, v12, v23
	v_min_u32_e32 v88, v21, v25
	v_min_u32_e32 v89, v22, v28
	v_min_u32_e32 v90, v24, v29
	v_min_u32_e32 v91, v30, v43
	v_min_u32_e32 v104, v26, v42
	v_min_u32_e32 v105, v44, v40
	v_min_u32_e32 v106, v27, v39
	v_min_u32_e32 v107, v41, v45
	v_min_u32_e32 v108, v36, v35
	v_min_u32_e32 v109, v37, v33
	v_min_u32_e32 v110, v31, v32
	v_min_u32_e32 v111, v47, v48
	v_min_u32_e32 v112, v34, v49
	v_min_u32_e32 v113, v38, v51
	v_min_u32_e32 v116, v50, v52
	v_min_u32_e32 v117, v46, v55
	v_min_u32_e32 v118, v53, v56
	v_min_u32_e32 v119, v54, v58
	v_min_u32_e32 v120, v57, v59
	v_max3_u32 v61, v61, v73, v83
	v_max3_u32 v13, v60, v13, v14
	v_max3_u32 v10, v62, v10, v84
	v_max3_u32 v6, v74, v6, v16
	v_max3_u32 v7, v63, v7, v85
	v_max3_u32 v2, v75, v2, v19
	v_max3_u32 v5, v5, v9, v86
	v_max3_u32 v9, v76, v18, v20
	v_max3_u32 v11, v15, v11, v87
	v_max3_u32 v12, v77, v12, v23
	v_max3_u32 v3, v8, v3, v88
	v_max3_u32 v8, v78, v21, v25
	v_max3_u32 v4, v17, v4, v89
	v_max3_u32 v14, v79, v22, v28
	v_max3_u32 v0, v0, v1, v90
	v_max3_u32 v1, v82, v24, v29
	v_max3_u32 v15, v30, v43, v111
	v_max3_u32 v16, v91, v47, v48
	v_max3_u32 v17, v26, v42, v112
	v_max3_u32 v18, v104, v34, v49
	v_max3_u32 v19, v44, v40, v113
	v_max3_u32 v20, v105, v38, v51
	v_max3_u32 v21, v27, v39, v116
	v_max3_u32 v22, v106, v50, v52
	v_max3_u32 v23, v41, v45, v117
	v_max3_u32 v24, v107, v46, v55
	v_max3_u32 v25, v36, v35, v118
	v_max3_u32 v26, v108, v53, v56
	v_max3_u32 v27, v37, v33, v119
	v_max3_u32 v28, v109, v54, v58
	v_max3_u32 v29, v31, v32, v120
	v_max3_u32 v30, v110, v57, v59
	v_max_u32_e32 v31, v61, v11
	v_min_u32_e32 v11, v61, v11
	v_max_u32_e32 v32, v13, v12
	v_min_u32_e32 v12, v13, v12
	v_max_u32_e32 v13, v10, v3
	v_min_u32_e32 v3, v10, v3
	v_max_u32_e32 v10, v6, v8
	v_min_u32_e32 v6, v6, v8
	v_max_u32_e32 v8, v7, v4
	v_min_u32_e32 v4, v7, v4
	v_max_u32_e32 v7, v2, v14
	v_min_u32_e32 v2, v2, v14
	v_max_u32_e32 v14, v5, v0
	v_min_u32_e32 v0, v5, v0
	v_max_u32_e32 v5, v9, v1
	v_min_u32_e32 v1, v9, v1
	v_max_u32_e32 v9, v15, v23
	v_min_u32_e32 v15, v15, v23
	v_max_u32_e32 v23, v16, v24
	v_min_u32_e32 v16, v16, v24
	v_max_u32_e32 v24, v17, v25
	v_min_u32_e32 v17, v17, v25
	v_max_u32_e32 v25, v18, v26
	v_min_u32_e32 v18, v18, v26
	v_max_u32_e32 v26, v19, v27
	v_min_u32_e32 v19, v19, v27
	v_max_u32_e32 v27, v20, v28
	v_min_u32_e32 v20, v20, v28
	v_max_u32_e32 v28, v21, v29
	v_min_u32_e32 v21, v21, v29
	v_max_u32_e32 v29, v22, v30
	v_min_u32_e32 v22, v22, v30
	v_max_u32_e32 v30, v31, v8
	v_min_u32_e32 v8, v31, v8
	v_max_u32_e32 v31, v32, v7
	v_min_u32_e32 v7, v32, v7
	v_max_u32_e32 v32, v13, v14
	v_min_u32_e32 v13, v13, v14
	v_max_u32_e32 v14, v10, v5
	v_min_u32_e32 v5, v10, v5
	v_max_u32_e32 v10, v11, v4
	v_min_u32_e32 v4, v11, v4
	v_max_u32_e32 v11, v12, v2
	v_min_u32_e32 v2, v12, v2
	v_max_u32_e32 v12, v3, v0
	v_min_u32_e32 v0, v3, v0
	v_max_u32_e32 v3, v6, v1
	v_min_u32_e32 v1, v6, v1
	v_max_u32_e32 v6, v15, v19
	v_min_u32_e32 v15, v15, v19
	v_max_u32_e32 v19, v16, v20
	v_min_u32_e32 v16, v16, v20
	v_max_u32_e32 v20, v17, v21
	v_min_u32_e32 v17, v17, v21
	v_max_u32_e32 v21, v18, v22
	v_min_u32_e32 v18, v18, v22
	v_max_u32_e32 v22, v9, v26
	v_min_u32_e32 v9, v9, v26
	v_max_u32_e32 v26, v23, v27
	v_min_u32_e32 v23, v23, v27
	v_max_u32_e32 v27, v24, v28
	v_min_u32_e32 v24, v24, v28
	v_max_u32_e32 v28, v25, v29
	v_min_u32_e32 v25, v25, v29
	v_max_u32_e32 v29, v30, v32
	v_min_u32_e32 v30, v30, v32
	v_max_u32_e32 v32, v31, v14
	v_min_u32_e32 v14, v31, v14
	v_max_u32_e32 v31, v8, v13
	v_min_u32_e32 v8, v8, v13
	v_max_u32_e32 v13, v7, v5
	v_min_u32_e32 v5, v7, v5
	v_max_u32_e32 v7, v10, v12
	v_min_u32_e32 v10, v10, v12
	v_max_u32_e32 v12, v11, v3
	v_min_u32_e32 v3, v11, v3
	v_max_u32_e32 v11, v4, v0
	v_min_u32_e32 v0, v4, v0
	v_max_u32_e32 v4, v2, v1
	v_min_u32_e32 v1, v2, v1
	v_max_u32_e32 v2, v15, v17
	v_min_u32_e32 v15, v15, v17
	v_max_u32_e32 v17, v16, v18
	v_min_u32_e32 v16, v16, v18
	v_max_u32_e32 v18, v6, v20
	v_min_u32_e32 v6, v6, v20
	v_max_u32_e32 v20, v19, v21
	v_min_u32_e32 v19, v19, v21
	v_max_u32_e32 v21, v9, v24
	v_min_u32_e32 v9, v9, v24
	v_max_u32_e32 v24, v23, v25
	v_min_u32_e32 v23, v23, v25
	v_max_u32_e32 v25, v22, v27
	v_min_u32_e32 v22, v22, v27
	v_max_u32_e32 v27, v26, v28
	v_min_u32_e32 v26, v26, v28
	v_min_u32_e32 v28, v29, v32
	v_min_u32_e32 v33, v30, v14
	v_min_u32_e32 v34, v31, v13
	v_min_u32_e32 v35, v8, v5
	v_min_u32_e32 v36, v7, v12
	v_min_u32_e32 v37, v10, v3
	v_min_u32_e32 v38, v11, v4
	v_min_u32_e32 v39, v0, v1
	v_min_u32_e32 v40, v15, v16
	v_min_u32_e32 v41, v2, v17
	v_min_u32_e32 v42, v6, v19
	v_min_u32_e32 v43, v18, v20
	v_min_u32_e32 v44, v9, v23
	v_min_u32_e32 v45, v21, v24
	v_min_u32_e32 v46, v22, v26
	v_min_u32_e32 v47, v25, v27
	v_max3_u32 v29, v29, v32, v40
	v_max3_u32 v15, v28, v15, v16
	v_max3_u32 v14, v30, v14, v41
	v_max3_u32 v2, v33, v2, v17
	v_max3_u32 v13, v31, v13, v42
	v_max3_u32 v6, v34, v6, v19
	v_max3_u32 v5, v8, v5, v43
	v_max3_u32 v8, v35, v18, v20
	v_max3_u32 v7, v7, v12, v44
	v_max3_u32 v9, v36, v9, v23
	v_max3_u32 v3, v10, v3, v45
	v_max3_u32 v10, v37, v21, v24
	v_max3_u32 v4, v11, v4, v46
	v_max3_u32 v11, v38, v22, v26
	v_max3_u32 v0, v0, v1, v47
	v_max3_u32 v1, v39, v25, v27
	v_readlane_b32 s22, v249, 30
	v_max_u32_e32 v12, v29, v7
	v_min_u32_e32 v7, v29, v7
	v_max_u32_e32 v16, v15, v9
	v_min_u32_e32 v9, v15, v9
	v_max_u32_e32 v15, v14, v3
	v_min_u32_e32 v3, v14, v3
	v_max_u32_e32 v14, v2, v10
	v_min_u32_e32 v2, v2, v10
	v_max_u32_e32 v10, v13, v4
	v_min_u32_e32 v4, v13, v4
	v_max_u32_e32 v13, v6, v11
	v_min_u32_e32 v6, v6, v11
	v_max_u32_e32 v11, v5, v0
	v_min_u32_e32 v0, v5, v0
	v_max_u32_e32 v5, v8, v1
	v_min_u32_e32 v1, v8, v1
	v_readlane_b32 s23, v249, 31
	v_max_u32_e32 v8, v12, v10
	v_min_u32_e32 v10, v12, v10
	v_max_u32_e32 v12, v16, v13
	v_min_u32_e32 v13, v16, v13
	v_max_u32_e32 v16, v15, v11
	v_min_u32_e32 v11, v15, v11
	v_max_u32_e32 v15, v14, v5
	v_min_u32_e32 v5, v14, v5
	v_max_u32_e32 v14, v7, v4
	v_min_u32_e32 v4, v7, v4
	v_max_u32_e32 v7, v9, v6
	v_min_u32_e32 v6, v9, v6
	v_max_u32_e32 v9, v3, v0
	v_min_u32_e32 v0, v3, v0
	v_max_u32_e32 v3, v2, v1
	v_min_u32_e32 v1, v2, v1
	s_load_dwordx2 s[22:23], s[22:23], 0x180
	v_max_u32_e32 v2, v8, v16
	v_min_u32_e32 v8, v8, v16
	v_max_u32_e32 v16, v12, v15
	v_min_u32_e32 v12, v12, v15
	v_max_u32_e32 v15, v10, v11
	v_min_u32_e32 v10, v10, v11
	v_max_u32_e32 v11, v13, v5
	v_min_u32_e32 v5, v13, v5
	v_max_u32_e32 v13, v14, v9
	v_min_u32_e32 v9, v14, v9
	v_max_u32_e32 v14, v7, v3
	v_min_u32_e32 v3, v7, v3
	v_max_u32_e32 v7, v4, v0
	v_min_u32_e32 v0, v4, v0
	v_max_u32_e32 v4, v6, v1
	v_min_u32_e32 v1, v6, v1
	v_max_u32_e32 v19, v0, v1
	v_min_u32_e32 v20, v0, v1
	v_lshl_add_u32 v0, s16, 7, v81
	v_ashrrev_i32_e32 v1, 31, v0
	v_readlane_b32 s16, v249, 19
	v_lshlrev_b64 v[0:1], 10, v[0:1]
	v_readlane_b32 s17, v249, 20
	v_max_u32_e32 v6, v2, v16
	v_min_u32_e32 v2, v2, v16
	v_max_u32_e32 v16, v8, v12
	v_min_u32_e32 v8, v8, v12
	s_waitcnt lgkmcnt(0)
	v_lshl_add_u64 v[0:1], s[22:23], 0, v[0:1]
	s_mov_b32 s21, s17
	s_lshl_b32 s20, s20, 6
	v_max_u32_e32 v12, v15, v11
	v_min_u32_e32 v11, v15, v11
	v_max_u32_e32 v15, v10, v5
	v_min_u32_e32 v10, v10, v5
	v_max_u32_e32 v17, v13, v14
	v_min_u32_e32 v13, v13, v14
	v_max_u32_e32 v14, v9, v3
	v_min_u32_e32 v9, v9, v3
	v_max_u32_e32 v18, v7, v4
	v_min_u32_e32 v7, v7, v4
	v_lshl_add_u64 v[4:5], v[0:1], 0, s[20:21]
	v_xor_b32_e32 v0, 0x7f, v6
	v_xor_b32_e32 v1, 0x7f, v2
	v_xor_b32_e32 v2, 0x7f, v16
	v_xor_b32_e32 v3, 0x7f, v8
	global_store_dwordx4 v[4:5], v[0:3], off
	v_writelane_b32 v249, s16, 19
	s_nop 0
	v_xor_b32_e32 v0, 0x7f, v12
	v_xor_b32_e32 v1, 0x7f, v11
	v_xor_b32_e32 v2, 0x7f, v15
	v_xor_b32_e32 v3, 0x7f, v10
	global_store_dwordx4 v[4:5], v[0:3], off offset:16
	v_writelane_b32 v249, s17, 20
	s_nop 0
	v_xor_b32_e32 v0, 0x7f, v17
	v_xor_b32_e32 v1, 0x7f, v13
	v_xor_b32_e32 v2, 0x7f, v14
	v_xor_b32_e32 v3, 0x7f, v9
	global_store_dwordx4 v[4:5], v[0:3], off offset:32
	s_nop 1
	v_xor_b32_e32 v0, 0x7f, v18
	v_xor_b32_e32 v1, 0x7f, v7
	v_xor_b32_e32 v2, 0x7f, v19
	v_xor_b32_e32 v3, 0x7f, v20
	global_store_dwordx4 v[4:5], v[0:3], off offset:48
	s_branch .LBB0_19

.LBB0_26:
	v_readlane_b32 s0, v249, 3
	v_readlane_b32 s1, v249, 4
	s_load_dword s8, s[0:1], 0x10
	s_waitcnt lgkmcnt(0)
	s_load_dword s10, s[0:1], 0x0
	v_readlane_b32 s2, v249, 41
	v_readlane_b32 s3, v249, 42
	s_add_u32 s2, s2, 0x80000
	s_addc_u32 s3, s3, 0
	s_waitcnt lgkmcnt(0)
	s_lshr_b32 s8, s8, 16
	s_cmp_lg_u32 s8, 0
	s_cselect_b64 s[8:9], -1, 0
	s_cmp_lg_u64 s[8:9], 0
	v_readlane_b32 s8, v249, 19
	v_readlane_b32 s0, v249, 30
	v_readlane_b32 s9, v249, 20
	s_addc_u32 s8, s10, 0
	s_movk_i32 s30, 0x840
.Lmodl_pq:
	s_cmp_ge_u32 s30, s8
	s_cbranch_scc0 .Lmodd_pq
	s_sub_u32 s30, s30, s8
	s_branch .Lmodl_pq
.Lmodd_pq:
	s_lshr_b32 s31, s8, 2
	s_cmp_gt_u32 s30, s31
	s_cselect_b32 s30, 0, s30
	s_sub_u32 s8, s8, s30
	v_readlane_b32 s1, v249, 31
	v_writelane_b32 v249, s8, 19
	s_load_dwordx2 s[0:1], s[0:1], 0x160
	v_mov_b32_e32 v0, v220
	v_writelane_b32 v249, s9, 20
	s_lshl_b64 s[8:9], s[8:9], 8
	v_readlane_b32 s10, v249, 0
	s_cmp_lt_u32 s10, s30
	s_cbranch_scc1 .Lskip_conv_pq
	s_sub_u32 s16, s10, s30
	s_ashr_i32 s17, s16, 31
	s_lshl_b64 s[10:11], s[16:17], 8
	s_add_u32 s10, s10, s6
	s_addc_u32 s11, s11, s7
	s_nop 0
	v_ashrrev_i32_e32 v1, 31, v0
	s_waitcnt vmcnt(0)
	v_lshl_add_u64 v[74:75], s[10:11], 0, v[0:1]
	v_cmp_gt_u64_e32 vcc, s[2:3], v[74:75]
	s_and_saveexec_b64 s[10:11], vcc
	s_cbranch_execz .LBB0_33
	v_readlane_b32 s12, v249, 30
	v_readlane_b32 s13, v249, 31
	s_load_dwordx2 s[14:15], s[12:13], 0xb8
	v_readlane_b32 s18, v249, 37
	v_readlane_b32 s19, v249, 38
	s_lshl_b64 s[12:13], s[16:17], 15
	s_lshl_b64 s[18:19], s[18:19], 26
	s_waitcnt lgkmcnt(0)
	s_add_u32 s14, s14, s18
	v_add_u32_e32 v2, 22, v0
	v_lshlrev_b64 v[0:1], 7, v[0:1]
	s_addc_u32 s15, s15, s19
	v_readlane_b32 s18, v249, 19
	v_lshl_add_u64 v[0:1], s[14:15], 0, v[0:1]
	s_mov_b64 s[14:15], 0x2aaab40
	v_readlane_b32 s19, v249, 20
	v_lshl_add_u64 v[70:71], v[0:1], 0, s[14:15]
	s_lshl_b64 s[14:15], s[18:19], 16
	v_and_b32_e32 v2, 31, v2
	s_add_u32 s16, s16, s18
	v_mul_u32_u24_e32 v2, 24, v2
	v_mov_b32_e32 v3, v80
	s_addc_u32 s17, s17, 0
	v_lshl_add_u64 v[68:69], s[0:1], 0, v[2:3]
	s_lshl_b64 s[16:17], s[16:17], 15
	s_mov_b64 s[18:19], 0
	s_branch .LBB0_29

.LBB0_33:
	s_or_b64 exec, exec, s[10:11]
	v_readlane_b32 s10, v249, 0
	s_sub_u32 s18, s10, s30
	s_ashr_i32 s19, s18, 31
	s_lshl_b64 s[10:11], s[18:19], 8
	s_add_u32 s10, s10, s6
	v_mov_b32_e32 v0, v220
	s_addc_u32 s11, s11, s7
	s_nop 0
	v_ashrrev_i32_e32 v1, 31, v0
	v_lshl_add_u64 v[70:71], s[10:11], 0, v[0:1]
	v_cmp_gt_u64_e32 vcc, s[2:3], v[70:71]
	s_and_saveexec_b64 s[10:11], vcc
	s_cbranch_execz .LBB0_40
	v_readlane_b32 s12, v249, 30
	v_readlane_b32 s13, v249, 31
	s_load_dwordx2 s[16:17], s[12:13], 0xc0
	v_readlane_b32 s22, v249, 19
	v_readlane_b32 s20, v249, 37
	v_readlane_b32 s23, v249, 20
	v_readlane_b32 s21, v249, 38
	s_lshl_b64 s[12:13], s[22:23], 13
	s_lshl_b64 s[14:15], s[18:19], 15
	s_lshl_b64 s[20:21], s[20:21], 26
	s_waitcnt lgkmcnt(0)
	s_add_u32 s16, s16, s20
	v_lshlrev_b64 v[0:1], 7, v[0:1]
	s_addc_u32 s17, s17, s21
	v_lshl_add_u64 v[0:1], s[16:17], 0, v[0:1]
	s_mov_b64 s[16:17], 0x2aaab40
	v_lshl_add_u64 v[66:67], v[0:1], 0, s[16:17]
	s_lshl_b64 s[16:17], s[22:23], 16
	s_add_u32 s18, s18, s22
	s_addc_u32 s19, s19, 0
	v_lshlrev_b64 v[64:65], 4, v[70:71]
	s_lshl_b64 s[18:19], s[18:19], 15
	s_mov_b64 s[20:21], 0
	s_branch .LBB0_36

.LBB0_40:
	s_or_b64 exec, exec, s[10:11]
.Lskip_conv_pq:
	s_waitcnt lgkmcnt(0)
	s_mov_b64 s[0:1], 0
.LBB0_41:
	v_writelane_b32 v249, s0, 46
	s_nop 1
	v_writelane_b32 v249, s1, 47
	s_branch .LBB0_46

.LBB0_49:
	s_and_b32 s2, s14, 7
	s_mulk_i32 s2, 0x84
	s_ashr_i32 s19, s14, 3
	s_add_i32 s2, s2, s19
	v_mov_b32_e32 v26, v220
	s_ashr_i32 s12, s2, 3
	s_ashr_i32 s13, s12, 31
	v_lshlrev_b32_e32 v122, 4, v26
	v_and_b32_e32 v0, 32, v26
	v_bitop3_b32 v0, v122, v0, 48 bitop3:0x6c
	s_and_b32 s18, s2, 7
	s_lshl_b64 s[2:3], s[12:13], 18
	v_lshrrev_b32_e32 v16, 2, v26
	v_lshrrev_b32_e32 v1, 1, v26
	v_lshrrev_b32_e32 v0, 1, v0
	v_ashrrev_i32_e32 v4, 3, v26
	s_add_u32 s20, s0, s2
	v_and_or_b32 v0, v1, 32, v0
	v_bfi_b32 v4, 15, v16, v4
	s_addc_u32 s21, s1, s3
	s_lshl_b32 s13, s18, 18
	v_lshlrev_b32_e32 v0, 1, v0
	v_mov_b32_e32 v1, v80
	v_ashrrev_i32_e32 v5, 31, v4
	v_add_u32_e32 v12, 0x1000, v122
	s_add_u32 s22, s15, s13
	v_lshl_add_u64 v[2:3], s[20:21], 0, v[0:1]
	v_lshlrev_b64 v[4:5], 11, v[4:5]
	v_readfirstlane_b32 s13, v122
	v_ashrrev_i32_e32 v8, 7, v12
	v_add_u32_e32 v17, 0x2000, v122
	v_lshl_add_u64 v[6:7], v[2:3], 0, v[4:5]
	s_mov_b32 m0, s13
	v_bfi_b32 v8, -16, v8, v16
	v_readfirstlane_b32 s13, v12
	v_ashrrev_i32_e32 v12, 7, v17
	v_add_u32_e32 v18, 0x3000, v122
	global_load_lds_dwordx4 v[6:7], off
	v_ashrrev_i32_e32 v9, 31, v8
	s_mov_b32 m0, s13
	v_bfi_b32 v12, -16, v12, v16
	v_readfirstlane_b32 s13, v17
	v_ashrrev_i32_e32 v17, 7, v18
	v_lshlrev_b64 v[8:9], 11, v[8:9]
	v_ashrrev_i32_e32 v13, 31, v12
	v_bfi_b32 v16, -16, v17, v16
	s_addc_u32 s23, s16, 0
	v_lshl_add_u64 v[10:11], v[2:3], 0, v[8:9]
	v_lshlrev_b64 v[12:13], 11, v[12:13]
	v_ashrrev_i32_e32 v17, 31, v16
	global_load_lds_dwordx4 v[10:11], off
	v_lshl_add_u64 v[14:15], v[2:3], 0, v[12:13]
	s_mov_b32 m0, s13
	v_lshlrev_b64 v[16:17], 11, v[16:17]
	v_readfirstlane_b32 s13, v18
	v_lshl_add_u64 v[18:19], s[22:23], 0, v[0:1]
	v_add_u32_e32 v1, 0x4000, v122
	global_load_lds_dwordx4 v[14:15], off
	v_lshl_add_u64 v[2:3], v[2:3], 0, v[16:17]
	s_mov_b32 m0, s13
	v_readfirstlane_b32 s13, v1
	v_add_u32_e32 v1, 0x5000, v122
	global_load_lds_dwordx4 v[2:3], off
	v_lshl_add_u64 v[20:21], v[18:19], 0, v[4:5]
	s_mov_b32 m0, s13
	v_readfirstlane_b32 s13, v1
	v_add_u32_e32 v1, 0x6000, v122
	global_load_lds_dwordx4 v[20:21], off
	v_lshl_add_u64 v[22:23], v[18:19], 0, v[8:9]
	s_mov_b32 m0, s13
	v_readfirstlane_b32 s13, v1
	v_add_u32_e32 v1, 0x7000, v122
	global_load_lds_dwordx4 v[22:23], off
	v_lshl_add_u64 v[24:25], v[18:19], 0, v[12:13]
	s_mov_b32 m0, s13
	v_readfirstlane_b32 s13, v1
	v_add_u32_e32 v1, 0x8000, v122
	global_load_lds_dwordx4 v[24:25], off
	v_lshl_add_u64 v[18:19], v[18:19], 0, v[16:17]
	s_mov_b32 m0, s13
	s_mov_b64 s[20:21], 0x80
	v_readfirstlane_b32 s13, v1
	v_add_u32_e32 v1, 0x9000, v122
	global_load_lds_dwordx4 v[18:19], off
	v_lshl_add_u64 v[6:7], v[6:7], 0, s[20:21]
	s_mov_b32 m0, s13
	v_readfirstlane_b32 s13, v1
	v_add_u32_e32 v1, 0xa000, v122
	global_load_lds_dwordx4 v[6:7], off
	v_lshl_add_u64 v[6:7], v[10:11], 0, s[20:21]
	s_mov_b32 m0, s13
	v_readfirstlane_b32 s13, v1
	v_add_u32_e32 v1, 0xb000, v122
	global_load_lds_dwordx4 v[6:7], off
	v_lshl_add_u64 v[6:7], v[14:15], 0, s[20:21]
	s_mov_b32 m0, s13
	v_readfirstlane_b32 s13, v1
	v_add_u32_e32 v1, 0xc000, v122
	global_load_lds_dwordx4 v[6:7], off
	v_lshl_add_u64 v[2:3], v[2:3], 0, s[20:21]
	s_mov_b32 m0, s13
	v_readfirstlane_b32 s13, v1
	v_add_u32_e32 v1, 0xd000, v122
	global_load_lds_dwordx4 v[2:3], off
	v_lshl_add_u64 v[2:3], v[20:21], 0, s[20:21]
	s_mov_b32 m0, s13
	v_readfirstlane_b32 s13, v1
	v_add_u32_e32 v1, 0xe000, v122
	global_load_lds_dwordx4 v[2:3], off
	v_lshl_add_u64 v[2:3], v[22:23], 0, s[20:21]
	s_mov_b32 m0, s13
	v_readfirstlane_b32 s13, v1
	v_add_u32_e32 v1, 0xf000, v122
	global_load_lds_dwordx4 v[2:3], off
	v_lshl_add_u64 v[2:3], v[24:25], 0, s[20:21]
	s_mov_b32 m0, s13
	v_readfirstlane_b32 s13, v1
	global_load_lds_dwordx4 v[2:3], off
	v_lshl_add_u64 v[2:3], v[18:19], 0, s[20:21]
	s_mov_b32 m0, s13
	v_lshlrev_b32_e32 v1, 6, v26
	global_load_lds_dwordx4 v[2:3], off
	v_lshlrev_b32_e32 v2, 2, v26
	v_and_b32_e32 v3, 48, v26
	v_bitop3_b32 v2, v2, v3, 32 bitop3:0x6c
	s_movk_i32 s13, 0x3c0
	v_and_or_b32 v2, v1, s13, v2
	s_movk_i32 s13, 0xe000
	v_and_or_b32 v121, v1, s13, v2
	v_lshlrev_b32_e32 v1, 7, v26
	s_movk_i32 s13, 0x2000
	v_and_or_b32 v120, v1, s13, v2
	s_add_i32 s13, s17, s19
	s_and_b32 s13, s13, 7
	v_readlane_b32 s20, v249, 19
	v_readlane_b32 s21, v249, 20
	s_lshl_b32 s20, s13, 18
	s_mov_b32 s13, s21
	v_lshl_add_u64 v[2:3], s[20:21], 0, v[16:17]
	v_or_b32_e32 v2, v2, v0
	v_lshl_add_u64 v[100:101], s[8:9], 0, v[2:3]
	v_lshl_add_u64 v[2:3], s[20:21], 0, v[12:13]
	v_or_b32_e32 v2, v2, v0
	v_lshl_add_u64 v[102:103], s[8:9], 0, v[2:3]
	v_lshl_add_u64 v[2:3], s[20:21], 0, v[8:9]
	v_or_b32_e32 v2, v2, v0
	v_lshl_add_u64 v[104:105], s[8:9], 0, v[2:3]
	v_lshl_add_u64 v[2:3], s[20:21], 0, v[4:5]
	v_or_b32_e32 v2, v2, v0
	v_lshl_add_u64 v[106:107], s[8:9], 0, v[2:3]
	v_lshl_add_u64 v[2:3], s[2:3], 0, v[16:17]
	v_or_b32_e32 v2, v2, v0
	v_lshl_add_u64 v[108:109], s[10:11], 0, v[2:3]
	v_lshl_add_u64 v[2:3], s[2:3], 0, v[12:13]
	v_or_b32_e32 v2, v2, v0
	v_lshl_add_u64 v[110:111], s[10:11], 0, v[2:3]
	v_lshl_add_u64 v[2:3], s[2:3], 0, v[8:9]
	v_or_b32_e32 v2, v2, v0
	v_lshl_add_u64 v[112:113], s[10:11], 0, v[2:3]
	v_lshl_add_u64 v[2:3], s[2:3], 0, v[4:5]
	v_writelane_b32 v249, s12, 19
	v_or_b32_e32 v2, v2, v0
	v_mov_b32_e32 v0, 0
	v_writelane_b32 v249, s13, 20
	v_lshl_add_u64 v[116:117], s[10:11], 0, v[2:3]
	s_mov_b64 s[2:3], 0
	s_mov_b32 s13, 0
	v_mov_b32_e32 v1, v0
	v_mov_b32_e32 v2, v0
	v_mov_b32_e32 v3, v0
	v_mov_b32_e32 v4, v0
	v_mov_b32_e32 v5, v0
	v_mov_b32_e32 v6, v0
	v_mov_b32_e32 v7, v0
	v_mov_b32_e32 v8, v0
	v_mov_b32_e32 v9, v0
	v_mov_b32_e32 v10, v0
	v_mov_b32_e32 v11, v0
	v_mov_b32_e32 v12, v0
	v_mov_b32_e32 v13, v0
	v_mov_b32_e32 v14, v0
	v_mov_b32_e32 v15, v0
	v_mov_b32_e32 v16, v0
	v_mov_b32_e32 v17, v0
	v_mov_b32_e32 v18, v0
	v_mov_b32_e32 v19, v0
	v_mov_b32_e32 v20, v0
	v_mov_b32_e32 v21, v0
	v_mov_b32_e32 v22, v0
	v_mov_b32_e32 v23, v0
	v_mov_b32_e32 v24, v0
	v_mov_b32_e32 v25, v0
	v_mov_b32_e32 v26, v0
	v_mov_b32_e32 v27, v0
	v_mov_b32_e32 v28, v0
	v_mov_b32_e32 v29, v0
	v_mov_b32_e32 v30, v0
	v_mov_b32_e32 v31, v0
	v_mov_b32_e32 v32, v0
	v_mov_b32_e32 v33, v0
	v_mov_b32_e32 v34, v0
	v_mov_b32_e32 v35, v0
	v_mov_b32_e32 v36, v0
	v_mov_b32_e32 v37, v0
	v_mov_b32_e32 v38, v0
	v_mov_b32_e32 v39, v0
	v_mov_b32_e32 v40, v0
	v_mov_b32_e32 v41, v0
	v_mov_b32_e32 v42, v0
	v_mov_b32_e32 v43, v0
	v_mov_b32_e32 v44, v0
	v_mov_b32_e32 v45, v0
	v_mov_b32_e32 v46, v0
	v_mov_b32_e32 v47, v0
	v_mov_b32_e32 v48, v0
	v_mov_b32_e32 v49, v0
	v_mov_b32_e32 v50, v0
	v_mov_b32_e32 v51, v0
	v_mov_b32_e32 v52, v0
	v_mov_b32_e32 v53, v0
	v_mov_b32_e32 v54, v0
	v_mov_b32_e32 v55, v0
	v_mov_b32_e32 v56, v0
	v_mov_b32_e32 v57, v0
	v_mov_b32_e32 v58, v0
	v_mov_b32_e32 v59, v0
	v_mov_b32_e32 v60, v0
	v_mov_b32_e32 v61, v0
	v_mov_b32_e32 v62, v0
	v_mov_b32_e32 v63, v0
	v_readfirstlane_b32 s60, v122
.LBB0_50:
	s_and_b32 s19, s13, 0x8000
	s_waitcnt vmcnt(8)
	s_barrier
	v_add_u32_e32 v123, s19, v121
	v_or_b32_e32 v156, s19, v120
	s_add_u32 s61, s60, s19
	ds_read_b128 v[124:127], v123
	ds_read_b128 v[140:143], v156 offset:16384
	ds_read_b128 v[144:147], v156 offset:18432
	ds_read_b128 v[148:151], v156 offset:20480
	ds_read_b128 v[152:155], v156 offset:22528
	ds_read_b128 v[128:131], v123 offset:2048
	ds_read_b128 v[132:135], v123 offset:4096
	ds_read_b128 v[136:139], v123 offset:6144
	s_waitcnt lgkmcnt(6)
	v_mfma_f32_16x16x32_bf16 v[60:63], v[124:127], v[140:143], v[60:63]
	ds_read_b128 v[196:199], v123 offset:1024
	s_waitcnt lgkmcnt(6)
	v_mfma_f32_16x16x32_bf16 v[56:59], v[124:127], v[144:147], v[56:59]
	ds_read_b128 v[212:215], v156 offset:17408
	s_waitcnt lgkmcnt(6)
	v_mfma_f32_16x16x32_bf16 v[52:55], v[124:127], v[148:151], v[52:55]
	ds_read_b128 v[216:219], v156 offset:19456
	s_waitcnt lgkmcnt(6)
	v_mfma_f32_16x16x32_bf16 v[48:51], v[124:127], v[152:155], v[48:51]
	ds_read_b128 v[240:243], v156 offset:21504
	ds_read_b128 v[244:247], v156 offset:23552
	s_waitcnt lgkmcnt(7)
	v_mfma_f32_16x16x32_bf16 v[44:47], v[128:131], v[140:143], v[44:47]
	v_mfma_f32_16x16x32_bf16 v[40:43], v[128:131], v[144:147], v[40:43]
	v_mfma_f32_16x16x32_bf16 v[36:39], v[128:131], v[148:151], v[36:39]
	v_mfma_f32_16x16x32_bf16 v[32:35], v[128:131], v[152:155], v[32:35]
	ds_read_b128 v[200:203], v123 offset:3072
	ds_read_b128 v[204:207], v123 offset:5120
	s_waitcnt lgkmcnt(8)
	v_mfma_f32_16x16x32_bf16 v[28:31], v[132:135], v[140:143], v[28:31]
	v_mfma_f32_16x16x32_bf16 v[24:27], v[132:135], v[144:147], v[24:27]
	v_mfma_f32_16x16x32_bf16 v[20:23], v[132:135], v[148:151], v[20:23]
	v_mfma_f32_16x16x32_bf16 v[16:19], v[132:135], v[152:155], v[16:19]
	ds_read_b128 v[208:211], v123 offset:7168
	s_waitcnt lgkmcnt(8)
	v_mfma_f32_16x16x32_bf16 v[12:15], v[136:139], v[140:143], v[12:15]
	v_mfma_f32_16x16x32_bf16 v[8:11], v[136:139], v[144:147], v[8:11]
	v_mfma_f32_16x16x32_bf16 v[4:7], v[136:139], v[148:151], v[4:7]
	v_mfma_f32_16x16x32_bf16 v[0:3], v[136:139], v[152:155], v[0:3]
	s_waitcnt lgkmcnt(0)
	s_barrier
	s_mov_b32 m0, s61
	v_lshl_add_u64 v[124:125], v[116:117], 0, s[2:3]
	v_mfma_f32_16x16x32_bf16 v[60:63], v[196:199], v[212:215], v[60:63]
	global_load_lds_dwordx4 v[124:125], off
	v_mfma_f32_16x16x32_bf16 v[56:59], v[196:199], v[216:219], v[56:59]
	s_add_u32 m0, s61, 0x1000
	v_lshl_add_u64 v[126:127], v[112:113], 0, s[2:3]
	v_mfma_f32_16x16x32_bf16 v[52:55], v[196:199], v[240:243], v[52:55]
	global_load_lds_dwordx4 v[126:127], off
	v_mfma_f32_16x16x32_bf16 v[48:51], v[196:199], v[244:247], v[48:51]
	s_add_u32 m0, s61, 0x2000
	v_lshl_add_u64 v[128:129], v[110:111], 0, s[2:3]
	v_mfma_f32_16x16x32_bf16 v[44:47], v[200:203], v[212:215], v[44:47]
	global_load_lds_dwordx4 v[128:129], off
	v_mfma_f32_16x16x32_bf16 v[40:43], v[200:203], v[216:219], v[40:43]
	s_add_u32 m0, s61, 0x3000
	v_lshl_add_u64 v[130:131], v[108:109], 0, s[2:3]
	v_mfma_f32_16x16x32_bf16 v[36:39], v[200:203], v[240:243], v[36:39]
	global_load_lds_dwordx4 v[130:131], off
	v_mfma_f32_16x16x32_bf16 v[32:35], v[200:203], v[244:247], v[32:35]
	s_add_u32 m0, s61, 0x4000
	v_lshl_add_u64 v[132:133], v[106:107], 0, s[2:3]
	v_mfma_f32_16x16x32_bf16 v[28:31], v[204:207], v[212:215], v[28:31]
	global_load_lds_dwordx4 v[132:133], off
	v_mfma_f32_16x16x32_bf16 v[24:27], v[204:207], v[216:219], v[24:27]
	s_add_u32 m0, s61, 0x5000
	v_lshl_add_u64 v[134:135], v[104:105], 0, s[2:3]
	v_mfma_f32_16x16x32_bf16 v[20:23], v[204:207], v[240:243], v[20:23]
	global_load_lds_dwordx4 v[134:135], off
	v_mfma_f32_16x16x32_bf16 v[16:19], v[204:207], v[244:247], v[16:19]
	s_add_u32 m0, s61, 0x6000
	v_lshl_add_u64 v[136:137], v[102:103], 0, s[2:3]
	v_mfma_f32_16x16x32_bf16 v[12:15], v[208:211], v[212:215], v[12:15]
	global_load_lds_dwordx4 v[136:137], off
	v_mfma_f32_16x16x32_bf16 v[8:11], v[208:211], v[216:219], v[8:11]
	s_add_u32 m0, s61, 0x7000
	v_lshl_add_u64 v[138:139], v[100:101], 0, s[2:3]
	v_mfma_f32_16x16x32_bf16 v[4:7], v[208:211], v[240:243], v[4:7]
	global_load_lds_dwordx4 v[138:139], off
	v_mfma_f32_16x16x32_bf16 v[0:3], v[208:211], v[244:247], v[0:3]
	s_add_u32 s2, s2, 0x80
	s_addc_u32 s3, s3, 0
	s_add_i32 s13, s13, 0x8000
	s_cmpk_lg_i32 s2, 0x700
	s_cbranch_scc1 .LBB0_50
	s_waitcnt vmcnt(8)
	s_barrier
	ds_read_b128 v[100:103], v121
	ds_read_b128 v[104:107], v121 offset:2048
	ds_read_b128 v[108:111], v121 offset:4096
	ds_read_b128 v[122:125], v121 offset:6144
	ds_read_b128 v[126:129], v120 offset:16384
	ds_read_b128 v[130:133], v120 offset:18432
	ds_read_b128 v[134:137], v120 offset:20480
	ds_read_b128 v[138:141], v120 offset:22528
	s_waitcnt lgkmcnt(0)
	v_mfma_f32_16x16x32_bf16 v[60:63], v[100:103], v[126:129], v[60:63]
	s_lshl_b32 s2, s12, 7
	s_ashr_i32 s3, s2, 31
	s_lshl_b64 s[2:3], s[2:3], 10
	v_mfma_f32_16x16x32_bf16 v[56:59], v[100:103], v[130:133], v[56:59]
	s_lshl_b32 s12, s18, 7
	s_or_b32 s2, s2, s12
	v_readlane_b32 s12, v249, 30
	v_mfma_f32_16x16x32_bf16 v[52:55], v[100:103], v[134:137], v[52:55]
	v_readlane_b32 s13, v249, 31
	v_mfma_f32_16x16x32_bf16 v[48:51], v[100:103], v[138:141], v[48:51]
	v_mfma_f32_16x16x32_bf16 v[44:47], v[104:107], v[126:129], v[44:47]
	v_mfma_f32_16x16x32_bf16 v[40:43], v[104:107], v[130:133], v[40:43]
	v_mfma_f32_16x16x32_bf16 v[36:39], v[104:107], v[134:137], v[36:39]
	v_mfma_f32_16x16x32_bf16 v[32:35], v[104:107], v[138:141], v[32:35]
	v_mfma_f32_16x16x32_bf16 v[28:31], v[108:111], v[126:129], v[28:31]
	v_mfma_f32_16x16x32_bf16 v[24:27], v[108:111], v[130:133], v[24:27]
	v_mfma_f32_16x16x32_bf16 v[20:23], v[108:111], v[134:137], v[20:23]
	v_mfma_f32_16x16x32_bf16 v[16:19], v[108:111], v[138:141], v[16:19]
	v_mfma_f32_16x16x32_bf16 v[12:15], v[122:125], v[126:129], v[12:15]
	v_mfma_f32_16x16x32_bf16 v[8:11], v[122:125], v[130:133], v[8:11]
	v_mfma_f32_16x16x32_bf16 v[4:7], v[122:125], v[134:137], v[4:7]
	v_mfma_f32_16x16x32_bf16 v[0:3], v[122:125], v[138:141], v[0:3]
	ds_read_b128 v[100:103], v121 offset:1024
	ds_read_b128 v[104:107], v121 offset:3072
	ds_read_b128 v[108:111], v121 offset:5120
	ds_read_b128 v[122:125], v121 offset:7168
	ds_read_b128 v[126:129], v120 offset:17408
	ds_read_b128 v[130:133], v120 offset:19456
	ds_read_b128 v[134:137], v120 offset:21504
	ds_read_b128 v[138:141], v120 offset:23552
	s_waitcnt lgkmcnt(0)
	s_barrier
	s_waitcnt vmcnt(0)
	s_barrier
	s_waitcnt lgkmcnt(3)
	v_mfma_f32_16x16x32_bf16 v[60:63], v[100:103], v[126:129], v[60:63]
	s_waitcnt lgkmcnt(2)
	v_mfma_f32_16x16x32_bf16 v[56:59], v[100:103], v[130:133], v[56:59]
	s_waitcnt lgkmcnt(1)
	v_mfma_f32_16x16x32_bf16 v[52:55], v[100:103], v[134:137], v[52:55]
	s_waitcnt lgkmcnt(0)
	v_mfma_f32_16x16x32_bf16 v[48:51], v[100:103], v[138:141], v[48:51]
	v_mfma_f32_16x16x32_bf16 v[44:47], v[104:107], v[126:129], v[44:47]
	v_mfma_f32_16x16x32_bf16 v[40:43], v[104:107], v[130:133], v[40:43]
	v_mfma_f32_16x16x32_bf16 v[36:39], v[104:107], v[134:137], v[36:39]
	v_mfma_f32_16x16x32_bf16 v[32:35], v[104:107], v[138:141], v[32:35]
	v_mfma_f32_16x16x32_bf16 v[28:31], v[108:111], v[126:129], v[28:31]
	v_mfma_f32_16x16x32_bf16 v[24:27], v[108:111], v[130:133], v[24:27]
	v_mfma_f32_16x16x32_bf16 v[20:23], v[108:111], v[134:137], v[20:23]
	v_mfma_f32_16x16x32_bf16 v[16:19], v[108:111], v[138:141], v[16:19]
	v_mfma_f32_16x16x32_bf16 v[12:15], v[122:125], v[126:129], v[12:15]
	v_mfma_f32_16x16x32_bf16 v[8:11], v[122:125], v[130:133], v[8:11]
	v_mfma_f32_16x16x32_bf16 v[4:7], v[122:125], v[134:137], v[4:7]
	v_mfma_f32_16x16x32_bf16 v[0:3], v[122:125], v[138:141], v[0:3]
	ds_read_b128 v[100:103], v121 offset:32768
	ds_read_b128 v[104:107], v121 offset:34816
	ds_read_b128 v[108:111], v121 offset:36864
	ds_read_b128 v[122:125], v121 offset:38912
	ds_read_b128 v[126:129], v120 offset:49152
	ds_read_b128 v[130:133], v120 offset:51200
	ds_read_b128 v[134:137], v120 offset:53248
	ds_read_b128 v[138:141], v120 offset:55296
	s_waitcnt lgkmcnt(3)
	v_mfma_f32_16x16x32_bf16 v[60:63], v[100:103], v[126:129], v[60:63]
	s_waitcnt lgkmcnt(2)
	v_mfma_f32_16x16x32_bf16 v[56:59], v[100:103], v[130:133], v[56:59]
	s_waitcnt lgkmcnt(1)
	v_mfma_f32_16x16x32_bf16 v[52:55], v[100:103], v[134:137], v[52:55]
	s_waitcnt lgkmcnt(0)
	v_mfma_f32_16x16x32_bf16 v[48:51], v[100:103], v[138:141], v[48:51]
	v_mfma_f32_16x16x32_bf16 v[44:47], v[104:107], v[126:129], v[44:47]
	v_mfma_f32_16x16x32_bf16 v[40:43], v[104:107], v[130:133], v[40:43]
	v_mfma_f32_16x16x32_bf16 v[36:39], v[104:107], v[134:137], v[36:39]
	v_mfma_f32_16x16x32_bf16 v[32:35], v[104:107], v[138:141], v[32:35]
	v_mfma_f32_16x16x32_bf16 v[28:31], v[108:111], v[126:129], v[28:31]
	v_mfma_f32_16x16x32_bf16 v[24:27], v[108:111], v[130:133], v[24:27]
	v_mfma_f32_16x16x32_bf16 v[20:23], v[108:111], v[134:137], v[20:23]
	v_mfma_f32_16x16x32_bf16 v[16:19], v[108:111], v[138:141], v[16:19]
	v_mfma_f32_16x16x32_bf16 v[12:15], v[122:125], v[126:129], v[12:15]
	v_mfma_f32_16x16x32_bf16 v[8:11], v[122:125], v[130:133], v[8:11]
	v_mfma_f32_16x16x32_bf16 v[4:7], v[122:125], v[134:137], v[4:7]
	v_mfma_f32_16x16x32_bf16 v[0:3], v[122:125], v[138:141], v[0:3]
	ds_read_b128 v[100:103], v121 offset:33792
	ds_read_b128 v[104:107], v121 offset:35840
	ds_read_b128 v[108:111], v121 offset:37888
	ds_read_b128 v[122:125], v121 offset:39936
	ds_read_b128 v[126:129], v120 offset:50176
	ds_read_b128 v[130:133], v120 offset:52224
	ds_read_b128 v[134:137], v120 offset:54272
	ds_read_b128 v[138:141], v120 offset:56320
	s_waitcnt lgkmcnt(0)
	s_barrier
	s_waitcnt lgkmcnt(3)
	v_mfma_f32_16x16x32_bf16 v[60:63], v[100:103], v[126:129], v[60:63]
	s_waitcnt lgkmcnt(0)
	s_barrier
	v_mfma_f32_16x16x32_bf16 v[56:59], v[100:103], v[130:133], v[56:59]
	s_nop 7
	ds_write2_b32 v118, v60, v56 offset1:16
	ds_write2_b32 v118, v61, v57 offset0:132 offset1:148
	v_mfma_f32_16x16x32_bf16 v[44:47], v[104:107], v[126:129], v[44:47]
	v_add_u32_e32 v56, 0x400, v118
	v_mfma_f32_16x16x32_bf16 v[40:43], v[104:107], v[130:133], v[40:43]
	v_mfma_f32_16x16x32_bf16 v[52:55], v[100:103], v[134:137], v[52:55]
	v_mfma_f32_16x16x32_bf16 v[48:51], v[100:103], v[138:141], v[48:51]
	ds_write2_b32 v56, v62, v58 offset0:8 offset1:24
	ds_write2_b32 v56, v63, v59 offset0:140 offset1:156
	s_nop 5
	ds_write2_b32 v118, v52, v48 offset0:32 offset1:48
	ds_write2_b32 v118, v53, v49 offset0:164 offset1:180
	ds_write2_b32 v56, v54, v50 offset0:40 offset1:56
	ds_write2_b32 v56, v55, v51 offset0:172 offset1:188
	v_add_u32_e32 v48, 0x2000, v118
	v_mfma_f32_16x16x32_bf16 v[28:31], v[108:111], v[126:129], v[28:31]
	ds_write2_b32 v48, v44, v40 offset0:64 offset1:80
	ds_write2_b32 v48, v45, v41 offset0:196 offset1:212
	v_add_u32_e32 v40, 0x2400, v118
	v_mfma_f32_16x16x32_bf16 v[24:27], v[108:111], v[130:133], v[24:27]
	v_mfma_f32_16x16x32_bf16 v[36:39], v[104:107], v[134:137], v[36:39]
	v_mfma_f32_16x16x32_bf16 v[32:35], v[104:107], v[138:141], v[32:35]
	ds_write2_b32 v40, v46, v42 offset0:72 offset1:88
	ds_write2_b32 v40, v47, v43 offset0:204 offset1:220
	s_nop 5
	ds_write2_b32 v48, v36, v32 offset0:96 offset1:112
	ds_write2_b32 v48, v37, v33 offset0:228 offset1:244
	ds_write2_b32 v40, v38, v34 offset0:104 offset1:120
	ds_write2_b32 v40, v39, v35 offset0:236 offset1:252
	v_add_u32_e32 v32, 0x4000, v118
	v_mfma_f32_16x16x32_bf16 v[20:23], v[108:111], v[134:137], v[20:23]
	ds_write2_b32 v32, v28, v24 offset0:128 offset1:144
	v_add_u32_e32 v24, 0x4400, v118
	ds_write2_b32 v24, v29, v25 offset0:4 offset1:20
	ds_write2_b32 v24, v30, v26 offset0:136 offset1:152
	v_mfma_f32_16x16x32_bf16 v[16:19], v[108:111], v[138:141], v[16:19]
	v_add_u32_e32 v25, 0x4800, v118
	ds_write2_b32 v25, v31, v27 offset0:12 offset1:28
	s_nop 5
	ds_write2_b32 v32, v20, v16 offset0:160 offset1:176
	ds_write2_b32 v24, v21, v17 offset0:36 offset1:52
	ds_write2_b32 v24, v22, v18 offset0:168 offset1:184
	ds_write2_b32 v25, v23, v19 offset0:44 offset1:60
	v_mfma_f32_16x16x32_bf16 v[12:15], v[122:125], v[126:129], v[12:15]
	v_add_u32_e32 v16, 0x6000, v118
	v_mfma_f32_16x16x32_bf16 v[8:11], v[122:125], v[130:133], v[8:11]
	v_mfma_f32_16x16x32_bf16 v[4:7], v[122:125], v[134:137], v[4:7]
	v_mfma_f32_16x16x32_bf16 v[0:3], v[122:125], v[138:141], v[0:3]
	s_nop 5
	ds_write2_b32 v16, v12, v8 offset0:192 offset1:208
	v_add_u32_e32 v8, 0x6400, v118
	ds_write2_b32 v8, v13, v9 offset0:68 offset1:84
	ds_write2_b32 v8, v14, v10 offset0:200 offset1:216
	v_add_u32_e32 v9, 0x6800, v118
	ds_write2_b32 v9, v15, v11 offset0:76 offset1:92
	ds_write2_b32 v16, v4, v0 offset0:224 offset1:240
	ds_write2_b32 v8, v5, v1 offset0:100 offset1:116
	ds_write2_b32 v8, v6, v2 offset0:232 offset1:248
	ds_write2_b32 v9, v7, v3 offset0:108 offset1:124
	s_waitcnt lgkmcnt(0)
	s_barrier
	v_mov_b32_e32 v1, s3
	v_or_b32_e32 v0, s2, v64
	s_load_dwordx2 s[2:3], s[12:13], 0x140
	s_nop 0
	s_load_dwordx2 s[12:13], s[12:13], 0x178
	v_lshlrev_b64 v[0:1], 1, v[0:1]
	s_waitcnt lgkmcnt(0)
	v_lshl_add_u64 v[2:3], s[2:3], 0, v[0:1]
	v_lshl_add_u64 v[4:5], s[12:13], 0, v[0:1]
	v_lshl_add_u64 v[0:1], v[2:3], 0, v[66:67]
	global_load_dwordx2 v[10:11], v[0:1], off
	v_lshl_add_u64 v[0:1], v[2:3], 0, v[68:69]
	global_load_dwordx2 v[12:13], v[0:1], off
	v_lshl_add_u64 v[0:1], v[2:3], 0, v[70:71]
	global_load_dwordx2 v[14:15], v[0:1], off
	v_lshl_add_u64 v[0:1], v[2:3], 0, v[72:73]
	global_load_dwordx2 v[16:17], v[0:1], off
	v_lshl_add_u64 v[0:1], v[2:3], 0, v[74:75]
	global_load_dwordx2 v[18:19], v[0:1], off
	v_lshl_add_u64 v[0:1], v[2:3], 0, v[76:77]
	global_load_dwordx2 v[20:21], v[0:1], off
	v_lshl_add_u64 v[0:1], v[2:3], 0, v[78:79]
	global_load_dwordx2 v[22:23], v[0:1], off
	v_lshl_add_u64 v[0:1], v[2:3], 0, v[82:83]
	global_load_dwordx2 v[24:25], v[0:1], off
	v_add_u32_e32 v0, v65, v81
	ds_read_b128 v[6:9], v0
	s_mov_b32 s2, 0x3fd744fd
	s_waitcnt vmcnt(7)
	v_lshlrev_b32_e32 v26, 16, v10
	v_and_b32_e32 v27, 0xffff0000, v10
	s_waitcnt lgkmcnt(0)
	v_pk_fma_f32 v[6:7], v[26:27], s[2:3], v[6:7] op_sel_hi:[1,0,1]
	v_lshlrev_b32_e32 v10, 16, v11
	v_bfe_u32 v1, v6, 16, 1
	v_and_b32_e32 v11, 0xffff0000, v11
	v_add3_u32 v1, v6, v1, s33
	v_bfe_u32 v6, v7, 16, 1
	v_pk_fma_f32 v[8:9], v[10:11], s[2:3], v[8:9] op_sel_hi:[1,0,1]
	v_add3_u32 v6, v7, v6, s33
	v_lshrrev_b32_e32 v1, 16, v1
	v_and_or_b32 v6, v6, s29, v1
	v_bfe_u32 v1, v8, 16, 1
	v_add3_u32 v1, v8, v1, s33
	v_bfe_u32 v7, v9, 16, 1
	v_add3_u32 v7, v9, v7, s33
	v_lshrrev_b32_e32 v1, 16, v1
	v_and_or_b32 v7, v7, s29, v1
	v_lshl_add_u64 v[8:9], v[4:5], 0, v[66:67]
	global_store_dwordx2 v[8:9], v[6:7], off
	ds_read_b128 v[6:9], v0 offset:4224
	s_waitcnt vmcnt(7)
	v_lshlrev_b32_e32 v10, 16, v12
	v_and_b32_e32 v11, 0xffff0000, v12
	v_lshlrev_b32_e32 v12, 16, v13
	v_and_b32_e32 v13, 0xffff0000, v13
	s_waitcnt lgkmcnt(0)
	v_pk_fma_f32 v[6:7], v[10:11], s[2:3], v[6:7] op_sel_hi:[1,0,1]
	v_pk_fma_f32 v[8:9], v[12:13], s[2:3], v[8:9] op_sel_hi:[1,0,1]
	v_bfe_u32 v1, v6, 16, 1
	v_add3_u32 v1, v6, v1, s33
	v_bfe_u32 v6, v7, 16, 1
	v_add3_u32 v6, v7, v6, s33
	v_lshrrev_b32_e32 v1, 16, v1
	v_and_or_b32 v6, v6, s29, v1
	v_bfe_u32 v1, v8, 16, 1
	v_add3_u32 v1, v8, v1, s33
	v_bfe_u32 v7, v9, 16, 1
	v_add3_u32 v7, v9, v7, s33
	v_lshrrev_b32_e32 v1, 16, v1
	v_and_or_b32 v7, v7, s29, v1
	v_lshl_add_u64 v[8:9], v[4:5], 0, v[68:69]
	global_store_dwordx2 v[8:9], v[6:7], off
	ds_read_b128 v[6:9], v0 offset:8448
	s_waitcnt vmcnt(7)
	v_lshlrev_b32_e32 v10, 16, v14
	v_and_b32_e32 v11, 0xffff0000, v14
	v_lshlrev_b32_e32 v12, 16, v15
	v_and_b32_e32 v13, 0xffff0000, v15
	s_waitcnt lgkmcnt(0)
	v_pk_fma_f32 v[6:7], v[10:11], s[2:3], v[6:7] op_sel_hi:[1,0,1]
	v_pk_fma_f32 v[8:9], v[12:13], s[2:3], v[8:9] op_sel_hi:[1,0,1]
	v_bfe_u32 v1, v6, 16, 1
	v_add3_u32 v1, v6, v1, s33
	v_bfe_u32 v6, v7, 16, 1
	v_add3_u32 v6, v7, v6, s33
	v_lshrrev_b32_e32 v1, 16, v1
	v_and_or_b32 v6, v6, s29, v1
	v_bfe_u32 v1, v8, 16, 1
	v_add3_u32 v1, v8, v1, s33
	v_bfe_u32 v7, v9, 16, 1
	v_add3_u32 v7, v9, v7, s33
	v_lshrrev_b32_e32 v1, 16, v1
	v_and_or_b32 v7, v7, s29, v1
	v_lshl_add_u64 v[8:9], v[4:5], 0, v[70:71]
	global_store_dwordx2 v[8:9], v[6:7], off
	ds_read_b128 v[6:9], v0 offset:12672
	s_waitcnt vmcnt(7)
	v_lshlrev_b32_e32 v10, 16, v16
	v_and_b32_e32 v11, 0xffff0000, v16
	v_lshlrev_b32_e32 v12, 16, v17
	v_and_b32_e32 v13, 0xffff0000, v17
	s_waitcnt lgkmcnt(0)
	v_pk_fma_f32 v[6:7], v[10:11], s[2:3], v[6:7] op_sel_hi:[1,0,1]
	v_pk_fma_f32 v[8:9], v[12:13], s[2:3], v[8:9] op_sel_hi:[1,0,1]
	v_bfe_u32 v1, v6, 16, 1
	v_add3_u32 v1, v6, v1, s33
	v_bfe_u32 v6, v7, 16, 1
	v_add3_u32 v6, v7, v6, s33
	v_lshrrev_b32_e32 v1, 16, v1
	v_and_or_b32 v6, v6, s29, v1
	v_bfe_u32 v1, v8, 16, 1
	v_add3_u32 v1, v8, v1, s33
	v_bfe_u32 v7, v9, 16, 1
	v_add3_u32 v7, v9, v7, s33
	v_lshrrev_b32_e32 v1, 16, v1
	v_and_or_b32 v7, v7, s29, v1
	v_lshl_add_u64 v[8:9], v[4:5], 0, v[72:73]
	global_store_dwordx2 v[8:9], v[6:7], off
	ds_read_b128 v[6:9], v0 offset:16896
	s_waitcnt vmcnt(7)
	v_lshlrev_b32_e32 v10, 16, v18
	v_and_b32_e32 v11, 0xffff0000, v18
	v_lshlrev_b32_e32 v12, 16, v19
	v_and_b32_e32 v13, 0xffff0000, v19
	s_waitcnt lgkmcnt(0)
	v_pk_fma_f32 v[6:7], v[10:11], s[2:3], v[6:7] op_sel_hi:[1,0,1]
	v_pk_fma_f32 v[8:9], v[12:13], s[2:3], v[8:9] op_sel_hi:[1,0,1]
	v_bfe_u32 v1, v6, 16, 1
	v_add3_u32 v1, v6, v1, s33
	v_bfe_u32 v6, v7, 16, 1
	v_add3_u32 v6, v7, v6, s33
	v_lshrrev_b32_e32 v1, 16, v1
	v_and_or_b32 v6, v6, s29, v1
	v_bfe_u32 v1, v8, 16, 1
	v_add3_u32 v1, v8, v1, s33
	v_bfe_u32 v7, v9, 16, 1
	v_add3_u32 v7, v9, v7, s33
	v_lshrrev_b32_e32 v1, 16, v1
	v_and_or_b32 v7, v7, s29, v1
	v_lshl_add_u64 v[8:9], v[4:5], 0, v[74:75]
	global_store_dwordx2 v[8:9], v[6:7], off
	ds_read_b128 v[6:9], v0 offset:21120
	s_waitcnt vmcnt(7)
	v_lshlrev_b32_e32 v10, 16, v20
	v_and_b32_e32 v11, 0xffff0000, v20
	v_lshlrev_b32_e32 v12, 16, v21
	v_and_b32_e32 v13, 0xffff0000, v21
	s_waitcnt lgkmcnt(0)
	v_pk_fma_f32 v[6:7], v[10:11], s[2:3], v[6:7] op_sel_hi:[1,0,1]
	v_pk_fma_f32 v[8:9], v[12:13], s[2:3], v[8:9] op_sel_hi:[1,0,1]
	v_bfe_u32 v1, v6, 16, 1
	v_add3_u32 v1, v6, v1, s33
	v_bfe_u32 v6, v7, 16, 1
	v_add3_u32 v6, v7, v6, s33
	v_lshrrev_b32_e32 v1, 16, v1
	v_and_or_b32 v6, v6, s29, v1
	v_bfe_u32 v1, v8, 16, 1
	v_add3_u32 v1, v8, v1, s33
	v_bfe_u32 v7, v9, 16, 1
	v_add3_u32 v7, v9, v7, s33
	v_lshrrev_b32_e32 v1, 16, v1
	v_and_or_b32 v7, v7, s29, v1
	v_lshl_add_u64 v[8:9], v[4:5], 0, v[76:77]
	global_store_dwordx2 v[8:9], v[6:7], off
	ds_read_b128 v[6:9], v0 offset:25344
	s_waitcnt vmcnt(7)
	v_lshlrev_b32_e32 v10, 16, v22
	v_and_b32_e32 v11, 0xffff0000, v22
	v_lshlrev_b32_e32 v12, 16, v23
	v_and_b32_e32 v13, 0xffff0000, v23
	s_waitcnt lgkmcnt(0)
	v_pk_fma_f32 v[6:7], v[10:11], s[2:3], v[6:7] op_sel_hi:[1,0,1]
	v_pk_fma_f32 v[8:9], v[12:13], s[2:3], v[8:9] op_sel_hi:[1,0,1]
	v_bfe_u32 v1, v6, 16, 1
	v_add3_u32 v1, v6, v1, s33
	v_bfe_u32 v6, v7, 16, 1
	v_add3_u32 v6, v7, v6, s33
	v_lshrrev_b32_e32 v1, 16, v1
	v_and_or_b32 v6, v6, s29, v1
	v_bfe_u32 v1, v8, 16, 1
	v_add3_u32 v1, v8, v1, s33
	v_bfe_u32 v7, v9, 16, 1
	v_add3_u32 v7, v9, v7, s33
	v_lshrrev_b32_e32 v1, 16, v1
	v_and_or_b32 v7, v7, s29, v1
	v_lshl_add_u64 v[8:9], v[4:5], 0, v[78:79]
	global_store_dwordx2 v[8:9], v[6:7], off
	ds_read_b128 v[6:9], v0 offset:29568
	s_waitcnt vmcnt(7)
	v_lshlrev_b32_e32 v10, 16, v24
	v_and_b32_e32 v11, 0xffff0000, v24
	v_lshlrev_b32_e32 v12, 16, v25
	v_and_b32_e32 v13, 0xffff0000, v25
	s_waitcnt lgkmcnt(0)
	v_pk_fma_f32 v[6:7], v[10:11], s[2:3], v[6:7] op_sel_hi:[1,0,1]
	v_pk_fma_f32 v[8:9], v[12:13], s[2:3], v[8:9] op_sel_hi:[1,0,1]
	v_bfe_u32 v1, v6, 16, 1
	v_add3_u32 v1, v6, v1, s33
	v_bfe_u32 v6, v7, 16, 1
	v_add3_u32 v6, v7, v6, s33
	v_lshrrev_b32_e32 v1, 16, v1
	v_and_or_b32 v6, v6, s29, v1
	v_bfe_u32 v1, v8, 16, 1
	v_add3_u32 v1, v8, v1, s33
	v_bfe_u32 v7, v9, 16, 1
	v_add3_u32 v7, v9, v7, s33
	v_lshrrev_b32_e32 v1, 16, v1
	v_and_or_b32 v7, v7, s29, v1
	v_lshl_add_u64 v[8:9], v[4:5], 0, v[82:83]
	global_store_dwordx2 v[8:9], v[6:7], off
	v_lshl_add_u64 v[6:7], v[2:3], 0, v[84:85]
	global_load_dwordx2 v[12:13], v[6:7], off
	v_lshl_add_u64 v[6:7], v[2:3], 0, v[86:87]
	global_load_dwordx2 v[14:15], v[6:7], off
	v_lshl_add_u64 v[6:7], v[2:3], 0, v[88:89]
	global_load_dwordx2 v[16:17], v[6:7], off
	v_lshl_add_u64 v[6:7], v[2:3], 0, v[90:91]
	global_load_dwordx2 v[18:19], v[6:7], off
	v_lshl_add_u64 v[6:7], v[2:3], 0, v[92:93]
	global_load_dwordx2 v[20:21], v[6:7], off
	v_lshl_add_u64 v[6:7], v[2:3], 0, v[94:95]
	global_load_dwordx2 v[22:23], v[6:7], off
	ds_read_b128 v[8:11], v119
	v_lshl_add_u64 v[6:7], v[2:3], 0, v[96:97]
	global_load_dwordx2 v[24:25], v[6:7], off
	v_lshl_add_u64 v[2:3], v[2:3], 0, v[98:99]
	global_load_dwordx2 v[6:7], v[2:3], off
	s_waitcnt vmcnt(7)
	v_lshlrev_b32_e32 v2, 16, v12
	v_and_b32_e32 v3, 0xffff0000, v12
	s_waitcnt lgkmcnt(0)
	v_pk_fma_f32 v[2:3], v[2:3], s[2:3], v[8:9] op_sel_hi:[1,0,1]
	v_lshlrev_b32_e32 v12, 16, v13
	v_bfe_u32 v1, v2, 16, 1
	v_and_b32_e32 v13, 0xffff0000, v13
	v_add3_u32 v1, v2, v1, s33
	v_bfe_u32 v2, v3, 16, 1
	v_pk_fma_f32 v[10:11], v[12:13], s[2:3], v[10:11] op_sel_hi:[1,0,1]
	v_add3_u32 v2, v3, v2, s33
	v_lshrrev_b32_e32 v1, 16, v1
	v_and_or_b32 v2, v2, s29, v1
	v_bfe_u32 v1, v10, 16, 1
	v_add3_u32 v1, v10, v1, s33
	v_bfe_u32 v3, v11, 16, 1
	v_add3_u32 v3, v11, v3, s33
	v_lshrrev_b32_e32 v1, 16, v1
	v_and_or_b32 v3, v3, s29, v1
	v_lshl_add_u64 v[8:9], v[4:5], 0, v[84:85]
	global_store_dwordx2 v[8:9], v[2:3], off
	ds_read_b128 v[8:11], v0 offset:38016
	s_waitcnt vmcnt(7)
	v_lshlrev_b32_e32 v2, 16, v14
	v_and_b32_e32 v3, 0xffff0000, v14
	v_lshlrev_b32_e32 v12, 16, v15
	v_and_b32_e32 v13, 0xffff0000, v15
	s_waitcnt lgkmcnt(0)
	v_pk_fma_f32 v[2:3], v[2:3], s[2:3], v[8:9] op_sel_hi:[1,0,1]
	v_pk_fma_f32 v[10:11], v[12:13], s[2:3], v[10:11] op_sel_hi:[1,0,1]
	v_bfe_u32 v1, v2, 16, 1
	v_add3_u32 v1, v2, v1, s33
	v_bfe_u32 v2, v3, 16, 1
	v_add3_u32 v2, v3, v2, s33
	v_lshrrev_b32_e32 v1, 16, v1
	v_and_or_b32 v2, v2, s29, v1
	v_bfe_u32 v1, v10, 16, 1
	v_add3_u32 v1, v10, v1, s33
	v_bfe_u32 v3, v11, 16, 1
	v_add3_u32 v3, v11, v3, s33
	v_lshrrev_b32_e32 v1, 16, v1
	v_and_or_b32 v3, v3, s29, v1
	v_lshl_add_u64 v[8:9], v[4:5], 0, v[86:87]
	global_store_dwordx2 v[8:9], v[2:3], off
	ds_read_b128 v[8:11], v0 offset:42240
	s_waitcnt vmcnt(7)
	v_lshlrev_b32_e32 v2, 16, v16
	v_and_b32_e32 v3, 0xffff0000, v16
	v_lshlrev_b32_e32 v12, 16, v17
	v_and_b32_e32 v13, 0xffff0000, v17
	s_waitcnt lgkmcnt(0)
	v_pk_fma_f32 v[2:3], v[2:3], s[2:3], v[8:9] op_sel_hi:[1,0,1]
	v_pk_fma_f32 v[10:11], v[12:13], s[2:3], v[10:11] op_sel_hi:[1,0,1]
	v_bfe_u32 v1, v2, 16, 1
	v_add3_u32 v1, v2, v1, s33
	v_bfe_u32 v2, v3, 16, 1
	v_add3_u32 v2, v3, v2, s33
	v_lshrrev_b32_e32 v1, 16, v1
	v_and_or_b32 v2, v2, s29, v1
	v_bfe_u32 v1, v10, 16, 1
	v_add3_u32 v1, v10, v1, s33
	v_bfe_u32 v3, v11, 16, 1
	v_add3_u32 v3, v11, v3, s33
	v_lshrrev_b32_e32 v1, 16, v1
	v_and_or_b32 v3, v3, s29, v1
	v_lshl_add_u64 v[8:9], v[4:5], 0, v[88:89]
	global_store_dwordx2 v[8:9], v[2:3], off
	ds_read_b128 v[8:11], v0 offset:46464
	s_waitcnt vmcnt(7)
	v_lshlrev_b32_e32 v2, 16, v18
	v_and_b32_e32 v3, 0xffff0000, v18
	v_lshlrev_b32_e32 v12, 16, v19
	v_and_b32_e32 v13, 0xffff0000, v19
	s_waitcnt lgkmcnt(0)
	v_pk_fma_f32 v[2:3], v[2:3], s[2:3], v[8:9] op_sel_hi:[1,0,1]
	v_pk_fma_f32 v[10:11], v[12:13], s[2:3], v[10:11] op_sel_hi:[1,0,1]
	v_bfe_u32 v1, v2, 16, 1
	v_add3_u32 v1, v2, v1, s33
	v_bfe_u32 v2, v3, 16, 1
	v_add3_u32 v2, v3, v2, s33
	v_lshrrev_b32_e32 v1, 16, v1
	v_and_or_b32 v2, v2, s29, v1
	v_bfe_u32 v1, v10, 16, 1
	v_add3_u32 v1, v10, v1, s33
	v_bfe_u32 v3, v11, 16, 1
	v_add3_u32 v3, v11, v3, s33
	v_lshrrev_b32_e32 v1, 16, v1
	v_and_or_b32 v3, v3, s29, v1
	v_lshl_add_u64 v[8:9], v[4:5], 0, v[90:91]
	global_store_dwordx2 v[8:9], v[2:3], off
	ds_read_b128 v[8:11], v0 offset:50688
	s_waitcnt vmcnt(7)
	v_lshlrev_b32_e32 v2, 16, v20
	v_and_b32_e32 v3, 0xffff0000, v20
	v_lshlrev_b32_e32 v12, 16, v21
	v_and_b32_e32 v13, 0xffff0000, v21
	s_waitcnt lgkmcnt(0)
	v_pk_fma_f32 v[2:3], v[2:3], s[2:3], v[8:9] op_sel_hi:[1,0,1]
	v_pk_fma_f32 v[10:11], v[12:13], s[2:3], v[10:11] op_sel_hi:[1,0,1]
	v_bfe_u32 v1, v2, 16, 1
	v_add3_u32 v1, v2, v1, s33
	v_bfe_u32 v2, v3, 16, 1
	v_add3_u32 v2, v3, v2, s33
	v_lshrrev_b32_e32 v1, 16, v1
	v_and_or_b32 v2, v2, s29, v1
	v_bfe_u32 v1, v10, 16, 1
	v_add3_u32 v1, v10, v1, s33
	v_bfe_u32 v3, v11, 16, 1
	v_add3_u32 v3, v11, v3, s33
	v_lshrrev_b32_e32 v1, 16, v1
	v_and_or_b32 v3, v3, s29, v1
	v_lshl_add_u64 v[8:9], v[4:5], 0, v[92:93]
	global_store_dwordx2 v[8:9], v[2:3], off
	ds_read_b128 v[8:11], v0 offset:54912
	s_waitcnt vmcnt(7)
	v_lshlrev_b32_e32 v2, 16, v22
	v_and_b32_e32 v3, 0xffff0000, v22
	v_lshlrev_b32_e32 v12, 16, v23
	v_and_b32_e32 v13, 0xffff0000, v23
	s_waitcnt lgkmcnt(0)
	v_pk_fma_f32 v[2:3], v[2:3], s[2:3], v[8:9] op_sel_hi:[1,0,1]
	v_pk_fma_f32 v[10:11], v[12:13], s[2:3], v[10:11] op_sel_hi:[1,0,1]
	v_bfe_u32 v1, v2, 16, 1
	v_add3_u32 v1, v2, v1, s33
	v_bfe_u32 v2, v3, 16, 1
	v_add3_u32 v2, v3, v2, s33
	v_lshrrev_b32_e32 v1, 16, v1
	v_and_or_b32 v2, v2, s29, v1
	v_bfe_u32 v1, v10, 16, 1
	v_add3_u32 v1, v10, v1, s33
	v_bfe_u32 v3, v11, 16, 1
	v_add3_u32 v3, v11, v3, s33
	v_lshrrev_b32_e32 v1, 16, v1
	v_and_or_b32 v3, v3, s29, v1
	v_lshl_add_u64 v[8:9], v[4:5], 0, v[94:95]
	global_store_dwordx2 v[8:9], v[2:3], off
	ds_read_b128 v[8:11], v0 offset:59136
	s_waitcnt vmcnt(7)
	v_lshlrev_b32_e32 v2, 16, v24
	v_and_b32_e32 v3, 0xffff0000, v24
	v_lshlrev_b32_e32 v12, 16, v25
	v_and_b32_e32 v13, 0xffff0000, v25
	s_waitcnt lgkmcnt(0)
	v_pk_fma_f32 v[2:3], v[2:3], s[2:3], v[8:9] op_sel_hi:[1,0,1]
	v_pk_fma_f32 v[10:11], v[12:13], s[2:3], v[10:11] op_sel_hi:[1,0,1]
	v_bfe_u32 v1, v2, 16, 1
	v_add3_u32 v1, v2, v1, s33
	v_bfe_u32 v2, v3, 16, 1
	v_add3_u32 v2, v3, v2, s33
	v_lshrrev_b32_e32 v1, 16, v1
	v_and_or_b32 v2, v2, s29, v1
	v_bfe_u32 v1, v10, 16, 1
	v_add3_u32 v1, v10, v1, s33
	v_bfe_u32 v3, v11, 16, 1
	v_add3_u32 v3, v11, v3, s33
	v_lshrrev_b32_e32 v1, 16, v1
	v_and_or_b32 v3, v3, s29, v1
	v_lshl_add_u64 v[8:9], v[4:5], 0, v[96:97]
	global_store_dwordx2 v[8:9], v[2:3], off
	ds_read_b128 v[0:3], v0 offset:63360
	s_waitcnt vmcnt(7)
	v_lshlrev_b32_e32 v8, 16, v6
	v_and_b32_e32 v9, 0xffff0000, v6
	v_lshlrev_b32_e32 v6, 16, v7
	v_and_b32_e32 v7, 0xffff0000, v7
	s_waitcnt lgkmcnt(0)
	v_pk_fma_f32 v[0:1], v[8:9], s[2:3], v[0:1] op_sel_hi:[1,0,1]
	v_pk_fma_f32 v[2:3], v[6:7], s[2:3], v[2:3] op_sel_hi:[1,0,1]
	v_bfe_u32 v6, v0, 16, 1
	v_add3_u32 v0, v0, v6, s33
	v_bfe_u32 v6, v1, 16, 1
	v_add3_u32 v1, v1, v6, s33
	v_lshrrev_b32_e32 v0, 16, v0
	v_and_or_b32 v0, v1, s29, v0
	v_bfe_u32 v1, v2, 16, 1
	v_readlane_b32 s2, v249, 7
	v_add3_u32 v1, v2, v1, s33
	v_bfe_u32 v2, v3, 16, 1
	s_add_i32 s14, s14, s2
	v_readlane_b32 s2, v249, 9
	v_add3_u32 v2, v3, v2, s33
	v_lshrrev_b32_e32 v1, 16, v1
	s_sub_i32 s17, s17, s2
	v_and_or_b32 v1, v2, s29, v1
	v_lshl_add_u64 v[2:3], v[4:5], 0, v[98:99]
	s_cmpk_gt_i32 s14, 0x41f
	global_store_dwordx2 v[2:3], v[0:1], off
	s_barrier
	v_readlane_b32 s3, v249, 8
	s_cbranch_scc0 .LBB0_49
.LBB0_52:
	v_readlane_b32 s0, v249, 3
	v_readlane_b32 s1, v249, 4
	s_load_dword s2, s[0:1], 0x10
	s_load_dword s8, s[0:1], 0x0
	v_readlane_b32 s3, v249, 0
	s_mov_b32 s14, s3
	v_readlane_b32 s0, v249, 30
	s_waitcnt lgkmcnt(0)
	s_lshr_b32 s2, s2, 16
	s_cmp_lg_u32 s2, 0
	s_cselect_b64 s[2:3], -1, 0
	s_cmp_lg_u64 s[2:3], 0
	v_readlane_b32 s2, v249, 19
	v_readlane_b32 s3, v249, 20
	s_addc_u32 s2, s8, 0
	s_movk_i32 s30, 0x420
.Lmodl_op:
	s_cmp_ge_u32 s30, s2
	s_cbranch_scc0 .Lmodd_op
	s_sub_u32 s30, s30, s2
	s_branch .Lmodl_op
.Lmodd_op:
	s_lshr_b32 s31, s2, 2
	s_cmp_gt_u32 s30, s31
	s_cselect_b32 s30, 0, s30
	s_sub_u32 s2, s2, s30
	s_cmp_lt_u32 s14, s30
	s_cbranch_scc1 .LBB0_67
	s_sub_u32 s14, s14, s30
	v_readlane_b32 s1, v249, 31
	v_writelane_b32 v249, s2, 19
	s_load_dwordx2 s[0:1], s[0:1], 0x160
	s_ashr_i32 s15, s14, 31
	v_writelane_b32 v249, s3, 20
	s_lshl_b64 s[2:3], s[2:3], 8
	s_lshl_b64 s[8:9], s[14:15], 8
	v_readlane_b32 s10, v249, 43
	v_readlane_b32 s11, v249, 44
	s_add_u32 s8, s8, s10
	v_mov_b32_e32 v0, v220
	s_addc_u32 s9, s9, s11
	s_nop 0
	v_ashrrev_i32_e32 v1, 31, v0
	s_waitcnt vmcnt(0)
	v_lshl_add_u64 v[74:75], s[8:9], 0, v[0:1]
	v_cmp_gt_u64_e32 vcc, s[6:7], v[74:75]
	s_and_saveexec_b64 s[8:9], vcc
	s_cbranch_execz .LBB0_59
	v_readlane_b32 s10, v249, 30
	v_readlane_b32 s11, v249, 31
	s_load_dwordx2 s[12:13], s[10:11], 0xb8
	v_readlane_b32 s16, v249, 37
	v_readlane_b32 s17, v249, 38
	s_lshl_b64 s[10:11], s[14:15], 15
	s_lshl_b64 s[16:17], s[16:17], 26
	s_waitcnt lgkmcnt(0)
	s_add_u32 s12, s12, s16
	v_add_u32_e32 v2, 11, v0
	v_lshlrev_b64 v[0:1], 7, v[0:1]
	s_addc_u32 s13, s13, s17
	v_readlane_b32 s16, v249, 19
	v_lshl_add_u64 v[0:1], s[12:13], 0, v[0:1]
	s_mov_b64 s[12:13], 0x15555c0
	v_readlane_b32 s17, v249, 20
	v_lshl_add_u64 v[70:71], v[0:1], 0, s[12:13]
	s_lshl_b64 s[12:13], s[16:17], 16
	v_and_b32_e32 v2, 31, v2
	s_add_u32 s14, s14, s16
	v_mul_u32_u24_e32 v2, 24, v2
	v_mov_b32_e32 v3, v80
	s_addc_u32 s15, s15, 0
	v_lshl_add_u64 v[68:69], s[0:1], 0, v[2:3]
	s_lshl_b64 s[14:15], s[14:15], 15
	s_mov_b64 s[16:17], 0
	s_branch .LBB0_55

.LBB0_59:
	s_or_b64 exec, exec, s[8:9]
	v_readlane_b32 s8, v249, 0
	s_sub_u32 s16, s8, s30
	s_ashr_i32 s17, s16, 31
	s_lshl_b64 s[8:9], s[16:17], 8
	v_readlane_b32 s10, v249, 43
	v_readlane_b32 s11, v249, 44
	s_add_u32 s8, s8, s10
	v_mov_b32_e32 v0, v220
	s_addc_u32 s9, s9, s11
	s_nop 0
	v_ashrrev_i32_e32 v1, 31, v0
	v_lshl_add_u64 v[70:71], s[8:9], 0, v[0:1]
	v_cmp_gt_u64_e32 vcc, s[6:7], v[70:71]
	s_and_saveexec_b64 s[8:9], vcc
	s_cbranch_execz .LBB0_66
	v_readlane_b32 s10, v249, 30
	v_readlane_b32 s11, v249, 31
	s_load_dwordx2 s[14:15], s[10:11], 0xc0
	v_readlane_b32 s20, v249, 19
	v_readlane_b32 s18, v249, 37
	v_readlane_b32 s21, v249, 20
	v_readlane_b32 s19, v249, 38
	s_lshl_b64 s[10:11], s[20:21], 13
	s_lshl_b64 s[12:13], s[16:17], 15
	s_lshl_b64 s[18:19], s[18:19], 26
	s_waitcnt lgkmcnt(0)
	s_add_u32 s14, s14, s18
	v_lshlrev_b64 v[0:1], 7, v[0:1]
	s_addc_u32 s15, s15, s19
	v_lshl_add_u64 v[0:1], s[14:15], 0, v[0:1]
	s_mov_b64 s[14:15], 0x15555c0
	v_lshl_add_u64 v[66:67], v[0:1], 0, s[14:15]
	s_lshl_b64 s[14:15], s[20:21], 16
	s_add_u32 s16, s16, s20
	s_addc_u32 s17, s17, 0
	v_lshlrev_b64 v[64:65], 4, v[70:71]
	s_lshl_b64 s[16:17], s[16:17], 15
	s_mov_b64 s[18:19], 0
	s_branch .LBB0_62

.LBB0_353:
	s_and_b32 s15, s14, 0x8000
	s_waitcnt vmcnt(8)
	s_barrier
	v_add_u32_e32 v93, s15, v91
	v_or_b32_e32 v128, s15, v65
	ds_read_b128 v[94:97], v93
	ds_read_b128 v[98:101], v93 offset:2048
	ds_read_b128 v[102:105], v93 offset:4096
	ds_read_b128 v[106:109], v93 offset:6144
	ds_read_b128 v[110:113], v128 offset:16384
	ds_read_b128 v[116:119], v128 offset:18432
	ds_read_b128 v[120:123], v128 offset:20480
	ds_read_b128 v[124:127], v128 offset:22528
	s_waitcnt lgkmcnt(0)
	v_mfma_f32_16x16x32_bf16 v[60:63], v[94:97], v[110:113], v[60:63]
	v_mfma_f32_16x16x32_bf16 v[56:59], v[94:97], v[116:119], v[56:59]
	v_mfma_f32_16x16x32_bf16 v[52:55], v[94:97], v[120:123], v[52:55]
	v_mfma_f32_16x16x32_bf16 v[48:51], v[94:97], v[124:127], v[48:51]
	v_mfma_f32_16x16x32_bf16 v[44:47], v[98:101], v[110:113], v[44:47]
	v_mfma_f32_16x16x32_bf16 v[40:43], v[98:101], v[116:119], v[40:43]
	v_mfma_f32_16x16x32_bf16 v[36:39], v[98:101], v[120:123], v[36:39]
	v_mfma_f32_16x16x32_bf16 v[32:35], v[98:101], v[124:127], v[32:35]
	v_mfma_f32_16x16x32_bf16 v[28:31], v[102:105], v[110:113], v[28:31]
	v_mfma_f32_16x16x32_bf16 v[24:27], v[102:105], v[116:119], v[24:27]
	v_mfma_f32_16x16x32_bf16 v[20:23], v[102:105], v[120:123], v[20:23]
	v_mfma_f32_16x16x32_bf16 v[16:19], v[102:105], v[124:127], v[16:19]
	v_mfma_f32_16x16x32_bf16 v[12:15], v[106:109], v[110:113], v[12:15]
	v_mfma_f32_16x16x32_bf16 v[8:11], v[106:109], v[116:119], v[8:11]
	v_mfma_f32_16x16x32_bf16 v[4:7], v[106:109], v[120:123], v[4:7]
	v_mfma_f32_16x16x32_bf16 v[0:3], v[106:109], v[124:127], v[0:3]
	ds_read_b128 v[94:97], v93 offset:1024
	ds_read_b128 v[98:101], v93 offset:3072
	ds_read_b128 v[102:105], v93 offset:5120
	ds_read_b128 v[106:109], v93 offset:7168
	ds_read_b128 v[110:113], v128 offset:17408
	ds_read_b128 v[116:119], v128 offset:19456
	ds_read_b128 v[120:123], v128 offset:21504
	ds_read_b128 v[124:127], v128 offset:23552
	v_add_u32_e32 v93, s15, v92
	s_waitcnt lgkmcnt(0)
	s_waitcnt lgkmcnt(3)
	v_mfma_f32_16x16x32_bf16 v[60:63], v[94:97], v[110:113], v[60:63]
	v_readfirstlane_b32 s15, v93
	s_barrier
	s_waitcnt lgkmcnt(2)
	v_mfma_f32_16x16x32_bf16 v[56:59], v[94:97], v[116:119], v[56:59]
	s_mov_b32 m0, s15
	s_waitcnt lgkmcnt(1)
	v_mfma_f32_16x16x32_bf16 v[52:55], v[94:97], v[120:123], v[52:55]
	s_waitcnt lgkmcnt(0)
	v_mfma_f32_16x16x32_bf16 v[48:51], v[94:97], v[124:127], v[48:51]
	v_add_u32_e32 v96, 0x1000, v93
	v_lshl_add_u64 v[94:95], v[82:83], 0, s[2:3]
	v_readfirstlane_b32 s15, v96
	v_add_u32_e32 v96, 0x2000, v93
	global_load_lds_dwordx4 v[94:95], off
	v_lshl_add_u64 v[94:95], v[78:79], 0, s[2:3]
	s_mov_b32 m0, s15
	v_readfirstlane_b32 s15, v96
	v_add_u32_e32 v96, 0x3000, v93
	global_load_lds_dwordx4 v[94:95], off
	v_lshl_add_u64 v[94:95], v[76:77], 0, s[2:3]
	s_mov_b32 m0, s15
	v_readfirstlane_b32 s15, v96
	v_add_u32_e32 v96, 0x4000, v93
	global_load_lds_dwordx4 v[94:95], off
	v_lshl_add_u64 v[94:95], v[74:75], 0, s[2:3]
	s_mov_b32 m0, s15
	v_readfirstlane_b32 s15, v96
	v_add_u32_e32 v96, 0x5000, v93
	global_load_lds_dwordx4 v[94:95], off
	v_lshl_add_u64 v[94:95], v[72:73], 0, s[2:3]
	s_mov_b32 m0, s15
	v_readfirstlane_b32 s15, v96
	v_add_u32_e32 v96, 0x6000, v93
	global_load_lds_dwordx4 v[94:95], off
	v_lshl_add_u64 v[94:95], v[70:71], 0, s[2:3]
	s_mov_b32 m0, s15
	v_readfirstlane_b32 s15, v96
	v_add_u32_e32 v93, 0x7000, v93
	global_load_lds_dwordx4 v[94:95], off
	v_lshl_add_u64 v[94:95], v[68:69], 0, s[2:3]
	s_mov_b32 m0, s15
	v_readfirstlane_b32 s15, v93
	global_load_lds_dwordx4 v[94:95], off
	v_lshl_add_u64 v[94:95], v[66:67], 0, s[2:3]
	s_mov_b32 m0, s15
	v_mfma_f32_16x16x32_bf16 v[44:47], v[98:101], v[110:113], v[44:47]
	global_load_lds_dwordx4 v[94:95], off
	s_add_u32 s2, s2, 0x80
	v_mfma_f32_16x16x32_bf16 v[40:43], v[98:101], v[116:119], v[40:43]
	s_addc_u32 s3, s3, 0
	s_add_i32 s14, s14, 0x8000
	s_cmpk_lg_i32 s2, 0x700
	v_mfma_f32_16x16x32_bf16 v[36:39], v[98:101], v[120:123], v[36:39]
	v_mfma_f32_16x16x32_bf16 v[32:35], v[98:101], v[124:127], v[32:35]
	v_mfma_f32_16x16x32_bf16 v[28:31], v[102:105], v[110:113], v[28:31]
	v_mfma_f32_16x16x32_bf16 v[24:27], v[102:105], v[116:119], v[24:27]
	v_mfma_f32_16x16x32_bf16 v[20:23], v[102:105], v[120:123], v[20:23]
	v_mfma_f32_16x16x32_bf16 v[16:19], v[102:105], v[124:127], v[16:19]
	v_mfma_f32_16x16x32_bf16 v[12:15], v[106:109], v[110:113], v[12:15]
	v_mfma_f32_16x16x32_bf16 v[8:11], v[106:109], v[116:119], v[8:11]
	v_mfma_f32_16x16x32_bf16 v[4:7], v[106:109], v[120:123], v[4:7]
	v_mfma_f32_16x16x32_bf16 v[0:3], v[106:109], v[124:127], v[0:3]
	s_cbranch_scc1 .LBB0_353
	s_waitcnt vmcnt(8)
	s_barrier
	ds_read_b128 v[66:69], v91
	ds_read_b128 v[70:73], v91 offset:2048
	ds_read_b128 v[74:77], v91 offset:4096
	ds_read_b128 v[92:95], v91 offset:6144
	ds_read_b128 v[96:99], v65 offset:16384
	ds_read_b128 v[100:103], v65 offset:18432
	ds_read_b128 v[104:107], v65 offset:20480
	ds_read_b128 v[108:111], v65 offset:22528
	s_waitcnt lgkmcnt(0)
	v_mfma_f32_16x16x32_bf16 v[60:63], v[66:69], v[96:99], v[60:63]
	s_lshr_b32 s16, s13, 8
	s_and_b32 s2, s31, 0x80
	s_cmpk_lt_u32 s13, 0x100
	v_mfma_f32_16x16x32_bf16 v[56:59], v[66:69], v[100:103], v[56:59]
	v_readlane_b32 s14, v249, 30
	v_readlane_b32 s15, v249, 31
	s_mov_b32 s13, s17
	v_mfma_f32_16x16x32_bf16 v[52:55], v[66:69], v[104:107], v[52:55]
	v_mfma_f32_16x16x32_bf16 v[48:51], v[66:69], v[108:111], v[48:51]
	v_mfma_f32_16x16x32_bf16 v[44:47], v[70:73], v[96:99], v[44:47]
	v_mfma_f32_16x16x32_bf16 v[40:43], v[70:73], v[100:103], v[40:43]
	v_mfma_f32_16x16x32_bf16 v[36:39], v[70:73], v[104:107], v[36:39]
	v_mfma_f32_16x16x32_bf16 v[32:35], v[70:73], v[108:111], v[32:35]
	v_mfma_f32_16x16x32_bf16 v[28:31], v[74:77], v[96:99], v[28:31]
	v_mfma_f32_16x16x32_bf16 v[24:27], v[74:77], v[100:103], v[24:27]
	v_mfma_f32_16x16x32_bf16 v[20:23], v[74:77], v[104:107], v[20:23]
	v_mfma_f32_16x16x32_bf16 v[16:19], v[74:77], v[108:111], v[16:19]
	v_mfma_f32_16x16x32_bf16 v[12:15], v[92:95], v[96:99], v[12:15]
	v_mfma_f32_16x16x32_bf16 v[8:11], v[92:95], v[100:103], v[8:11]
	v_mfma_f32_16x16x32_bf16 v[4:7], v[92:95], v[104:107], v[4:7]
	v_mfma_f32_16x16x32_bf16 v[0:3], v[92:95], v[108:111], v[0:3]
	ds_read_b128 v[66:69], v91 offset:1024
	ds_read_b128 v[70:73], v91 offset:3072
	ds_read_b128 v[74:77], v91 offset:5120
	ds_read_b128 v[92:95], v91 offset:7168
	ds_read_b128 v[96:99], v65 offset:17408
	ds_read_b128 v[100:103], v65 offset:19456
	ds_read_b128 v[104:107], v65 offset:21504
	ds_read_b128 v[108:111], v65 offset:23552
	s_waitcnt lgkmcnt(0)
	s_barrier
	s_waitcnt lgkmcnt(3)
	v_mfma_f32_16x16x32_bf16 v[60:63], v[66:69], v[96:99], v[60:63]
	s_waitcnt vmcnt(0)
	s_barrier
	s_waitcnt lgkmcnt(2)
	v_mfma_f32_16x16x32_bf16 v[56:59], v[66:69], v[100:103], v[56:59]
	s_waitcnt lgkmcnt(1)
	v_mfma_f32_16x16x32_bf16 v[52:55], v[66:69], v[104:107], v[52:55]
	s_waitcnt lgkmcnt(0)
	v_mfma_f32_16x16x32_bf16 v[48:51], v[66:69], v[108:111], v[48:51]
	v_mfma_f32_16x16x32_bf16 v[44:47], v[70:73], v[96:99], v[44:47]
	v_mfma_f32_16x16x32_bf16 v[40:43], v[70:73], v[100:103], v[40:43]
	v_mfma_f32_16x16x32_bf16 v[36:39], v[70:73], v[104:107], v[36:39]
	v_mfma_f32_16x16x32_bf16 v[32:35], v[70:73], v[108:111], v[32:35]
	v_mfma_f32_16x16x32_bf16 v[28:31], v[74:77], v[96:99], v[28:31]
	v_mfma_f32_16x16x32_bf16 v[24:27], v[74:77], v[100:103], v[24:27]
	v_mfma_f32_16x16x32_bf16 v[20:23], v[74:77], v[104:107], v[20:23]
	v_mfma_f32_16x16x32_bf16 v[16:19], v[74:77], v[108:111], v[16:19]
	v_mfma_f32_16x16x32_bf16 v[12:15], v[92:95], v[96:99], v[12:15]
	v_mfma_f32_16x16x32_bf16 v[8:11], v[92:95], v[100:103], v[8:11]
	v_mfma_f32_16x16x32_bf16 v[4:7], v[92:95], v[104:107], v[4:7]
	v_mfma_f32_16x16x32_bf16 v[0:3], v[92:95], v[108:111], v[0:3]
	ds_read_b128 v[66:69], v91 offset:32768
	ds_read_b128 v[70:73], v91 offset:34816
	ds_read_b128 v[74:77], v91 offset:36864
	ds_read_b128 v[92:95], v91 offset:38912
	ds_read_b128 v[96:99], v65 offset:49152
	ds_read_b128 v[100:103], v65 offset:51200
	ds_read_b128 v[104:107], v65 offset:53248
	ds_read_b128 v[108:111], v65 offset:55296
	s_waitcnt lgkmcnt(3)
	v_mfma_f32_16x16x32_bf16 v[60:63], v[66:69], v[96:99], v[60:63]
	s_waitcnt lgkmcnt(2)
	v_mfma_f32_16x16x32_bf16 v[56:59], v[66:69], v[100:103], v[56:59]
	s_waitcnt lgkmcnt(1)
	v_mfma_f32_16x16x32_bf16 v[52:55], v[66:69], v[104:107], v[52:55]
	s_waitcnt lgkmcnt(0)
	v_mfma_f32_16x16x32_bf16 v[48:51], v[66:69], v[108:111], v[48:51]
	v_mfma_f32_16x16x32_bf16 v[44:47], v[70:73], v[96:99], v[44:47]
	v_mfma_f32_16x16x32_bf16 v[40:43], v[70:73], v[100:103], v[40:43]
	v_mfma_f32_16x16x32_bf16 v[36:39], v[70:73], v[104:107], v[36:39]
	v_mfma_f32_16x16x32_bf16 v[32:35], v[70:73], v[108:111], v[32:35]
	v_mfma_f32_16x16x32_bf16 v[28:31], v[74:77], v[96:99], v[28:31]
	v_mfma_f32_16x16x32_bf16 v[24:27], v[74:77], v[100:103], v[24:27]
	v_mfma_f32_16x16x32_bf16 v[20:23], v[74:77], v[104:107], v[20:23]
	v_mfma_f32_16x16x32_bf16 v[16:19], v[74:77], v[108:111], v[16:19]
	v_mfma_f32_16x16x32_bf16 v[12:15], v[92:95], v[96:99], v[12:15]
	v_mfma_f32_16x16x32_bf16 v[8:11], v[92:95], v[100:103], v[8:11]
	v_mfma_f32_16x16x32_bf16 v[4:7], v[92:95], v[104:107], v[4:7]
	v_mfma_f32_16x16x32_bf16 v[0:3], v[92:95], v[108:111], v[0:3]
	ds_read_b128 v[66:69], v91 offset:33792
	ds_read_b128 v[70:73], v91 offset:35840
	ds_read_b128 v[74:77], v91 offset:37888
	ds_read_b128 v[92:95], v91 offset:39936
	ds_read_b128 v[96:99], v65 offset:50176
	ds_read_b128 v[100:103], v65 offset:52224
	ds_read_b128 v[104:107], v65 offset:54272
	ds_read_b128 v[108:111], v65 offset:56320
	s_waitcnt lgkmcnt(0)
	s_barrier
	s_waitcnt lgkmcnt(3)
	v_mfma_f32_16x16x32_bf16 v[116:119], v[66:69], v[96:99], v[60:63]
	s_waitcnt lgkmcnt(0)
	s_barrier
	s_nop 0
	v_or_b32_e32 v61, s2, v88
	s_movk_i32 s2, 0xf8
	s_cselect_b32 s2, s2, 0x100
	s_add_u32 s2, s14, s2
	s_addc_u32 s3, s15, 0
	s_load_dwordx2 s[2:3], s[2:3], 0x0
	s_nop 0
	s_load_dwordx2 s[14:15], s[14:15], 0x158
	s_lshl_b32 s12, s12, 1
	s_or_b32 s16, s12, s16
	v_writelane_b32 v249, s12, 19
	v_lshl_add_u32 v60, s30, 7, v85
	v_mfma_f32_16x16x32_bf16 v[44:47], v[70:73], v[96:99], v[44:47]
	v_writelane_b32 v249, s13, 20
	s_lshl_b64 s[12:13], s[16:17], 18
	s_waitcnt lgkmcnt(0)
	s_add_u32 s12, s14, s12
	v_mfma_f32_16x16x32_bf16 v[40:43], v[70:73], v[100:103], v[40:43]
	s_addc_u32 s13, s15, s13
	v_lshlrev_b32_e32 v62, 2, v61
	v_or_b32_e32 v82, 3, v60
	v_mfma_f32_16x16x32_bf16 v[36:39], v[70:73], v[104:107], v[36:39]
	v_ashrrev_i32_e32 v83, 31, v82
	v_mov_b32_e32 v63, v80
	v_lshl_add_u64 v[62:63], s[2:3], 0, v[62:63]
	v_mfma_f32_16x16x32_bf16 v[32:35], v[70:73], v[108:111], v[32:35]
	v_or_b32_e32 v72, 1, v60
	v_ashrrev_i32_e32 v73, 31, v72
	v_bfe_u32 v65, v116, 16, 1
	v_mfma_f32_16x16x32_bf16 v[56:59], v[66:69], v[100:103], v[56:59]
	v_add3_u32 v65, v116, v65, s33
	s_mov_b64 s[2:3], 0
	v_mfma_f32_16x16x32_bf16 v[52:55], v[66:69], v[104:107], v[52:55]
	v_mfma_f32_16x16x32_bf16 v[48:51], v[66:69], v[108:111], v[48:51]
	v_lshlrev_b32_e32 v66, 1, v61
	v_mov_b32_e32 v67, v80
	v_ashrrev_i32_e32 v61, 31, v60
	v_mfma_f32_16x16x32_bf16 v[28:31], v[74:77], v[96:99], v[28:31]
	v_lshl_add_u64 v[66:67], s[12:13], 0, v[66:67]
	v_lshl_add_u64 v[68:69], s[10:11], 0, v[60:61]
	v_lshlrev_b64 v[70:71], 9, v[60:61]
	v_mfma_f32_16x16x32_bf16 v[24:27], v[74:77], v[100:103], v[24:27]
	v_bfe_u32 v61, v117, 16, 1
	v_add3_u32 v61, v117, v61, s33
	v_lshlrev_b64 v[68:69], 10, v[68:69]
	v_mfma_f32_16x16x32_bf16 v[20:23], v[74:77], v[104:107], v[20:23]
	v_lshl_add_u64 v[68:69], v[62:63], 0, v[68:69]
	v_lshl_add_u64 v[70:71], v[66:67], 0, v[70:71]
	global_store_dword v[68:69], v116, off
	v_mfma_f32_16x16x32_bf16 v[16:19], v[74:77], v[108:111], v[16:19]
	v_lshl_add_u64 v[74:75], s[10:11], 0, v[72:73]
	v_lshlrev_b64 v[72:73], 9, v[72:73]
	v_or_b32_e32 v76, 2, v60
	v_lshl_add_u64 v[72:73], v[66:67], 0, v[72:73]
	v_ashrrev_i32_e32 v77, 31, v76
	global_store_short_d16_hi v[72:73], v61, off
	v_lshl_add_u64 v[78:79], s[10:11], 0, v[76:77]
	v_bfe_u32 v61, v118, 16, 1
	v_lshlrev_b64 v[76:77], 9, v[76:77]
	v_mfma_f32_16x16x32_bf16 v[12:15], v[92:95], v[96:99], v[12:15]
	v_add3_u32 v61, v118, v61, s33
	v_lshl_add_u64 v[76:77], v[66:67], 0, v[76:77]
	v_lshlrev_b64 v[74:75], 10, v[74:75]
	v_mfma_f32_16x16x32_bf16 v[8:11], v[92:95], v[100:103], v[8:11]
	v_lshlrev_b64 v[78:79], 10, v[78:79]
	global_store_short_d16_hi v[76:77], v61, off
	v_bfe_u32 v61, v119, 16, 1
	v_mfma_f32_16x16x32_bf16 v[4:7], v[92:95], v[104:107], v[4:7]
	v_lshl_add_u64 v[74:75], v[62:63], 0, v[74:75]
	v_lshl_add_u64 v[78:79], v[62:63], 0, v[78:79]
	v_add3_u32 v61, v119, v61, s33
	v_mfma_f32_16x16x32_bf16 v[0:3], v[92:95], v[108:111], v[0:3]
	v_lshl_add_u64 v[92:93], s[10:11], 0, v[82:83]
	v_lshlrev_b64 v[92:93], 10, v[92:93]
	v_lshlrev_b64 v[82:83], 9, v[82:83]
	v_lshl_add_u64 v[92:93], v[62:63], 0, v[92:93]
	v_lshl_add_u64 v[82:83], v[66:67], 0, v[82:83]
	global_store_short_d16_hi v[70:71], v65, off
	global_store_dword v[74:75], v117, off
	global_store_dword v[78:79], v118, off
	global_store_dword v[92:93], v119, off
	global_store_short_d16_hi v[82:83], v61, off
	global_store_dword v[68:69], v56, off offset:64
	v_bfe_u32 v61, v56, 16, 1
	v_add3_u32 v56, v56, v61, s33
	global_store_short_d16_hi v[70:71], v56, off offset:32
	global_store_dword v[74:75], v57, off offset:64
	v_bfe_u32 v56, v57, 16, 1
	v_add3_u32 v56, v57, v56, s33
	global_store_short_d16_hi v[72:73], v56, off offset:32
	global_store_dword v[78:79], v58, off offset:64
	v_bfe_u32 v56, v58, 16, 1
	v_add3_u32 v56, v58, v56, s33
	global_store_short_d16_hi v[76:77], v56, off offset:32
	global_store_dword v[92:93], v59, off offset:64
	v_bfe_u32 v56, v59, 16, 1
	v_add3_u32 v56, v59, v56, s33
	global_store_short_d16_hi v[82:83], v56, off offset:32
	global_store_dword v[68:69], v52, off offset:128
	v_bfe_u32 v56, v52, 16, 1
	v_add3_u32 v52, v52, v56, s33
	global_store_short_d16_hi v[70:71], v52, off offset:64
	global_store_dword v[74:75], v53, off offset:128
	v_bfe_u32 v52, v53, 16, 1
	v_add3_u32 v52, v53, v52, s33
	global_store_short_d16_hi v[72:73], v52, off offset:64
	global_store_dword v[78:79], v54, off offset:128
	v_bfe_u32 v52, v54, 16, 1
	v_add3_u32 v52, v54, v52, s33
	global_store_short_d16_hi v[76:77], v52, off offset:64
	global_store_dword v[92:93], v55, off offset:128
	v_bfe_u32 v52, v55, 16, 1
	v_add3_u32 v52, v55, v52, s33
	global_store_short_d16_hi v[82:83], v52, off offset:64
	global_store_dword v[68:69], v48, off offset:192
	v_bfe_u32 v52, v48, 16, 1
	v_add3_u32 v48, v48, v52, s33
	global_store_short_d16_hi v[70:71], v48, off offset:96
	global_store_dword v[74:75], v49, off offset:192
	v_bfe_u32 v48, v49, 16, 1
	v_add3_u32 v48, v49, v48, s33
	global_store_short_d16_hi v[72:73], v48, off offset:96
	global_store_dword v[78:79], v50, off offset:192
	v_bfe_u32 v48, v50, 16, 1
	v_add3_u32 v48, v50, v48, s33
	global_store_short_d16_hi v[76:77], v48, off offset:96
	global_store_dword v[92:93], v51, off offset:192
	v_bfe_u32 v48, v51, 16, 1
	v_add3_u32 v48, v51, v48, s33
	global_store_short_d16_hi v[82:83], v48, off offset:96
	v_or_b32_e32 v48, 16, v60
	v_ashrrev_i32_e32 v49, 31, v48
	v_lshl_add_u64 v[50:51], s[10:11], 0, v[48:49]
	v_lshlrev_b64 v[50:51], 10, v[50:51]
	v_lshl_add_u64 v[50:51], v[62:63], 0, v[50:51]
	v_bfe_u32 v52, v44, 16, 1
	global_store_dword v[50:51], v44, off
	v_add3_u32 v44, v44, v52, s33
	v_or_b32_e32 v52, 17, v60
	v_ashrrev_i32_e32 v53, 31, v52
	v_lshlrev_b64 v[48:49], 9, v[48:49]
	v_lshl_add_u64 v[54:55], s[10:11], 0, v[52:53]
	v_lshl_add_u64 v[48:49], v[66:67], 0, v[48:49]
	v_lshlrev_b64 v[54:55], 10, v[54:55]
	global_store_short_d16_hi v[48:49], v44, off
	v_lshl_add_u64 v[54:55], v[62:63], 0, v[54:55]
	v_bfe_u32 v44, v45, 16, 1
	global_store_dword v[54:55], v45, off
	v_add3_u32 v56, v45, v44, s33
	v_lshlrev_b64 v[44:45], 9, v[52:53]
	v_or_b32_e32 v52, 18, v60
	v_lshl_add_u64 v[44:45], v[66:67], 0, v[44:45]
	v_ashrrev_i32_e32 v53, 31, v52
	global_store_short_d16_hi v[44:45], v56, off
	v_lshl_add_u64 v[56:57], s[10:11], 0, v[52:53]
	v_lshlrev_b64 v[56:57], 10, v[56:57]
	v_lshl_add_u64 v[56:57], v[62:63], 0, v[56:57]
	v_bfe_u32 v58, v46, 16, 1
	global_store_dword v[56:57], v46, off
	v_add3_u32 v46, v46, v58, s33
	v_or_b32_e32 v58, 19, v60
	v_ashrrev_i32_e32 v59, 31, v58
	v_lshlrev_b64 v[52:53], 9, v[52:53]
	v_lshl_add_u64 v[68:69], s[10:11], 0, v[58:59]
	v_lshl_add_u64 v[52:53], v[66:67], 0, v[52:53]
	v_lshlrev_b64 v[68:69], 10, v[68:69]
	global_store_short_d16_hi v[52:53], v46, off
	v_lshl_add_u64 v[68:69], v[62:63], 0, v[68:69]
	v_bfe_u32 v46, v47, 16, 1
	global_store_dword v[68:69], v47, off
	v_add3_u32 v61, v47, v46, s33
	v_lshlrev_b64 v[46:47], 9, v[58:59]
	v_lshl_add_u64 v[46:47], v[66:67], 0, v[46:47]
	v_bfe_u32 v58, v40, 16, 1
	global_store_short_d16_hi v[46:47], v61, off
	global_store_dword v[50:51], v40, off offset:64
	v_add3_u32 v40, v40, v58, s33
	global_store_short_d16_hi v[48:49], v40, off offset:32
	global_store_dword v[54:55], v41, off offset:64
	v_bfe_u32 v40, v41, 16, 1
	v_add3_u32 v40, v41, v40, s33
	global_store_short_d16_hi v[44:45], v40, off offset:32
	global_store_dword v[56:57], v42, off offset:64
	v_bfe_u32 v40, v42, 16, 1
	v_add3_u32 v40, v42, v40, s33
	global_store_short_d16_hi v[52:53], v40, off offset:32
	global_store_dword v[68:69], v43, off offset:64
	v_bfe_u32 v40, v43, 16, 1
	v_add3_u32 v40, v43, v40, s33
	global_store_short_d16_hi v[46:47], v40, off offset:32
	global_store_dword v[50:51], v36, off offset:128
	v_bfe_u32 v40, v36, 16, 1
	v_add3_u32 v36, v36, v40, s33
	global_store_short_d16_hi v[48:49], v36, off offset:64
	global_store_dword v[54:55], v37, off offset:128
	v_bfe_u32 v36, v37, 16, 1
	v_add3_u32 v36, v37, v36, s33
	global_store_short_d16_hi v[44:45], v36, off offset:64
	global_store_dword v[56:57], v38, off offset:128
	v_bfe_u32 v36, v38, 16, 1
	v_add3_u32 v36, v38, v36, s33
	global_store_short_d16_hi v[52:53], v36, off offset:64
	global_store_dword v[68:69], v39, off offset:128
	v_bfe_u32 v36, v39, 16, 1
	v_add3_u32 v36, v39, v36, s33
	global_store_short_d16_hi v[46:47], v36, off offset:64
	global_store_dword v[50:51], v32, off offset:192
	v_bfe_u32 v36, v32, 16, 1
	v_add3_u32 v32, v32, v36, s33
	global_store_short_d16_hi v[48:49], v32, off offset:96
	global_store_dword v[54:55], v33, off offset:192
	v_bfe_u32 v32, v33, 16, 1
	v_add3_u32 v32, v33, v32, s33
	global_store_short_d16_hi v[44:45], v32, off offset:96
	global_store_dword v[56:57], v34, off offset:192
	v_bfe_u32 v32, v34, 16, 1
	v_add3_u32 v32, v34, v32, s33
	global_store_short_d16_hi v[52:53], v32, off offset:96
	global_store_dword v[68:69], v35, off offset:192
	v_bfe_u32 v32, v35, 16, 1
	v_add3_u32 v32, v35, v32, s33
	global_store_short_d16_hi v[46:47], v32, off offset:96
	v_or_b32_e32 v32, 32, v60
	v_ashrrev_i32_e32 v33, 31, v32
	v_lshl_add_u64 v[34:35], s[10:11], 0, v[32:33]
	v_lshlrev_b64 v[34:35], 10, v[34:35]
	v_lshl_add_u64 v[34:35], v[62:63], 0, v[34:35]
	v_bfe_u32 v36, v28, 16, 1
	global_store_dword v[34:35], v28, off
	v_add3_u32 v28, v28, v36, s33
	v_or_b32_e32 v36, 33, v60
	v_ashrrev_i32_e32 v37, 31, v36
	v_lshlrev_b64 v[32:33], 9, v[32:33]
	v_lshl_add_u64 v[38:39], s[10:11], 0, v[36:37]
	v_lshl_add_u64 v[32:33], v[66:67], 0, v[32:33]
	v_lshlrev_b64 v[38:39], 10, v[38:39]
	global_store_short_d16_hi v[32:33], v28, off
	v_lshl_add_u64 v[38:39], v[62:63], 0, v[38:39]
	v_bfe_u32 v28, v29, 16, 1
	global_store_dword v[38:39], v29, off
	v_add3_u32 v40, v29, v28, s33
	v_lshlrev_b64 v[28:29], 9, v[36:37]
	v_or_b32_e32 v36, 34, v60
	v_lshl_add_u64 v[28:29], v[66:67], 0, v[28:29]
	v_ashrrev_i32_e32 v37, 31, v36
	global_store_short_d16_hi v[28:29], v40, off
	v_lshl_add_u64 v[40:41], s[10:11], 0, v[36:37]
	v_lshlrev_b64 v[40:41], 10, v[40:41]
	v_lshl_add_u64 v[40:41], v[62:63], 0, v[40:41]
	v_bfe_u32 v42, v30, 16, 1
	global_store_dword v[40:41], v30, off
	v_add3_u32 v30, v30, v42, s33
	v_or_b32_e32 v42, 35, v60
	v_ashrrev_i32_e32 v43, 31, v42
	v_lshlrev_b64 v[36:37], 9, v[36:37]
	v_lshl_add_u64 v[44:45], s[10:11], 0, v[42:43]
	v_lshl_add_u64 v[36:37], v[66:67], 0, v[36:37]
	v_lshlrev_b64 v[44:45], 10, v[44:45]
	global_store_short_d16_hi v[36:37], v30, off
	v_lshl_add_u64 v[44:45], v[62:63], 0, v[44:45]
	v_bfe_u32 v30, v31, 16, 1
	global_store_dword v[44:45], v31, off
	v_add3_u32 v46, v31, v30, s33
	v_lshlrev_b64 v[30:31], 9, v[42:43]
	v_lshl_add_u64 v[30:31], v[66:67], 0, v[30:31]
	v_bfe_u32 v42, v24, 16, 1
	global_store_short_d16_hi v[30:31], v46, off
	global_store_dword v[34:35], v24, off offset:64
	v_add3_u32 v24, v24, v42, s33
	global_store_short_d16_hi v[32:33], v24, off offset:32
	global_store_dword v[38:39], v25, off offset:64
	v_bfe_u32 v24, v25, 16, 1
	v_add3_u32 v24, v25, v24, s33
	global_store_short_d16_hi v[28:29], v24, off offset:32
	global_store_dword v[40:41], v26, off offset:64
	v_bfe_u32 v24, v26, 16, 1
	v_add3_u32 v24, v26, v24, s33
	global_store_short_d16_hi v[36:37], v24, off offset:32
	global_store_dword v[44:45], v27, off offset:64
	v_bfe_u32 v24, v27, 16, 1
	v_add3_u32 v24, v27, v24, s33
	global_store_short_d16_hi v[30:31], v24, off offset:32
	global_store_dword v[34:35], v20, off offset:128
	v_bfe_u32 v24, v20, 16, 1
	v_add3_u32 v20, v20, v24, s33
	global_store_short_d16_hi v[32:33], v20, off offset:64
	global_store_dword v[38:39], v21, off offset:128
	v_bfe_u32 v20, v21, 16, 1
	v_add3_u32 v20, v21, v20, s33
	global_store_short_d16_hi v[28:29], v20, off offset:64
	global_store_dword v[40:41], v22, off offset:128
	v_bfe_u32 v20, v22, 16, 1
	v_add3_u32 v20, v22, v20, s33
	global_store_short_d16_hi v[36:37], v20, off offset:64
	global_store_dword v[44:45], v23, off offset:128
	v_bfe_u32 v20, v23, 16, 1
	v_add3_u32 v20, v23, v20, s33
	global_store_short_d16_hi v[30:31], v20, off offset:64
	global_store_dword v[34:35], v16, off offset:192
	v_bfe_u32 v20, v16, 16, 1
	v_add3_u32 v16, v16, v20, s33
	global_store_short_d16_hi v[32:33], v16, off offset:96
	global_store_dword v[38:39], v17, off offset:192
	v_bfe_u32 v16, v17, 16, 1
	v_add3_u32 v16, v17, v16, s33
	global_store_short_d16_hi v[28:29], v16, off offset:96
	global_store_dword v[40:41], v18, off offset:192
	v_bfe_u32 v16, v18, 16, 1
	v_add3_u32 v16, v18, v16, s33
	global_store_short_d16_hi v[36:37], v16, off offset:96
	global_store_dword v[44:45], v19, off offset:192
	v_bfe_u32 v16, v19, 16, 1
	v_add3_u32 v16, v19, v16, s33
	global_store_short_d16_hi v[30:31], v16, off offset:96
	v_or_b32_e32 v16, 48, v60
	v_ashrrev_i32_e32 v17, 31, v16
	v_lshl_add_u64 v[18:19], s[10:11], 0, v[16:17]
	v_lshlrev_b64 v[18:19], 10, v[18:19]
	v_lshl_add_u64 v[18:19], v[62:63], 0, v[18:19]
	v_bfe_u32 v20, v12, 16, 1
	global_store_dword v[18:19], v12, off
	v_add3_u32 v12, v12, v20, s33
	v_or_b32_e32 v20, 49, v60
	v_ashrrev_i32_e32 v21, 31, v20
	v_lshlrev_b64 v[16:17], 9, v[16:17]
	v_lshl_add_u64 v[22:23], s[10:11], 0, v[20:21]
	v_lshl_add_u64 v[16:17], v[66:67], 0, v[16:17]
	v_lshlrev_b64 v[22:23], 10, v[22:23]
	global_store_short_d16_hi v[16:17], v12, off
	v_lshl_add_u64 v[22:23], v[62:63], 0, v[22:23]
	v_bfe_u32 v12, v13, 16, 1
	global_store_dword v[22:23], v13, off
	v_add3_u32 v24, v13, v12, s33
	v_lshlrev_b64 v[12:13], 9, v[20:21]
	v_or_b32_e32 v20, 50, v60
	v_lshl_add_u64 v[12:13], v[66:67], 0, v[12:13]
	v_ashrrev_i32_e32 v21, 31, v20
	global_store_short_d16_hi v[12:13], v24, off
	v_lshl_add_u64 v[24:25], s[10:11], 0, v[20:21]
	v_lshlrev_b64 v[24:25], 10, v[24:25]
	v_lshl_add_u64 v[24:25], v[62:63], 0, v[24:25]
	v_bfe_u32 v26, v14, 16, 1
	global_store_dword v[24:25], v14, off
	v_add3_u32 v14, v14, v26, s33
	v_or_b32_e32 v26, 51, v60
	v_ashrrev_i32_e32 v27, 31, v26
	v_lshlrev_b64 v[20:21], 9, v[20:21]
	v_lshl_add_u64 v[28:29], s[10:11], 0, v[26:27]
	v_lshl_add_u64 v[20:21], v[66:67], 0, v[20:21]
	v_lshlrev_b64 v[28:29], 10, v[28:29]
	global_store_short_d16_hi v[20:21], v14, off
	v_lshl_add_u64 v[28:29], v[62:63], 0, v[28:29]
	v_bfe_u32 v14, v15, 16, 1
	global_store_dword v[28:29], v15, off
	v_add3_u32 v30, v15, v14, s33
	v_lshlrev_b64 v[14:15], 9, v[26:27]
	v_lshl_add_u64 v[14:15], v[66:67], 0, v[14:15]
	v_bfe_u32 v26, v8, 16, 1
	global_store_short_d16_hi v[14:15], v30, off
	global_store_dword v[18:19], v8, off offset:64
	v_add3_u32 v8, v8, v26, s33
	global_store_short_d16_hi v[16:17], v8, off offset:32
	global_store_dword v[22:23], v9, off offset:64
	v_bfe_u32 v8, v9, 16, 1
	v_add3_u32 v8, v9, v8, s33
	global_store_short_d16_hi v[12:13], v8, off offset:32
	global_store_dword v[24:25], v10, off offset:64
	v_bfe_u32 v8, v10, 16, 1
	v_add3_u32 v8, v10, v8, s33
	global_store_short_d16_hi v[20:21], v8, off offset:32
	global_store_dword v[28:29], v11, off offset:64
	v_bfe_u32 v8, v11, 16, 1
	v_add3_u32 v8, v11, v8, s33
	global_store_short_d16_hi v[14:15], v8, off offset:32
	global_store_dword v[18:19], v4, off offset:128
	v_bfe_u32 v8, v4, 16, 1
	v_add3_u32 v4, v4, v8, s33
	global_store_short_d16_hi v[16:17], v4, off offset:64
	global_store_dword v[22:23], v5, off offset:128
	v_bfe_u32 v4, v5, 16, 1
	v_add3_u32 v4, v5, v4, s33
	global_store_short_d16_hi v[12:13], v4, off offset:64
	global_store_dword v[24:25], v6, off offset:128
	v_bfe_u32 v4, v6, 16, 1
	v_add3_u32 v4, v6, v4, s33
	global_store_short_d16_hi v[20:21], v4, off offset:64
	global_store_dword v[28:29], v7, off offset:128
	v_bfe_u32 v4, v7, 16, 1
	v_add3_u32 v4, v7, v4, s33
	global_store_short_d16_hi v[14:15], v4, off offset:64
	global_store_dword v[18:19], v0, off offset:192
	v_bfe_u32 v4, v0, 16, 1
	v_add3_u32 v0, v0, v4, s33
	global_store_short_d16_hi v[16:17], v0, off offset:96
	global_store_dword v[22:23], v1, off offset:192
	v_bfe_u32 v0, v1, 16, 1
	v_add3_u32 v0, v1, v0, s33
	global_store_short_d16_hi v[12:13], v0, off offset:96
	global_store_dword v[24:25], v2, off offset:192
	v_bfe_u32 v0, v2, 16, 1
	v_add3_u32 v0, v2, v0, s33
	global_store_short_d16_hi v[20:21], v0, off offset:96
	global_store_dword v[28:29], v3, off offset:192
	v_bfe_u32 v0, v3, 16, 1
	v_add3_u32 v0, v3, v0, s33
	global_store_short_d16_hi v[14:15], v0, off offset:96

.LBB0_357:
	s_and_b32 s13, s11, 0x8000
	s_waitcnt vmcnt(8)
	s_barrier
	v_add_u32_e32 v93, s13, v65
	v_or_b32_e32 v128, s13, v91
	ds_read_b128 v[94:97], v93
	ds_read_b128 v[98:101], v93 offset:2048
	ds_read_b128 v[102:105], v93 offset:4096
	ds_read_b128 v[106:109], v93 offset:6144
	ds_read_b128 v[110:113], v128 offset:16384
	ds_read_b128 v[116:119], v128 offset:18432
	ds_read_b128 v[120:123], v128 offset:20480
	ds_read_b128 v[124:127], v128 offset:22528
	s_waitcnt lgkmcnt(0)
	v_mfma_f32_16x16x32_bf16 v[60:63], v[94:97], v[110:113], v[60:63]
	v_mfma_f32_16x16x32_bf16 v[56:59], v[94:97], v[116:119], v[56:59]
	v_mfma_f32_16x16x32_bf16 v[52:55], v[94:97], v[120:123], v[52:55]
	v_mfma_f32_16x16x32_bf16 v[48:51], v[94:97], v[124:127], v[48:51]
	v_mfma_f32_16x16x32_bf16 v[44:47], v[98:101], v[110:113], v[44:47]
	v_mfma_f32_16x16x32_bf16 v[40:43], v[98:101], v[116:119], v[40:43]
	v_mfma_f32_16x16x32_bf16 v[36:39], v[98:101], v[120:123], v[36:39]
	v_mfma_f32_16x16x32_bf16 v[32:35], v[98:101], v[124:127], v[32:35]
	v_mfma_f32_16x16x32_bf16 v[28:31], v[102:105], v[110:113], v[28:31]
	v_mfma_f32_16x16x32_bf16 v[24:27], v[102:105], v[116:119], v[24:27]
	v_mfma_f32_16x16x32_bf16 v[20:23], v[102:105], v[120:123], v[20:23]
	v_mfma_f32_16x16x32_bf16 v[16:19], v[102:105], v[124:127], v[16:19]
	v_mfma_f32_16x16x32_bf16 v[12:15], v[106:109], v[110:113], v[12:15]
	v_mfma_f32_16x16x32_bf16 v[8:11], v[106:109], v[116:119], v[8:11]
	v_mfma_f32_16x16x32_bf16 v[4:7], v[106:109], v[120:123], v[4:7]
	v_mfma_f32_16x16x32_bf16 v[0:3], v[106:109], v[124:127], v[0:3]
	ds_read_b128 v[94:97], v93 offset:1024
	ds_read_b128 v[98:101], v93 offset:3072
	ds_read_b128 v[102:105], v93 offset:5120
	ds_read_b128 v[106:109], v93 offset:7168
	ds_read_b128 v[110:113], v128 offset:17408
	ds_read_b128 v[116:119], v128 offset:19456
	ds_read_b128 v[120:123], v128 offset:21504
	ds_read_b128 v[124:127], v128 offset:23552
	v_add_u32_e32 v93, s13, v92
	s_waitcnt lgkmcnt(0)
	s_waitcnt lgkmcnt(3)
	v_mfma_f32_16x16x32_bf16 v[60:63], v[94:97], v[110:113], v[60:63]
	v_readfirstlane_b32 s13, v93
	s_barrier
	s_waitcnt lgkmcnt(2)
	v_mfma_f32_16x16x32_bf16 v[56:59], v[94:97], v[116:119], v[56:59]
	s_mov_b32 m0, s13
	s_waitcnt lgkmcnt(1)
	v_mfma_f32_16x16x32_bf16 v[52:55], v[94:97], v[120:123], v[52:55]
	s_waitcnt lgkmcnt(0)
	v_mfma_f32_16x16x32_bf16 v[48:51], v[94:97], v[124:127], v[48:51]
	v_add_u32_e32 v96, 0x1000, v93
	v_lshl_add_u64 v[94:95], v[82:83], 0, s[2:3]
	v_readfirstlane_b32 s13, v96
	v_add_u32_e32 v96, 0x2000, v93
	global_load_lds_dwordx4 v[94:95], off
	v_lshl_add_u64 v[94:95], v[78:79], 0, s[2:3]
	s_mov_b32 m0, s13
	v_readfirstlane_b32 s13, v96
	v_add_u32_e32 v96, 0x3000, v93
	global_load_lds_dwordx4 v[94:95], off
	v_lshl_add_u64 v[94:95], v[76:77], 0, s[2:3]
	s_mov_b32 m0, s13
	v_readfirstlane_b32 s13, v96
	v_add_u32_e32 v96, 0x4000, v93
	global_load_lds_dwordx4 v[94:95], off
	v_lshl_add_u64 v[94:95], v[74:75], 0, s[2:3]
	s_mov_b32 m0, s13
	v_readfirstlane_b32 s13, v96
	v_add_u32_e32 v96, 0x5000, v93
	global_load_lds_dwordx4 v[94:95], off
	v_lshl_add_u64 v[94:95], v[72:73], 0, s[2:3]
	s_mov_b32 m0, s13
	v_readfirstlane_b32 s13, v96
	v_add_u32_e32 v96, 0x6000, v93
	global_load_lds_dwordx4 v[94:95], off
	v_lshl_add_u64 v[94:95], v[70:71], 0, s[2:3]
	s_mov_b32 m0, s13
	v_readfirstlane_b32 s13, v96
	v_add_u32_e32 v93, 0x7000, v93
	global_load_lds_dwordx4 v[94:95], off
	v_lshl_add_u64 v[94:95], v[68:69], 0, s[2:3]
	s_mov_b32 m0, s13
	v_readfirstlane_b32 s13, v93
	global_load_lds_dwordx4 v[94:95], off
	v_lshl_add_u64 v[94:95], v[66:67], 0, s[2:3]
	s_mov_b32 m0, s13
	v_mfma_f32_16x16x32_bf16 v[44:47], v[98:101], v[110:113], v[44:47]
	global_load_lds_dwordx4 v[94:95], off
	s_add_u32 s2, s2, 0x80
	v_mfma_f32_16x16x32_bf16 v[40:43], v[98:101], v[116:119], v[40:43]
	s_addc_u32 s3, s3, 0
	s_add_i32 s11, s11, 0x8000
	s_cmpk_lg_i32 s2, 0x700
	v_mfma_f32_16x16x32_bf16 v[36:39], v[98:101], v[120:123], v[36:39]
	v_mfma_f32_16x16x32_bf16 v[32:35], v[98:101], v[124:127], v[32:35]
	v_mfma_f32_16x16x32_bf16 v[28:31], v[102:105], v[110:113], v[28:31]
	v_mfma_f32_16x16x32_bf16 v[24:27], v[102:105], v[116:119], v[24:27]
	v_mfma_f32_16x16x32_bf16 v[20:23], v[102:105], v[120:123], v[20:23]
	v_mfma_f32_16x16x32_bf16 v[16:19], v[102:105], v[124:127], v[16:19]
	v_mfma_f32_16x16x32_bf16 v[12:15], v[106:109], v[110:113], v[12:15]
	v_mfma_f32_16x16x32_bf16 v[8:11], v[106:109], v[116:119], v[8:11]
	v_mfma_f32_16x16x32_bf16 v[4:7], v[106:109], v[120:123], v[4:7]
	v_mfma_f32_16x16x32_bf16 v[0:3], v[106:109], v[124:127], v[0:3]
	s_cbranch_scc1 .LBB0_357
	s_waitcnt vmcnt(8)
	s_barrier
	ds_read_b128 v[66:69], v65
	ds_read_b128 v[70:73], v91 offset:16384
	ds_read_b128 v[74:77], v91 offset:18432
	ds_read_b128 v[92:95], v91 offset:20480
	ds_read_b128 v[96:99], v91 offset:22528
	s_waitcnt lgkmcnt(0)
	v_mfma_f32_16x16x32_bf16 v[60:63], v[66:69], v[70:73], v[60:63]
	s_lshl_b32 s30, s12, 7
	s_cmp_gt_i32 s10, 7
	s_cselect_b64 s[12:13], -1, 0
	v_mfma_f32_16x16x32_bf16 v[56:59], v[66:69], v[74:77], v[56:59]
	s_or_b64 s[2:3], s[0:1], s[12:13]
	s_and_b64 vcc, exec, s[2:3]
	v_mfma_f32_16x16x32_bf16 v[52:55], v[66:69], v[92:95], v[52:55]
	v_mfma_f32_16x16x32_bf16 v[48:51], v[66:69], v[96:99], v[48:51]
	ds_read_b128 v[66:69], v65 offset:2048
	s_waitcnt lgkmcnt(0)
	v_mfma_f32_16x16x32_bf16 v[44:47], v[66:69], v[70:73], v[44:47]
	v_mfma_f32_16x16x32_bf16 v[40:43], v[66:69], v[74:77], v[40:43]
	v_mfma_f32_16x16x32_bf16 v[36:39], v[66:69], v[92:95], v[36:39]
	v_mfma_f32_16x16x32_bf16 v[32:35], v[66:69], v[96:99], v[32:35]
	ds_read_b128 v[66:69], v65 offset:4096
	s_waitcnt lgkmcnt(0)
	v_mfma_f32_16x16x32_bf16 v[28:31], v[66:69], v[70:73], v[28:31]
	v_mfma_f32_16x16x32_bf16 v[24:27], v[66:69], v[74:77], v[24:27]
	v_mfma_f32_16x16x32_bf16 v[20:23], v[66:69], v[92:95], v[20:23]
	v_mfma_f32_16x16x32_bf16 v[16:19], v[66:69], v[96:99], v[16:19]
	ds_read_b128 v[66:69], v65 offset:6144
	s_waitcnt lgkmcnt(0)
	v_mfma_f32_16x16x32_bf16 v[12:15], v[66:69], v[70:73], v[12:15]
	ds_read_b128 v[70:73], v65 offset:1024
	v_mfma_f32_16x16x32_bf16 v[8:11], v[66:69], v[74:77], v[8:11]
	ds_read_b128 v[74:77], v91 offset:19456
	v_mfma_f32_16x16x32_bf16 v[4:7], v[66:69], v[92:95], v[4:7]
	ds_read_b128 v[92:95], v91 offset:21504
	v_mfma_f32_16x16x32_bf16 v[0:3], v[66:69], v[96:99], v[0:3]
	ds_read_b128 v[66:69], v91 offset:17408
	ds_read_b128 v[96:99], v91 offset:23552
	s_waitcnt lgkmcnt(1)
	v_mfma_f32_16x16x32_bf16 v[60:63], v[70:73], v[66:69], v[60:63]
	v_mfma_f32_16x16x32_bf16 v[56:59], v[70:73], v[74:77], v[56:59]
	v_mfma_f32_16x16x32_bf16 v[52:55], v[70:73], v[92:95], v[52:55]
	s_waitcnt lgkmcnt(0)
	v_mfma_f32_16x16x32_bf16 v[48:51], v[70:73], v[96:99], v[48:51]
	ds_read_b128 v[70:73], v65 offset:3072
	s_waitcnt lgkmcnt(0)
	v_mfma_f32_16x16x32_bf16 v[44:47], v[70:73], v[66:69], v[44:47]
	v_mfma_f32_16x16x32_bf16 v[40:43], v[70:73], v[74:77], v[40:43]
	v_mfma_f32_16x16x32_bf16 v[36:39], v[70:73], v[92:95], v[36:39]
	v_mfma_f32_16x16x32_bf16 v[32:35], v[70:73], v[96:99], v[32:35]
	ds_read_b128 v[70:73], v65 offset:5120
	s_waitcnt lgkmcnt(0)
	v_mfma_f32_16x16x32_bf16 v[28:31], v[70:73], v[66:69], v[28:31]
	v_mfma_f32_16x16x32_bf16 v[24:27], v[70:73], v[74:77], v[24:27]
	v_mfma_f32_16x16x32_bf16 v[20:23], v[70:73], v[92:95], v[20:23]
	v_mfma_f32_16x16x32_bf16 v[16:19], v[70:73], v[96:99], v[16:19]
	ds_read_b128 v[70:73], v65 offset:7168
	s_waitcnt lgkmcnt(0)
	s_barrier
	s_waitcnt vmcnt(0)
	s_barrier
	s_waitcnt lgkmcnt(0)
	v_mfma_f32_16x16x32_bf16 v[12:15], v[70:73], v[66:69], v[12:15]
	ds_read_b128 v[66:69], v65 offset:32768
	ds_read_b128 v[124:127], v91 offset:54272
	v_mfma_f32_16x16x32_bf16 v[8:11], v[70:73], v[74:77], v[8:11]
	ds_read_b128 v[74:77], v91 offset:51200
	v_mfma_f32_16x16x32_bf16 v[4:7], v[70:73], v[92:95], v[4:7]
	ds_read_b128 v[92:95], v91 offset:53248
	v_mfma_f32_16x16x32_bf16 v[0:3], v[70:73], v[96:99], v[0:3]
	ds_read_b128 v[70:73], v91 offset:49152
	s_waitcnt lgkmcnt(1)
	v_mfma_f32_16x16x32_bf16 v[96:99], v[66:69], v[92:95], v[52:55]
	s_nop 2
	ds_read_b128 v[52:55], v91 offset:55296
	s_waitcnt lgkmcnt(1)
	v_mfma_f32_16x16x32_bf16 v[60:63], v[66:69], v[70:73], v[60:63]
	v_mfma_f32_16x16x32_bf16 v[56:59], v[66:69], v[74:77], v[56:59]
	s_waitcnt lgkmcnt(0)
	v_mfma_f32_16x16x32_bf16 v[66:69], v[66:69], v[52:55], v[48:51]
	s_nop 2
	ds_read_b128 v[48:51], v65 offset:34816
	s_waitcnt lgkmcnt(0)
	v_mfma_f32_16x16x32_bf16 v[104:107], v[48:51], v[52:55], v[32:35]
	s_nop 2
	ds_read_b128 v[32:35], v65 offset:36864
	s_waitcnt lgkmcnt(0)
	v_mfma_f32_16x16x32_bf16 v[116:119], v[32:35], v[52:55], v[16:19]
	s_nop 2
	ds_read_b128 v[16:19], v65 offset:38912
	v_mfma_f32_16x16x32_bf16 v[44:47], v[48:51], v[70:73], v[44:47]
	v_mfma_f32_16x16x32_bf16 v[28:31], v[32:35], v[70:73], v[28:31]
	s_waitcnt lgkmcnt(0)
	v_mfma_f32_16x16x32_bf16 v[12:15], v[16:19], v[70:73], v[12:15]
	v_mfma_f32_16x16x32_bf16 v[70:73], v[16:19], v[92:95], v[4:7]
	s_nop 2
	ds_read_b128 v[4:7], v65 offset:33792
	v_mfma_f32_16x16x32_bf16 v[40:43], v[48:51], v[74:77], v[40:43]
	v_mfma_f32_16x16x32_bf16 v[24:27], v[32:35], v[74:77], v[24:27]
	v_mfma_f32_16x16x32_bf16 v[8:11], v[16:19], v[74:77], v[8:11]
	ds_read_b128 v[74:77], v91 offset:52224
	v_mfma_f32_16x16x32_bf16 v[120:123], v[16:19], v[52:55], v[0:3]
	s_nop 2
	ds_read_b128 v[0:3], v91 offset:50176
	s_waitcnt lgkmcnt(1)
	v_mfma_f32_16x16x32_bf16 v[52:55], v[4:7], v[74:77], v[56:59]
	v_mfma_f32_16x16x32_bf16 v[56:59], v[4:7], v[124:127], v[96:99]
	s_nop 2
	ds_read_b128 v[96:99], v91 offset:56320
	v_mfma_f32_16x16x32_bf16 v[100:103], v[48:51], v[92:95], v[36:39]
	s_waitcnt lgkmcnt(1)
	v_mfma_f32_16x16x32_bf16 v[48:51], v[4:7], v[0:3], v[60:63]
	s_waitcnt lgkmcnt(0)
	v_mfma_f32_16x16x32_bf16 v[60:63], v[4:7], v[96:99], v[66:69]
	ds_read_b128 v[4:7], v65 offset:35840
	ds_read_b128 v[128:131], v65 offset:37888
	ds_read_b128 v[132:135], v65 offset:39936
	s_waitcnt lgkmcnt(0)
	v_mfma_f32_16x16x32_bf16 v[108:111], v[32:35], v[92:95], v[20:23]
	s_barrier
	v_add_u32_e32 v66, s30, v81
	s_waitcnt lgkmcnt(2)
	v_mfma_f32_16x16x32_bf16 v[32:35], v[4:7], v[0:3], v[44:47]
	v_or_b32_e32 v65, v66, v84
	v_or_b32_e32 v95, 1, v65
	v_or_b32_e32 v94, 2, v65
	v_mfma_f32_16x16x32_bf16 v[36:39], v[4:7], v[74:77], v[40:43]
	v_or_b32_e32 v93, 3, v65
	v_or_b32_e32 v92, 16, v65
	v_or_b32_e32 v91, 17, v65
	v_mfma_f32_16x16x32_bf16 v[40:43], v[4:7], v[124:127], v[100:103]
	v_or_b32_e32 v83, 18, v65
	v_or_b32_e32 v82, 19, v65
	v_or_b32_e32 v79, 32, v65
	v_mfma_f32_16x16x32_bf16 v[44:47], v[4:7], v[96:99], v[104:107]
	v_or_b32_e32 v78, 33, v65
	s_waitcnt lgkmcnt(0)
	s_barrier
	v_mfma_f32_16x16x32_bf16 v[16:19], v[128:131], v[0:3], v[28:31]
	v_mfma_f32_16x16x32_bf16 v[20:23], v[128:131], v[74:77], v[24:27]
	v_mfma_f32_16x16x32_bf16 v[24:27], v[128:131], v[124:127], v[108:111]
	v_mfma_f32_16x16x32_bf16 v[28:31], v[128:131], v[96:99], v[116:119]
	v_mfma_f32_16x16x32_bf16 v[0:3], v[132:135], v[0:3], v[12:15]
	v_mfma_f32_16x16x32_bf16 v[4:7], v[132:135], v[74:77], v[8:11]
	v_or_b32_e32 v77, 34, v65
	v_or_b32_e32 v76, 35, v65
	v_or_b32_e32 v75, 48, v65
	v_mfma_f32_16x16x32_bf16 v[8:11], v[132:135], v[124:127], v[70:73]
	v_or_b32_e32 v74, 49, v65
	v_mfma_f32_16x16x32_bf16 v[12:15], v[132:135], v[96:99], v[120:123]
	s_nop 0
	v_or_b32_e32 v73, 50, v65
	v_or_b32_e32 v72, 51, v65
	s_cbranch_vccnz .LBB0_360
	v_lshlrev_b32_e32 v67, 4, v65
	s_movk_i32 s11, 0x4000
	v_and_b32_e32 v67, 0x1fcc0, v67
	v_cmp_gt_i32_e32 vcc, s11, v65
	v_lshlrev_b32_e32 v68, 4, v95
	v_and_b32_e32 v68, 0x1fcd0, v68
	v_cndmask_b32_e32 v67, v235, v67, vcc
	v_cmp_gt_i32_e32 vcc, s11, v95
	v_readlane_b32 s2, v249, 30
	v_readlane_b32 s3, v249, 31
	v_cndmask_b32_e32 v68, v236, v68, vcc
	v_or_b32_e32 v68, v68, v86
	v_lshlrev_b32_e32 v70, 2, v68
	v_lshlrev_b32_e32 v68, 4, v94
	v_and_b32_e32 v68, 0x1fce0, v68
	v_cmp_gt_i32_e32 vcc, s11, v94
	s_load_dwordx2 s[2:3], s[2:3], 0x170
	v_or_b32_e32 v67, v67, v86
	v_cndmask_b32_e32 v68, v237, v68, vcc
	v_or_b32_e32 v68, v68, v86
	v_lshlrev_b32_e32 v96, 2, v68
	v_lshlrev_b32_e32 v68, 4, v93
	v_and_b32_e32 v68, 0x1fcf0, v68
	v_cmp_gt_i32_e32 vcc, s11, v93
	v_lshlrev_b32_e32 v67, 2, v67
	v_lshlrev_b32_e32 v100, 4, v91
	v_cndmask_b32_e32 v68, v238, v68, vcc
	v_or_b32_e32 v68, v68, v86
	v_lshlrev_b32_e32 v98, 2, v68
	s_waitcnt lgkmcnt(0)
	global_load_dwordx2 v[68:69], v67, s[2:3]
	s_nop 0
	global_load_dwordx2 v[70:71], v70, s[2:3]
	s_nop 0
	global_load_dwordx2 v[96:97], v96, s[2:3]
	s_nop 0
	global_load_dwordx2 v[98:99], v98, s[2:3]
	v_lshlrev_b32_e32 v67, 4, v92
	v_and_b32_e32 v67, 0x1fdc0, v67
	v_cmp_gt_i32_e32 vcc, s11, v92
	v_and_b32_e32 v100, 0x1fdd0, v100
	v_lshlrev_b32_e32 v108, 4, v78
	v_cndmask_b32_e32 v67, v235, v67, vcc
	v_cmp_gt_i32_e32 vcc, s11, v91
	v_or_b32_e32 v67, v67, v86
	v_lshlrev_b32_e32 v67, 2, v67
	v_cndmask_b32_e32 v100, v236, v100, vcc
	v_or_b32_e32 v100, v100, v86
	v_lshlrev_b32_e32 v102, 2, v100
	v_lshlrev_b32_e32 v100, 4, v83
	v_and_b32_e32 v100, 0x1fde0, v100
	v_cmp_gt_i32_e32 vcc, s11, v83
	v_and_b32_e32 v108, 0x1fed0, v108
	v_lshlrev_b32_e32 v118, 4, v74
	v_cndmask_b32_e32 v100, v237, v100, vcc
	v_or_b32_e32 v100, v100, v86
	v_lshlrev_b32_e32 v104, 2, v100
	v_lshlrev_b32_e32 v100, 4, v82
	v_and_b32_e32 v100, 0x1fdf0, v100
	v_cmp_gt_i32_e32 vcc, s11, v82
	v_and_b32_e32 v118, 0x1ffd0, v118
	v_lshlrev_b32_e32 v122, 4, v72
	v_cndmask_b32_e32 v100, v238, v100, vcc
	v_or_b32_e32 v100, v100, v86
	v_lshlrev_b32_e32 v106, 2, v100
	global_load_dwordx2 v[100:101], v67, s[2:3]
	s_nop 0
	global_load_dwordx2 v[102:103], v102, s[2:3]
	s_nop 0
	global_load_dwordx2 v[104:105], v104, s[2:3]
	s_nop 0
	global_load_dwordx2 v[106:107], v106, s[2:3]
	v_lshlrev_b32_e32 v67, 4, v79
	v_and_b32_e32 v67, 0x1fec0, v67
	v_cmp_gt_i32_e32 vcc, s11, v79
	v_and_b32_e32 v122, 0x1fff0, v122
	v_and_b32_e32 v126, 64, v229
	v_cndmask_b32_e32 v67, v235, v67, vcc
	v_cmp_gt_i32_e32 vcc, s11, v78
	v_or_b32_e32 v67, v67, v86
	v_lshlrev_b32_e32 v67, 2, v67
	v_cndmask_b32_e32 v108, v236, v108, vcc
	v_or_b32_e32 v108, v108, v86
	v_lshlrev_b32_e32 v110, 2, v108
	v_lshlrev_b32_e32 v108, 4, v77
	v_and_b32_e32 v108, 0x1fee0, v108
	v_cmp_gt_i32_e32 vcc, s11, v77
	v_add_u32_e32 v126, 64, v126
	s_waitcnt vmcnt(7)
	v_mov_b32_e32 v128, v68
	v_cndmask_b32_e32 v108, v237, v108, vcc
	v_or_b32_e32 v108, v108, v86
	v_lshlrev_b32_e32 v112, 2, v108
	v_lshlrev_b32_e32 v108, 4, v76
	v_and_b32_e32 v108, 0x1fef0, v108
	v_cmp_gt_i32_e32 vcc, s11, v76
	s_waitcnt vmcnt(6)
	v_mov_b32_e32 v129, v70
	v_mov_b32_e32 v70, v69
	v_cndmask_b32_e32 v108, v238, v108, vcc
	v_or_b32_e32 v108, v108, v86
	v_lshlrev_b32_e32 v116, 2, v108
	global_load_dwordx2 v[108:109], v67, s[2:3]
	s_nop 0
	global_load_dwordx2 v[110:111], v110, s[2:3]
	s_nop 0
	global_load_dwordx2 v[112:113], v112, s[2:3]
	s_nop 0
	global_load_dwordx2 v[116:117], v116, s[2:3]
	v_lshlrev_b32_e32 v67, 4, v75
	v_and_b32_e32 v67, 0x1ffc0, v67
	v_cmp_gt_i32_e32 vcc, s11, v75
	s_nop 1
	v_cndmask_b32_e32 v67, v235, v67, vcc
	v_cmp_gt_i32_e32 vcc, s11, v74
	v_or_b32_e32 v67, v67, v86
	v_lshlrev_b32_e32 v67, 2, v67
	v_cndmask_b32_e32 v118, v236, v118, vcc
	v_or_b32_e32 v118, v118, v86
	v_lshlrev_b32_e32 v120, 2, v118
	global_load_dwordx2 v[118:119], v67, s[2:3]
	s_nop 0
	global_load_dwordx2 v[120:121], v120, s[2:3]
	v_lshlrev_b32_e32 v67, 4, v73
	v_and_b32_e32 v67, 0x1ffe0, v67
	v_cmp_gt_i32_e32 vcc, s11, v73
	s_nop 1
	v_cndmask_b32_e32 v67, v237, v67, vcc
	v_cmp_gt_i32_e32 vcc, s11, v72
	v_or_b32_e32 v67, v67, v86
	v_lshlrev_b32_e32 v67, 2, v67
	v_cndmask_b32_e32 v122, v238, v122, vcc
	v_or_b32_e32 v122, v122, v86
	v_lshlrev_b32_e32 v124, 2, v122
	global_load_dwordx2 v[122:123], v67, s[2:3]
	s_nop 0
	global_load_dwordx2 v[124:125], v124, s[2:3]
	v_xor_b32_e32 v67, 8, v229
	v_cmp_lt_i32_e32 vcc, v67, v126
	s_nop 1
	v_cndmask_b32_e32 v67, v229, v67, vcc
	v_lshlrev_b32_e32 v67, 2, v67
	ds_bpermute_b32 v126, v67, v48
	ds_bpermute_b32 v127, v67, v49
	s_waitcnt lgkmcnt(0)
	v_pk_mul_f32 v[68:69], v[70:71], v[126:127]
	ds_bpermute_b32 v70, v67, v50
	ds_bpermute_b32 v71, v67, v51
	v_cndmask_b32_e64 v69, v69, -v69, s[6:7]
	v_cndmask_b32_e64 v68, v68, -v68, s[6:7]
	v_pk_fma_f32 v[48:49], v[48:49], v[128:129], v[68:69]
	s_waitcnt vmcnt(13)
	v_mov_b32_e32 v68, v96
	s_waitcnt vmcnt(12)
	v_mov_b32_e32 v69, v98
	v_mov_b32_e32 v98, v97
	ds_bpermute_b32 v96, v67, v32
	ds_bpermute_b32 v97, v67, v33
	s_waitcnt lgkmcnt(2)
	v_pk_mul_f32 v[70:71], v[98:99], v[70:71]
	s_nop 0
	v_cndmask_b32_e64 v71, v71, -v71, s[6:7]
	v_cndmask_b32_e64 v70, v70, -v70, s[6:7]
	v_pk_fma_f32 v[50:51], v[50:51], v[68:69], v[70:71]
	s_waitcnt vmcnt(10)
	v_mov_b32_e32 v69, v102
	v_mov_b32_e32 v102, v101
	s_waitcnt lgkmcnt(0)
	v_pk_mul_f32 v[70:71], v[102:103], v[96:97]
	ds_bpermute_b32 v96, v67, v34
	ds_bpermute_b32 v97, v67, v35
	v_mov_b32_e32 v68, v100
	v_cndmask_b32_e64 v71, v71, -v71, s[6:7]
	v_cndmask_b32_e64 v70, v70, -v70, s[6:7]
	v_pk_fma_f32 v[32:33], v[32:33], v[68:69], v[70:71]
	s_waitcnt vmcnt(8)
	v_mov_b32_e32 v69, v106
	v_mov_b32_e32 v106, v105
	s_waitcnt lgkmcnt(0)
	v_pk_mul_f32 v[70:71], v[106:107], v[96:97]
	ds_bpermute_b32 v96, v67, v16
	ds_bpermute_b32 v97, v67, v17
	v_mov_b32_e32 v68, v104
	v_cndmask_b32_e64 v71, v71, -v71, s[6:7]
	v_cndmask_b32_e64 v70, v70, -v70, s[6:7]
	v_pk_fma_f32 v[34:35], v[34:35], v[68:69], v[70:71]
	s_waitcnt vmcnt(7)
	v_mov_b32_e32 v68, v108
	s_waitcnt vmcnt(6)
	v_mov_b32_e32 v69, v110
	v_mov_b32_e32 v110, v109
	s_waitcnt lgkmcnt(0)
	v_pk_mul_f32 v[70:71], v[110:111], v[96:97]
	ds_bpermute_b32 v96, v67, v18
	ds_bpermute_b32 v97, v67, v19
	v_cndmask_b32_e64 v71, v71, -v71, s[6:7]
	v_cndmask_b32_e64 v70, v70, -v70, s[6:7]
	v_pk_fma_f32 v[16:17], v[16:17], v[68:69], v[70:71]
	s_waitcnt vmcnt(4)
	v_mov_b32_e32 v69, v116
	v_mov_b32_e32 v116, v113
	s_waitcnt lgkmcnt(0)
	v_pk_mul_f32 v[70:71], v[116:117], v[96:97]
	ds_bpermute_b32 v96, v67, v0
	ds_bpermute_b32 v97, v67, v1
	v_mov_b32_e32 v68, v112
	v_cndmask_b32_e64 v71, v71, -v71, s[6:7]
	v_cndmask_b32_e64 v70, v70, -v70, s[6:7]
	v_pk_fma_f32 v[18:19], v[18:19], v[68:69], v[70:71]
	s_waitcnt vmcnt(2)
	v_mov_b32_e32 v69, v120
	v_mov_b32_e32 v120, v119
	s_waitcnt lgkmcnt(0)
	v_pk_mul_f32 v[70:71], v[120:121], v[96:97]
	ds_bpermute_b32 v96, v67, v2
	ds_bpermute_b32 v97, v67, v3
	v_mov_b32_e32 v68, v118
	v_cndmask_b32_e64 v71, v71, -v71, s[6:7]
	v_cndmask_b32_e64 v70, v70, -v70, s[6:7]
	v_pk_fma_f32 v[0:1], v[0:1], v[68:69], v[70:71]
	s_waitcnt vmcnt(1)
	v_mov_b32_e32 v68, v122
	s_waitcnt vmcnt(0)
	v_mov_b32_e32 v69, v124
	v_mov_b32_e32 v124, v123
	s_waitcnt lgkmcnt(0)
	v_pk_mul_f32 v[70:71], v[124:125], v[96:97]
	s_nop 0
	v_cndmask_b32_e64 v71, v71, -v71, s[6:7]
	v_cndmask_b32_e64 v70, v70, -v70, s[6:7]
	v_pk_fma_f32 v[2:3], v[2:3], v[68:69], v[70:71]

.LBB0_715:
	v_readlane_b32 s0, v249, 3
	v_readlane_b32 s1, v249, 4
	s_load_dword s2, s[0:1], 0x10
	s_load_dword s4, s[0:1], 0x0
	v_readlane_b32 s3, v249, 0
	s_mov_b32 s8, s3
	v_readlane_b32 s0, v249, 30
	s_waitcnt lgkmcnt(0)
	s_lshr_b32 s2, s2, 16
	s_cmp_lg_u32 s2, 0
	s_cselect_b64 s[2:3], -1, 0
	s_cmp_lg_u64 s[2:3], 0
	v_readlane_b32 s2, v249, 19
	v_readlane_b32 s3, v249, 20
	s_addc_u32 s2, s4, 0
	v_readlane_b32 s31, v249, 37
	s_movk_i32 s30, 0x630
	s_bitcmp1_b32 s31, 0
	s_cselect_b32 s30, 0x738, s30
	s_cmp_eq_u32 s31, 0
	s_cselect_b32 s31, 64, 0
	s_add_u32 s30, s30, s31

.Lmodd_ip:
	s_lshr_b32 s31, s2, 2
	s_cmp_gt_u32 s30, s31
	s_cselect_b32 s30, 0, s30
	s_sub_u32 s2, s2, s30
	s_cmp_lt_u32 s8, s30
	s_cbranch_scc1 .LBB0_730
	s_sub_u32 s8, s8, s30
	v_readlane_b32 s1, v249, 31
	v_writelane_b32 v249, s2, 19
	s_load_dwordx2 s[0:1], s[0:1], 0x160
	s_ashr_i32 s9, s8, 31
	v_writelane_b32 v249, s3, 20
	s_lshl_b64 s[2:3], s[2:3], 8
	s_lshl_b64 s[4:5], s[8:9], 8
	v_readlane_b32 s6, v249, 41
	v_readlane_b32 s7, v249, 42
	s_add_u32 s10, s4, s6
	v_mov_b32_e32 v0, v220
	s_addc_u32 s11, s5, s7
	v_readlane_b32 s14, v249, 43
	v_ashrrev_i32_e32 v1, 31, v0
	v_lshl_add_u64 v[76:77], s[10:11], 0, v[0:1]
	v_readlane_b32 s15, v249, 44
	s_nop 1
	v_cmp_gt_u64_e32 vcc, s[14:15], v[76:77]
	s_and_saveexec_b64 s[4:5], vcc
	s_cbranch_execz .LBB0_722
	v_readlane_b32 s12, v249, 37
	v_readlane_b32 s13, v249, 38
	v_and_b32_e32 v2, 31, v0
	s_lshl_b64 s[12:13], s[12:13], 26
	s_lshl_b64 s[8:9], s[8:9], 15
	v_mul_u32_u24_e32 v2, 24, v2
	v_mov_b32_e32 v3, v80
	s_add_u32 s8, s12, s8
	s_waitcnt lgkmcnt(0)
	v_lshl_add_u64 v[68:69], s[0:1], 0, v[2:3]
	s_addc_u32 s9, s13, s9
	v_lshlrev_b64 v[2:3], 7, v[0:1]
	v_readlane_b32 s6, v249, 30
	v_lshl_add_u64 v[70:71], s[8:9], 0, v[2:3]
	v_readlane_b32 s8, v249, 19
	v_readlane_b32 s7, v249, 31
	v_readlane_b32 s9, v249, 20
	s_load_dwordx2 s[6:7], s[6:7], 0xb8
	s_lshl_b64 s[8:9], s[8:9], 16
	s_add_u32 s10, s10, s2
	s_addc_u32 s11, s11, s3
	v_lshl_add_u64 v[0:1], s[10:11], 0, v[0:1]
	s_waitcnt vmcnt(0)
	v_lshlrev_b64 v[72:73], 7, v[0:1]
	s_mov_b64 s[10:11], 0
	s_branch .LBB0_718

.LBB0_722:
	s_or_b64 exec, exec, s[4:5]
	v_readlane_b32 s4, v249, 0
	s_sub_u32 s10, s4, s30
	s_ashr_i32 s11, s10, 31
	s_lshl_b64 s[4:5], s[10:11], 8
	v_readlane_b32 s6, v249, 41
	v_readlane_b32 s7, v249, 42
	s_add_u32 s12, s4, s6
	v_mov_b32_e32 v0, v220
	s_addc_u32 s13, s5, s7
	v_readlane_b32 s18, v249, 43
	v_ashrrev_i32_e32 v1, 31, v0
	v_lshl_add_u64 v[70:71], s[12:13], 0, v[0:1]
	v_readlane_b32 s19, v249, 44
	s_nop 1
	v_cmp_gt_u64_e32 vcc, s[18:19], v[70:71]
	s_and_saveexec_b64 s[4:5], vcc
	s_cbranch_execz .LBB0_729
	v_readlane_b32 s16, v249, 19
	v_readlane_b32 s14, v249, 37
	v_readlane_b32 s17, v249, 20
	v_readlane_b32 s15, v249, 38
	s_lshl_b64 s[8:9], s[16:17], 13
	s_lshl_b64 s[14:15], s[14:15], 26
	s_lshl_b64 s[10:11], s[10:11], 15
	v_readlane_b32 s6, v249, 30
	s_add_u32 s10, s14, s10
	v_readlane_b32 s7, v249, 31
	s_addc_u32 s11, s15, s11
	v_lshlrev_b64 v[2:3], 7, v[0:1]
	s_load_dwordx2 s[6:7], s[6:7], 0xc0
	v_lshl_add_u64 v[66:67], s[10:11], 0, v[2:3]
	s_lshl_b64 s[10:11], s[16:17], 16
	s_add_u32 s12, s12, s2
	s_addc_u32 s13, s13, s3
	v_lshl_add_u64 v[0:1], s[12:13], 0, v[0:1]
	v_lshlrev_b64 v[64:65], 4, v[70:71]
	v_lshlrev_b64 v[68:69], 7, v[0:1]
	s_mov_b64 s[12:13], 0
	s_branch .LBB0_725
